# v38 + s_nop padding so every 16-MFMA block in the GEMM K-loops starts 8-byte aligned
# baseline (speedup 1.0000x reference)
; #define PG8_STAGE(bufoff, gbase, voff) do { _Pragma("unroll") for (int _i = 0; _i < 2; ++_i) \
;         __builtin_amdgcn_global_load_lds((const unsigned*)((const char*)(gbase) + (voff)[_i]), (PG8_LAS unsigned*)(lds + (bufoff) + ldsw + _i * 8192), 16, 0, 0); } while (0)
; #define PG8_LDA(dst, b, h) do { _Pragma("unroll") for (int m = 0; m < 4; ++m) _Pragma("unroll") for (int k = 0; k < 2; ++k) dst[m][k] = *(const PG8_LAS bf16x8*)(lds + PG8_SA(b, h) + aoff + m * 2048 + k * 1024); } while (0)
; #define PG8_LDB(dst, b, h) do { _Pragma("unroll") for (int n = 0; n < 2; ++n) _Pragma("unroll") for (int k = 0; k < 2; ++k) dst[n][k] = *(const PG8_LAS bf16x8*)(lds + PG8_SB(b, h) + boff + n * 2048 + k * 1024); } while (0)
; #define PG8_MMA(ai, bj, At, Bt) do { __builtin_amdgcn_s_setprio(1); _Pragma("unroll") for (int m = 0; m < 4; ++m) _Pragma("unroll") for (int n = 0; n < 2; ++n) _Pragma("unroll") for (int k = 0; k < 2; ++k) \
;         acc[ai][bj][m][n] = __builtin_amdgcn_mfma_f32_16x16x32_bf16(Bt[n][k], At[m][k], acc[ai][bj][m][n], 0, 0, 0); __builtin_amdgcn_s_setprio(0); } while (0)
; #define PG8_WAIT_V(n) asm volatile("s_waitcnt vmcnt(" #n ")" ::: "memory")
; template <class Epi, class Sched, bool ALIGN_EPI = false, bool SP2 = false>
; __device__ __forceinline__ void gemm_phase(PG8_LAS unsigned char* lds, const Gemm g, const Sched& S, const Epi& E) {
;     ...
;         const char* nA = has_next ? (const char*)g.A + (size_t)nxt.pm * tstep : cA; const char* nB = has_next ? (const char*)g.Bt + (size_t)nxt.pn * tstep : cB;
;         for (int t = 0; t < nt; t += 2) {
;             const bool last = (t == nt - 2);
;             const char* a1 = cA + (size_t)(t + 1) * kstep;
;             const char* a2 = last ? nA : cA + (size_t)(t + 2) * kstep; const char* b2 = last ? nB : cB + (size_t)(t + 2) * kstep;
;             const char* a3 = a2 + kstep; const char* b3 = b2 + kstep;
;             if (last && has_next) S.a_ready(nxt);
;             if constexpr (SP2) {
;             PG8_LDB(B0, 0, 0); PG8_LDB(B1, 0, 1); PG8_SCHED; PG8_LDA(At, 0, 0); PG8_STAGE(PG8_SA(1, 1), a1 + hstep, voffA);
;             PG8_WAIT_V(8); PG8_WAIT_L(0); PG8_BAR; PG8_MMA(0, 0, At, B0); PG8_MMA(0, 1, At, B1); PG8_BAR; PG8_SCHED;
;             PG8_LDA(At, 0, 1); PG8_STAGE(PG8_SB(0, 0), b2, voffB); PG8_STAGE(PG8_SB(0, 1), b2 + hstep, voffB); PG8_STAGE(PG8_SA(0, 0), a2, voffA);
.Lpeel_p1:
	s_add_u32 s10, s8, 0xfffc0080
	s_addc_u32 s11, s9, -1
	s_add_i32 s30, 0, 0x10000
	s_cmp_eq_u32 s43, 12
	s_cselect_b32 s15, s33, s11
	s_cselect_b32 s14, s34, s10
	v_add_u32_e32 v0, s30, v204
	s_cselect_b32 s11, s35, s42
	s_cselect_b32 s10, s40, s41
	s_add_i32 s51, 0, 0x14000
	ds_read_b128 v[18:21], v0
	ds_read_b128 v[22:25], v0 offset:1024
	ds_read_b128 v[26:29], v0 offset:2048
	ds_read_b128 v[30:33], v0 offset:3072
	v_add_u32_e32 v0, s51, v204
	ds_read_b128 v[46:49], v0
	ds_read_b128 v[54:57], v0 offset:1024
	ds_read_b128 v[170:173], v0 offset:2048
	ds_read_b128 v[174:177], v0 offset:3072
	v_lshl_add_u64 v[190:191], s[8:9], 0, v[166:167]
	s_add_i32 m0, s21, 0xc000
	ds_read_b128 v[178:181], v225
	ds_read_b128 v[182:185], v225 offset:1024
	ds_read_b128 v[186:189], v225 offset:2048
	ds_read_b128 v[226:229], v225 offset:3072
	ds_read_b128 v[230:233], v225 offset:4096
	ds_read_b128 v[234:237], v225 offset:5120
	ds_read_b128 v[238:241], v225 offset:6144
	ds_read_b128 v[242:245], v225 offset:7168
	global_load_lds_dwordx4 v[190:191], off
	v_lshl_add_u64 v[190:191], s[8:9], 0, v[168:169]
	s_add_i32 m0, s21, 0xe000
	s_nop 0
	global_load_lds_dwordx4 v[190:191], off
	s_waitcnt vmcnt(8)
	s_waitcnt lgkmcnt(0)
	s_barrier
	s_setprio 1
	s_waitcnt lgkmcnt(0)
	v_mfma_f32_16x16x32_bf16 v[150:153], v[18:21], v[178:181], 0
	v_mfma_f32_16x16x32_bf16 v[146:149], v[26:29], v[178:181], 0
	v_mfma_f32_16x16x32_bf16 v[134:137], v[18:21], v[186:189], 0
	v_mfma_f32_16x16x32_bf16 v[130:133], v[26:29], v[186:189], 0
	v_mfma_f32_16x16x32_bf16 v[118:121], v[18:21], v[230:233], 0
	v_mfma_f32_16x16x32_bf16 v[114:117], v[26:29], v[230:233], 0
	v_mfma_f32_16x16x32_bf16 v[102:105], v[18:21], v[238:241], 0
	v_mfma_f32_16x16x32_bf16 v[98:101], v[26:29], v[238:241], 0
	v_mfma_f32_16x16x32_bf16 v[150:153], v[22:25], v[182:185], v[150:153]
	v_mfma_f32_16x16x32_bf16 v[146:149], v[30:33], v[182:185], v[146:149]
	v_mfma_f32_16x16x32_bf16 v[134:137], v[22:25], v[226:229], v[134:137]
	v_mfma_f32_16x16x32_bf16 v[130:133], v[30:33], v[226:229], v[130:133]
	v_mfma_f32_16x16x32_bf16 v[118:121], v[22:25], v[234:237], v[118:121]
	v_mfma_f32_16x16x32_bf16 v[114:117], v[30:33], v[234:237], v[114:117]
	v_mfma_f32_16x16x32_bf16 v[102:105], v[22:25], v[242:245], v[102:105]
	v_mfma_f32_16x16x32_bf16 v[98:101], v[30:33], v[242:245], v[98:101]
	s_setprio 0
	s_setprio 1
	v_mfma_f32_16x16x32_bf16 v[142:145], v[46:49], v[178:181], 0
	v_mfma_f32_16x16x32_bf16 v[138:141], v[170:173], v[178:181], 0
	v_mfma_f32_16x16x32_bf16 v[126:129], v[46:49], v[186:189], 0
	v_mfma_f32_16x16x32_bf16 v[122:125], v[170:173], v[186:189], 0
	v_mfma_f32_16x16x32_bf16 v[110:113], v[46:49], v[230:233], 0
	v_mfma_f32_16x16x32_bf16 v[106:109], v[170:173], v[230:233], 0
	v_mfma_f32_16x16x32_bf16 v[94:97], v[46:49], v[238:241], 0
	v_mfma_f32_16x16x32_bf16 v[90:93], v[170:173], v[238:241], 0
	v_mfma_f32_16x16x32_bf16 v[142:145], v[54:57], v[182:185], v[142:145]
	v_mfma_f32_16x16x32_bf16 v[138:141], v[174:177], v[182:185], v[138:141]
	v_mfma_f32_16x16x32_bf16 v[126:129], v[54:57], v[226:229], v[126:129]
	v_mfma_f32_16x16x32_bf16 v[122:125], v[174:177], v[226:229], v[122:125]
	v_mfma_f32_16x16x32_bf16 v[110:113], v[54:57], v[234:237], v[110:113]
	v_mfma_f32_16x16x32_bf16 v[106:109], v[174:177], v[234:237], v[106:109]
	v_mfma_f32_16x16x32_bf16 v[94:97], v[54:57], v[242:245], v[94:97]
	v_mfma_f32_16x16x32_bf16 v[90:93], v[174:177], v[242:245], v[90:93]
	s_setprio 0
	s_barrier
	s_add_i32 s30, s30, s20
	v_lshl_add_u64 v[190:191], s[10:11], 0, v[156:157]
	s_mov_b32 m0, s30
	ds_read_b128 v[178:181], v225 offset:16384
	ds_read_b128 v[182:185], v225 offset:17408
	ds_read_b128 v[186:189], v225 offset:18432
	ds_read_b128 v[226:229], v225 offset:19456
	ds_read_b128 v[230:233], v225 offset:20480
	ds_read_b128 v[234:237], v225 offset:21504
	ds_read_b128 v[238:241], v225 offset:22528
	ds_read_b128 v[242:245], v225 offset:23552
	global_load_lds_dwordx4 v[190:191], off
	s_add_i32 m0, s30, 0x2000
	s_add_u32 s30, s10, 0x40000
	v_lshl_add_u64 v[198:199], s[10:11], 0, v[160:161]
	s_addc_u32 s31, s11, 0
	s_add_i32 s51, s51, s20
	global_load_lds_dwordx4 v[198:199], off
	v_lshl_add_u64 v[200:201], s[30:31], 0, v[156:157]
	s_mov_b32 m0, s51
	v_lshl_add_u64 v[250:251], s[14:15], 0, v[158:159]
	global_load_lds_dwordx4 v[200:201], off
	v_lshl_add_u64 v[200:201], s[30:31], 0, v[160:161]
	s_add_i32 m0, s51, 0x2000
	s_nop 0
	global_load_lds_dwordx4 v[200:201], off
	v_lshl_add_u64 v[200:201], s[14:15], 0, v[154:155]
	s_mov_b32 m0, s21
	s_nop 0
	global_load_lds_dwordx4 v[200:201], off
	s_mov_b32 m0, s45
	s_nop 0
	global_load_lds_dwordx4 v[250:251], off
	s_waitcnt vmcnt(8)
	s_waitcnt lgkmcnt(0)
	s_barrier
; #define PG8_STAGE(bufoff, gbase, voff) do { _Pragma("unroll") for (int _i = 0; _i < 2; ++_i) \
;         __builtin_amdgcn_global_load_lds((const unsigned*)((const char*)(gbase) + (voff)[_i]), (PG8_LAS unsigned*)(lds + (bufoff) + ldsw + _i * 8192), 16, 0, 0); } while (0)
; #define PG8_LDA(dst, b, h) do { _Pragma("unroll") for (int m = 0; m < 4; ++m) _Pragma("unroll") for (int k = 0; k < 2; ++k) dst[m][k] = *(const PG8_LAS bf16x8*)(lds + PG8_SA(b, h) + aoff + m * 2048 + k * 1024); } while (0)
; #define PG8_LDB(dst, b, h) do { _Pragma("unroll") for (int n = 0; n < 2; ++n) _Pragma("unroll") for (int k = 0; k < 2; ++k) dst[n][k] = *(const PG8_LAS bf16x8*)(lds + PG8_SB(b, h) + boff + n * 2048 + k * 1024); } while (0)
; #define PG8_MMA(ai, bj, At, Bt) do { __builtin_amdgcn_s_setprio(1); _Pragma("unroll") for (int m = 0; m < 4; ++m) _Pragma("unroll") for (int n = 0; n < 2; ++n) _Pragma("unroll") for (int k = 0; k < 2; ++k) \
;         acc[ai][bj][m][n] = __builtin_amdgcn_mfma_f32_16x16x32_bf16(Bt[n][k], At[m][k], acc[ai][bj][m][n], 0, 0, 0); __builtin_amdgcn_s_setprio(0); } while (0)
; #define PG8_WAIT_V(n) asm volatile("s_waitcnt vmcnt(" #n ")" ::: "memory")
; #define PG8_WAIT_L(n) asm volatile("s_waitcnt lgkmcnt(" #n ")" ::: "memory")
; #define PG8_BAR __builtin_amdgcn_s_barrier()
; #define PG8_SCHED __builtin_amdgcn_sched_barrier(0)
; template <class Epi, class Sched, bool ALIGN_EPI = false, bool SP2 = false>
; __device__ __forceinline__ void gemm_phase(PG8_LAS unsigned char* lds, const Gemm g, const Sched& S, const Epi& E) {
;     ...
;             PG8_WAIT_V(8); PG8_WAIT_L(0); PG8_BAR; PG8_MMA(0, 0, At, B0); PG8_MMA(0, 1, At, B1); PG8_BAR; PG8_SCHED;
;             PG8_LDA(At, 0, 1); PG8_STAGE(PG8_SB(0, 0), b2, voffB); PG8_STAGE(PG8_SB(0, 1), b2 + hstep, voffB); PG8_STAGE(PG8_SA(0, 0), a2, voffA);
;             PG8_WAIT_V(8); PG8_WAIT_L(0); PG8_BAR; PG8_MMA(1, 0, At, B0); PG8_MMA(1, 1, At, B1); PG8_BAR; PG8_SCHED;
;             PG8_LDB(B0, 1, 0); PG8_LDB(B1, 1, 1); PG8_SCHED; PG8_LDA(At, 1, 0); PG8_STAGE(PG8_SA(0, 1), a2 + hstep, voffA);
;             PG8_WAIT_V(8); PG8_WAIT_L(0); PG8_BAR; PG8_MMA(0, 0, At, B0); PG8_MMA(0, 1, At, B1); PG8_BAR; PG8_SCHED;
	s_nop 0
	s_setprio 1
	s_waitcnt lgkmcnt(0)
	v_mfma_f32_16x16x32_bf16 v[86:89], v[18:21], v[178:181], 0
	v_mfma_f32_16x16x32_bf16 v[82:85], v[26:29], v[178:181], 0
	v_mfma_f32_16x16x32_bf16 v[70:73], v[18:21], v[186:189], 0
	v_mfma_f32_16x16x32_bf16 v[66:69], v[26:29], v[186:189], 0
	v_mfma_f32_16x16x32_bf16 v[50:53], v[18:21], v[230:233], 0
	v_mfma_f32_16x16x32_bf16 v[42:45], v[26:29], v[230:233], 0
	v_mfma_f32_16x16x32_bf16 v[14:17], v[18:21], v[238:241], 0
	v_mfma_f32_16x16x32_bf16 v[10:13], v[26:29], v[238:241], 0
	v_mfma_f32_16x16x32_bf16 v[86:89], v[22:25], v[182:185], v[86:89]
	v_mfma_f32_16x16x32_bf16 v[82:85], v[30:33], v[182:185], v[82:85]
	v_mfma_f32_16x16x32_bf16 v[70:73], v[22:25], v[226:229], v[70:73]
	v_mfma_f32_16x16x32_bf16 v[66:69], v[30:33], v[226:229], v[66:69]
	v_mfma_f32_16x16x32_bf16 v[50:53], v[22:25], v[234:237], v[50:53]
	v_mfma_f32_16x16x32_bf16 v[42:45], v[30:33], v[234:237], v[42:45]
	v_mfma_f32_16x16x32_bf16 v[14:17], v[22:25], v[242:245], v[14:17]
	v_mfma_f32_16x16x32_bf16 v[10:13], v[30:33], v[242:245], v[10:13]
	s_setprio 0
	s_setprio 1
	v_mfma_f32_16x16x32_bf16 v[38:41], v[46:49], v[230:233], 0
	v_mfma_f32_16x16x32_bf16 v[34:37], v[170:173], v[230:233], 0
	v_mfma_f32_16x16x32_bf16 v[6:9], v[46:49], v[238:241], 0
	v_mfma_f32_16x16x32_bf16 v[2:5], v[170:173], v[238:241], 0
	v_mfma_f32_16x16x32_bf16 v[18:21], v[46:49], v[178:181], 0
	v_mfma_f32_16x16x32_bf16 v[22:25], v[170:173], v[178:181], 0
	v_mfma_f32_16x16x32_bf16 v[26:29], v[46:49], v[186:189], 0
	v_mfma_f32_16x16x32_bf16 v[30:33], v[170:173], v[186:189], 0
	v_mfma_f32_16x16x32_bf16 v[38:41], v[54:57], v[234:237], v[38:41]
	v_mfma_f32_16x16x32_bf16 v[34:37], v[174:177], v[234:237], v[34:37]
	v_mfma_f32_16x16x32_bf16 v[6:9], v[54:57], v[242:245], v[6:9]
	v_mfma_f32_16x16x32_bf16 v[2:5], v[174:177], v[242:245], v[2:5]
	v_mfma_f32_16x16x32_bf16 v[18:21], v[54:57], v[182:185], v[18:21]
	v_mfma_f32_16x16x32_bf16 v[22:25], v[174:177], v[182:185], v[22:25]
	v_mfma_f32_16x16x32_bf16 v[26:29], v[54:57], v[226:229], v[26:29]
	v_mfma_f32_16x16x32_bf16 v[30:33], v[174:177], v[226:229], v[30:33]
	s_setprio 0
	s_barrier
	s_add_i32 s30, 0, 0x18000
	v_add_u32_e32 v0, s30, v204
	s_add_i32 s31, 0, 0x1c000
	ds_read_b128 v[46:49], v0
	ds_read_b128 v[54:57], v0 offset:1024
	ds_read_b128 v[58:61], v0 offset:2048
	ds_read_b128 v[62:65], v0 offset:3072
	v_add_u32_e32 v0, s31, v204
	ds_read_b128 v[170:173], v0
	ds_read_b128 v[174:177], v0 offset:1024
	ds_read_b128 v[178:181], v0 offset:2048
	ds_read_b128 v[182:185], v0 offset:3072
	s_add_u32 s14, s14, 0x40000
	s_addc_u32 s15, s15, 0
	s_mov_b32 m0, s62
	v_lshl_add_u64 v[246:247], s[14:15], 0, v[154:155]
	ds_read_b128 v[74:77], v225 offset:32768
	ds_read_b128 v[78:81], v225 offset:33792
	ds_read_b128 v[186:189], v225 offset:34816
	ds_read_b128 v[226:229], v225 offset:35840
	ds_read_b128 v[230:233], v225 offset:36864
	ds_read_b128 v[234:237], v225 offset:37888
	ds_read_b128 v[238:241], v225 offset:38912
	ds_read_b128 v[242:245], v225 offset:39936
	global_load_lds_dwordx4 v[246:247], off
	v_lshl_add_u64 v[246:247], s[14:15], 0, v[158:159]
	s_mov_b32 m0, s63
	s_nop 0
	global_load_lds_dwordx4 v[246:247], off
	s_waitcnt vmcnt(8)
	s_waitcnt lgkmcnt(0)
	s_barrier
	s_nop 0
	s_setprio 1
	s_waitcnt lgkmcnt(0)
	v_mfma_f32_16x16x32_bf16 v[150:153], v[46:49], v[74:77], v[150:153]
	v_mfma_f32_16x16x32_bf16 v[146:149], v[58:61], v[74:77], v[146:149]
	v_mfma_f32_16x16x32_bf16 v[134:137], v[46:49], v[186:189], v[134:137]
	v_mfma_f32_16x16x32_bf16 v[130:133], v[58:61], v[186:189], v[130:133]
	v_mfma_f32_16x16x32_bf16 v[118:121], v[46:49], v[230:233], v[118:121]
	v_mfma_f32_16x16x32_bf16 v[114:117], v[58:61], v[230:233], v[114:117]
	v_mfma_f32_16x16x32_bf16 v[102:105], v[46:49], v[238:241], v[102:105]
	v_mfma_f32_16x16x32_bf16 v[98:101], v[58:61], v[238:241], v[98:101]
	v_mfma_f32_16x16x32_bf16 v[150:153], v[54:57], v[78:81], v[150:153]
	v_mfma_f32_16x16x32_bf16 v[146:149], v[62:65], v[78:81], v[146:149]
	v_mfma_f32_16x16x32_bf16 v[134:137], v[54:57], v[226:229], v[134:137]
	v_mfma_f32_16x16x32_bf16 v[130:133], v[62:65], v[226:229], v[130:133]
	v_mfma_f32_16x16x32_bf16 v[118:121], v[54:57], v[234:237], v[118:121]
	v_mfma_f32_16x16x32_bf16 v[114:117], v[62:65], v[234:237], v[114:117]
	v_mfma_f32_16x16x32_bf16 v[102:105], v[54:57], v[242:245], v[102:105]
	v_mfma_f32_16x16x32_bf16 v[98:101], v[62:65], v[242:245], v[98:101]
	s_setprio 0
	s_setprio 1
	v_mfma_f32_16x16x32_bf16 v[142:145], v[170:173], v[74:77], v[142:145]
	v_mfma_f32_16x16x32_bf16 v[74:77], v[178:181], v[74:77], v[138:141]
	v_mfma_f32_16x16x32_bf16 v[138:141], v[182:185], v[78:81], v[74:77]
	v_mfma_f32_16x16x32_bf16 v[74:77], v[170:173], v[186:189], v[126:129]
	v_mfma_f32_16x16x32_bf16 v[126:129], v[174:177], v[226:229], v[74:77]
	v_mfma_f32_16x16x32_bf16 v[74:77], v[178:181], v[186:189], v[122:125]
	v_mfma_f32_16x16x32_bf16 v[122:125], v[182:185], v[226:229], v[74:77]
	v_mfma_f32_16x16x32_bf16 v[74:77], v[170:173], v[230:233], v[110:113]
	v_mfma_f32_16x16x32_bf16 v[110:113], v[174:177], v[234:237], v[74:77]
	v_mfma_f32_16x16x32_bf16 v[74:77], v[178:181], v[230:233], v[106:109]
	v_mfma_f32_16x16x32_bf16 v[106:109], v[182:185], v[234:237], v[74:77]
	v_mfma_f32_16x16x32_bf16 v[74:77], v[170:173], v[238:241], v[94:97]
	v_mfma_f32_16x16x32_bf16 v[94:97], v[174:177], v[242:245], v[74:77]
	v_mfma_f32_16x16x32_bf16 v[74:77], v[178:181], v[238:241], v[90:93]
	v_mfma_f32_16x16x32_bf16 v[142:145], v[174:177], v[78:81], v[142:145]
	v_mfma_f32_16x16x32_bf16 v[90:93], v[182:185], v[242:245], v[74:77]
	s_setprio 0
	s_barrier
; #define PG8_STAGE(bufoff, gbase, voff) do { _Pragma("unroll") for (int _i = 0; _i < 2; ++_i) \
;         __builtin_amdgcn_global_load_lds((const unsigned*)((const char*)(gbase) + (voff)[_i]), (PG8_LAS unsigned*)(lds + (bufoff) + ldsw + _i * 8192), 16, 0, 0); } while (0)
; #define PG8_LDA(dst, b, h) do { _Pragma("unroll") for (int m = 0; m < 4; ++m) _Pragma("unroll") for (int k = 0; k < 2; ++k) dst[m][k] = *(const PG8_LAS bf16x8*)(lds + PG8_SA(b, h) + aoff + m * 2048 + k * 1024); } while (0)
; #define PG8_LDB(dst, b, h) do { _Pragma("unroll") for (int n = 0; n < 2; ++n) _Pragma("unroll") for (int k = 0; k < 2; ++k) dst[n][k] = *(const PG8_LAS bf16x8*)(lds + PG8_SB(b, h) + boff + n * 2048 + k * 1024); } while (0)
; template <class Epi, class Sched, bool ALIGN_EPI = false, bool SP2 = false>
; __device__ __forceinline__ void gemm_phase(PG8_LAS unsigned char* lds, const Gemm g, const Sched& S, const Epi& E) {
;     ...
;         for (int t = 0; t < nt; t += 2) {
;             const bool last = (t == nt - 2);
;             const char* a1 = cA + (size_t)(t + 1) * kstep;
;             const char* a2 = last ? nA : cA + (size_t)(t + 2) * kstep; const char* b2 = last ? nB : cB + (size_t)(t + 2) * kstep;
;             const char* a3 = a2 + kstep; const char* b3 = b2 + kstep;
;             if (last && has_next) S.a_ready(nxt);
;             if constexpr (SP2) {
;             PG8_LDB(B0, 0, 0); PG8_LDB(B1, 0, 1); PG8_SCHED; PG8_LDA(At, 0, 0); PG8_STAGE(PG8_SA(1, 1), a1 + hstep, voffA);
;             PG8_WAIT_V(8); PG8_WAIT_L(0); PG8_BAR; PG8_MMA(0, 0, At, B0); PG8_MMA(0, 1, At, B1); PG8_BAR; PG8_SCHED;
;             PG8_LDA(At, 0, 1); PG8_STAGE(PG8_SB(0, 0), b2, voffB); PG8_STAGE(PG8_SB(0, 1), b2 + hstep, voffB); PG8_STAGE(PG8_SA(0, 0), a2, voffA);
;             PG8_WAIT_V(8); PG8_WAIT_L(0); PG8_BAR; PG8_MMA(1, 0, At, B0); PG8_MMA(1, 1, At, B1); PG8_BAR; PG8_SCHED;
;             PG8_LDB(B0, 1, 0); PG8_LDB(B1, 1, 1); PG8_SCHED; PG8_LDA(At, 1, 0); PG8_STAGE(PG8_SA(0, 1), a2 + hstep, voffA);
;             PG8_WAIT_V(8); PG8_WAIT_L(0); PG8_BAR; PG8_MMA(0, 0, At, B0); PG8_MMA(0, 1, At, B1); PG8_BAR; PG8_SCHED;
;             PG8_LDA(At, 1, 1); PG8_STAGE(PG8_SB(1, 0), b3, voffB); PG8_STAGE(PG8_SB(1, 1), b3 + hstep, voffB); PG8_STAGE(PG8_SA(1, 0), a3, voffA);
;             PG8_WAIT_V(8); PG8_WAIT_L(0); PG8_BAR; PG8_MMA(1, 0, At, B0); PG8_MMA(1, 1, At, B1); PG8_BAR; PG8_SCHED;
	s_add_i32 s14, s30, s20
	v_lshl_add_u64 v[78:79], v[190:191], 0, s[0:1]
	s_mov_b32 m0, s14
	s_nop 0
	ds_read_b128 v[74:77], v225 offset:49152
	ds_read_b128 v[186:189], v225 offset:50176
	ds_read_b128 v[226:229], v225 offset:51200
	ds_read_b128 v[230:233], v225 offset:52224
	ds_read_b128 v[234:237], v225 offset:53248
	ds_read_b128 v[238:241], v225 offset:54272
	ds_read_b128 v[242:245], v225 offset:55296
	ds_read_b128 v[246:249], v225 offset:56320
	global_load_lds_dwordx4 v[78:79], off
	s_add_i32 m0, s14, 0x2000
	s_add_u32 s10, s10, 0x40080
	v_lshl_add_u64 v[78:79], v[198:199], 0, s[0:1]
	s_addc_u32 s11, s11, 0
	s_add_i32 s14, s31, s20
	global_load_lds_dwordx4 v[78:79], off
	v_lshl_add_u64 v[78:79], s[10:11], 0, v[156:157]
	s_mov_b32 m0, s14
	s_nop 0
	global_load_lds_dwordx4 v[78:79], off
	v_lshl_add_u64 v[78:79], s[10:11], 0, v[160:161]
	s_add_i32 m0, s14, 0x2000
	s_nop 0
	global_load_lds_dwordx4 v[78:79], off
	v_lshl_add_u64 v[78:79], v[200:201], 0, s[0:1]
	s_mov_b32 m0, s64
	s_nop 0
	global_load_lds_dwordx4 v[78:79], off
	v_lshl_add_u64 v[78:79], v[250:251], 0, s[0:1]
	s_mov_b32 m0, s65
	s_nop 0
	global_load_lds_dwordx4 v[78:79], off
	s_waitcnt vmcnt(8)
	s_waitcnt lgkmcnt(0)
	s_barrier
	s_nop 0
	s_setprio 1
	s_waitcnt lgkmcnt(0)
	v_mfma_f32_16x16x32_bf16 v[78:81], v[46:49], v[74:77], v[86:89]
	v_mfma_f32_16x16x32_bf16 v[86:89], v[54:57], v[186:189], v[78:81]
	v_mfma_f32_16x16x32_bf16 v[78:81], v[58:61], v[74:77], v[82:85]
	v_mfma_f32_16x16x32_bf16 v[70:73], v[46:49], v[226:229], v[70:73]
	v_mfma_f32_16x16x32_bf16 v[66:69], v[58:61], v[226:229], v[66:69]
	v_mfma_f32_16x16x32_bf16 v[50:53], v[46:49], v[234:237], v[50:53]
	v_mfma_f32_16x16x32_bf16 v[42:45], v[58:61], v[234:237], v[42:45]
	v_mfma_f32_16x16x32_bf16 v[14:17], v[46:49], v[242:245], v[14:17]
	v_mfma_f32_16x16x32_bf16 v[10:13], v[58:61], v[242:245], v[10:13]
	v_mfma_f32_16x16x32_bf16 v[82:85], v[62:65], v[186:189], v[78:81]
	v_mfma_f32_16x16x32_bf16 v[70:73], v[54:57], v[230:233], v[70:73]
	v_mfma_f32_16x16x32_bf16 v[66:69], v[62:65], v[230:233], v[66:69]
	v_mfma_f32_16x16x32_bf16 v[50:53], v[54:57], v[238:241], v[50:53]
	v_mfma_f32_16x16x32_bf16 v[42:45], v[62:65], v[238:241], v[42:45]
	v_mfma_f32_16x16x32_bf16 v[14:17], v[54:57], v[246:249], v[14:17]
	v_mfma_f32_16x16x32_bf16 v[10:13], v[62:65], v[246:249], v[10:13]
	s_setprio 0
	s_setprio 1
	v_mfma_f32_16x16x32_bf16 v[18:21], v[170:173], v[74:77], v[18:21]
	v_mfma_f32_16x16x32_bf16 v[78:81], v[174:177], v[186:189], v[18:21]
	v_mfma_f32_16x16x32_bf16 v[18:21], v[178:181], v[74:77], v[22:25]
	v_mfma_f32_16x16x32_bf16 v[74:77], v[182:185], v[186:189], v[18:21]
	v_mfma_f32_16x16x32_bf16 v[18:21], v[170:173], v[226:229], v[26:29]
	v_mfma_f32_16x16x32_bf16 v[62:65], v[174:177], v[230:233], v[18:21]
	v_mfma_f32_16x16x32_bf16 v[18:21], v[178:181], v[226:229], v[30:33]
	v_mfma_f32_16x16x32_bf16 v[58:61], v[182:185], v[230:233], v[18:21]
	v_mfma_f32_16x16x32_bf16 v[18:21], v[170:173], v[234:237], v[38:41]
	v_mfma_f32_16x16x32_bf16 v[38:41], v[174:177], v[238:241], v[18:21]
	v_mfma_f32_16x16x32_bf16 v[18:21], v[178:181], v[234:237], v[34:37]
	v_mfma_f32_16x16x32_bf16 v[6:9], v[170:173], v[242:245], v[6:9]
	v_mfma_f32_16x16x32_bf16 v[2:5], v[178:181], v[242:245], v[2:5]
	v_mfma_f32_16x16x32_bf16 v[34:37], v[182:185], v[238:241], v[18:21]
	v_mfma_f32_16x16x32_bf16 v[6:9], v[174:177], v[246:249], v[6:9]
	v_mfma_f32_16x16x32_bf16 v[2:5], v[182:185], v[246:249], v[2:5]
	s_setprio 0
	s_barrier
	s_add_i32 s43, s43, 2
	s_add_u32 s8, s8, 0x100
	s_addc_u32 s9, s9, 0
	s_add_u32 s41, s41, 0x100
	s_addc_u32 s42, s42, 0
	s_cmp_gt_u32 s43, 13
	s_cbranch_scc0 .LBB0_188
	s_branch .Lpeel_exit_p1
.LBB0_188:
	s_add_u32 s10, s8, 0xfffc0080
	s_addc_u32 s11, s9, -1
	s_add_i32 s30, 0, 0x10000
	s_cmp_eq_u32 s43, 12
	s_cselect_b32 s15, s33, s11
	s_cselect_b32 s14, s34, s10
	v_add_u32_e32 v0, s30, v204
	s_cselect_b32 s11, s35, s42
	s_cselect_b32 s10, s40, s41
	s_add_i32 s51, 0, 0x14000
	ds_read_b128 v[18:21], v0
	ds_read_b128 v[22:25], v0 offset:1024
	ds_read_b128 v[26:29], v0 offset:2048
	ds_read_b128 v[30:33], v0 offset:3072
	v_add_u32_e32 v0, s51, v204
	ds_read_b128 v[46:49], v0
	ds_read_b128 v[54:57], v0 offset:1024
	ds_read_b128 v[170:173], v0 offset:2048
	ds_read_b128 v[174:177], v0 offset:3072
	v_lshl_add_u64 v[190:191], s[8:9], 0, v[166:167]
	s_add_i32 m0, s21, 0xc000
	ds_read_b128 v[178:181], v225
	ds_read_b128 v[182:185], v225 offset:1024
	ds_read_b128 v[186:189], v225 offset:2048
	ds_read_b128 v[226:229], v225 offset:3072
	ds_read_b128 v[230:233], v225 offset:4096
	ds_read_b128 v[234:237], v225 offset:5120
	ds_read_b128 v[238:241], v225 offset:6144
	ds_read_b128 v[242:245], v225 offset:7168
	global_load_lds_dwordx4 v[190:191], off
	v_lshl_add_u64 v[190:191], s[8:9], 0, v[168:169]
	s_add_i32 m0, s21, 0xe000
	s_nop 0
	global_load_lds_dwordx4 v[190:191], off
	s_waitcnt vmcnt(8)
	s_waitcnt lgkmcnt(0)
	s_barrier
; #define PG8_STAGE(bufoff, gbase, voff) do { _Pragma("unroll") for (int _i = 0; _i < 2; ++_i) \
;         __builtin_amdgcn_global_load_lds((const unsigned*)((const char*)(gbase) + (voff)[_i]), (PG8_LAS unsigned*)(lds + (bufoff) + ldsw + _i * 8192), 16, 0, 0); } while (0)
; #define PG8_LDA(dst, b, h) do { _Pragma("unroll") for (int m = 0; m < 4; ++m) _Pragma("unroll") for (int k = 0; k < 2; ++k) dst[m][k] = *(const PG8_LAS bf16x8*)(lds + PG8_SA(b, h) + aoff + m * 2048 + k * 1024); } while (0)
; #define PG8_LDB(dst, b, h) do { _Pragma("unroll") for (int n = 0; n < 2; ++n) _Pragma("unroll") for (int k = 0; k < 2; ++k) dst[n][k] = *(const PG8_LAS bf16x8*)(lds + PG8_SB(b, h) + boff + n * 2048 + k * 1024); } while (0)
; #define PG8_MMA(ai, bj, At, Bt) do { __builtin_amdgcn_s_setprio(1); _Pragma("unroll") for (int m = 0; m < 4; ++m) _Pragma("unroll") for (int n = 0; n < 2; ++n) _Pragma("unroll") for (int k = 0; k < 2; ++k) \
;         acc[ai][bj][m][n] = __builtin_amdgcn_mfma_f32_16x16x32_bf16(Bt[n][k], At[m][k], acc[ai][bj][m][n], 0, 0, 0); __builtin_amdgcn_s_setprio(0); } while (0)
; #define PG8_WAIT_V(n) asm volatile("s_waitcnt vmcnt(" #n ")" ::: "memory")
; #define PG8_WAIT_L(n) asm volatile("s_waitcnt lgkmcnt(" #n ")" ::: "memory")
; #define PG8_BAR __builtin_amdgcn_s_barrier()
; #define PG8_SCHED __builtin_amdgcn_sched_barrier(0)
; template <class Epi, class Sched, bool ALIGN_EPI = false, bool SP2 = false>
; __device__ __forceinline__ void gemm_phase(PG8_LAS unsigned char* lds, const Gemm g, const Sched& S, const Epi& E) {
;     ...
;             PG8_LDB(B0, 0, 0); PG8_LDB(B1, 0, 1); PG8_SCHED; PG8_LDA(At, 0, 0); PG8_STAGE(PG8_SA(1, 1), a1 + hstep, voffA);
;             PG8_WAIT_V(8); PG8_WAIT_L(0); PG8_BAR; PG8_MMA(0, 0, At, B0); PG8_MMA(0, 1, At, B1); PG8_BAR; PG8_SCHED;
;             PG8_LDA(At, 0, 1); PG8_STAGE(PG8_SB(0, 0), b2, voffB); PG8_STAGE(PG8_SB(0, 1), b2 + hstep, voffB); PG8_STAGE(PG8_SA(0, 0), a2, voffA);
;             PG8_WAIT_V(8); PG8_WAIT_L(0); PG8_BAR; PG8_MMA(1, 0, At, B0); PG8_MMA(1, 1, At, B1); PG8_BAR; PG8_SCHED;
	s_setprio 1
	s_waitcnt lgkmcnt(0)
	v_mfma_f32_16x16x32_bf16 v[150:153], v[18:21], v[178:181], v[150:153]
	v_mfma_f32_16x16x32_bf16 v[146:149], v[26:29], v[178:181], v[146:149]
	v_mfma_f32_16x16x32_bf16 v[134:137], v[18:21], v[186:189], v[134:137]
	v_mfma_f32_16x16x32_bf16 v[130:133], v[26:29], v[186:189], v[130:133]
	v_mfma_f32_16x16x32_bf16 v[118:121], v[18:21], v[230:233], v[118:121]
	v_mfma_f32_16x16x32_bf16 v[114:117], v[26:29], v[230:233], v[114:117]
	v_mfma_f32_16x16x32_bf16 v[102:105], v[18:21], v[238:241], v[102:105]
	v_mfma_f32_16x16x32_bf16 v[98:101], v[26:29], v[238:241], v[98:101]
	v_mfma_f32_16x16x32_bf16 v[150:153], v[22:25], v[182:185], v[150:153]
	v_mfma_f32_16x16x32_bf16 v[146:149], v[30:33], v[182:185], v[146:149]
	v_mfma_f32_16x16x32_bf16 v[134:137], v[22:25], v[226:229], v[134:137]
	v_mfma_f32_16x16x32_bf16 v[130:133], v[30:33], v[226:229], v[130:133]
	v_mfma_f32_16x16x32_bf16 v[118:121], v[22:25], v[234:237], v[118:121]
	v_mfma_f32_16x16x32_bf16 v[114:117], v[30:33], v[234:237], v[114:117]
	v_mfma_f32_16x16x32_bf16 v[102:105], v[22:25], v[242:245], v[102:105]
	v_mfma_f32_16x16x32_bf16 v[98:101], v[30:33], v[242:245], v[98:101]
	s_setprio 0
	s_setprio 1
	v_mfma_f32_16x16x32_bf16 v[142:145], v[46:49], v[178:181], v[142:145]
	v_mfma_f32_16x16x32_bf16 v[138:141], v[170:173], v[178:181], v[138:141]
	v_mfma_f32_16x16x32_bf16 v[126:129], v[46:49], v[186:189], v[126:129]
	v_mfma_f32_16x16x32_bf16 v[122:125], v[170:173], v[186:189], v[122:125]
	v_mfma_f32_16x16x32_bf16 v[110:113], v[46:49], v[230:233], v[110:113]
	v_mfma_f32_16x16x32_bf16 v[106:109], v[170:173], v[230:233], v[106:109]
	v_mfma_f32_16x16x32_bf16 v[94:97], v[46:49], v[238:241], v[94:97]
	v_mfma_f32_16x16x32_bf16 v[90:93], v[170:173], v[238:241], v[90:93]
	v_mfma_f32_16x16x32_bf16 v[142:145], v[54:57], v[182:185], v[142:145]
	v_mfma_f32_16x16x32_bf16 v[138:141], v[174:177], v[182:185], v[138:141]
	v_mfma_f32_16x16x32_bf16 v[126:129], v[54:57], v[226:229], v[126:129]
	v_mfma_f32_16x16x32_bf16 v[122:125], v[174:177], v[226:229], v[122:125]
	v_mfma_f32_16x16x32_bf16 v[110:113], v[54:57], v[234:237], v[110:113]
	v_mfma_f32_16x16x32_bf16 v[106:109], v[174:177], v[234:237], v[106:109]
	v_mfma_f32_16x16x32_bf16 v[94:97], v[54:57], v[242:245], v[94:97]
	v_mfma_f32_16x16x32_bf16 v[90:93], v[174:177], v[242:245], v[90:93]
	s_setprio 0
	s_barrier
	s_add_i32 s30, s30, s20
	v_lshl_add_u64 v[190:191], s[10:11], 0, v[156:157]
	s_mov_b32 m0, s30
	ds_read_b128 v[178:181], v225 offset:16384
	ds_read_b128 v[182:185], v225 offset:17408
	ds_read_b128 v[186:189], v225 offset:18432
	ds_read_b128 v[226:229], v225 offset:19456
	ds_read_b128 v[230:233], v225 offset:20480
	ds_read_b128 v[234:237], v225 offset:21504
	ds_read_b128 v[238:241], v225 offset:22528
	ds_read_b128 v[242:245], v225 offset:23552
	global_load_lds_dwordx4 v[190:191], off
	s_add_i32 m0, s30, 0x2000
	s_add_u32 s30, s10, 0x40000
	v_lshl_add_u64 v[198:199], s[10:11], 0, v[160:161]
	s_addc_u32 s31, s11, 0
	s_add_i32 s51, s51, s20
	global_load_lds_dwordx4 v[198:199], off
	v_lshl_add_u64 v[200:201], s[30:31], 0, v[156:157]
	s_mov_b32 m0, s51
	v_lshl_add_u64 v[250:251], s[14:15], 0, v[158:159]
	global_load_lds_dwordx4 v[200:201], off
	v_lshl_add_u64 v[200:201], s[30:31], 0, v[160:161]
	s_add_i32 m0, s51, 0x2000
	s_nop 0
	global_load_lds_dwordx4 v[200:201], off
	v_lshl_add_u64 v[200:201], s[14:15], 0, v[154:155]
	s_mov_b32 m0, s21
	s_nop 0
	global_load_lds_dwordx4 v[200:201], off
	s_mov_b32 m0, s45
	s_nop 0
	global_load_lds_dwordx4 v[250:251], off
	s_waitcnt vmcnt(8)
	s_waitcnt lgkmcnt(0)
	s_barrier
	s_nop 0
	s_setprio 1
	s_waitcnt lgkmcnt(0)
	v_mfma_f32_16x16x32_bf16 v[86:89], v[18:21], v[178:181], v[86:89]
	v_mfma_f32_16x16x32_bf16 v[82:85], v[26:29], v[178:181], v[82:85]
	v_mfma_f32_16x16x32_bf16 v[70:73], v[18:21], v[186:189], v[70:73]
	v_mfma_f32_16x16x32_bf16 v[66:69], v[26:29], v[186:189], v[66:69]
	v_mfma_f32_16x16x32_bf16 v[50:53], v[18:21], v[230:233], v[50:53]
	v_mfma_f32_16x16x32_bf16 v[42:45], v[26:29], v[230:233], v[42:45]
	v_mfma_f32_16x16x32_bf16 v[14:17], v[18:21], v[238:241], v[14:17]
	v_mfma_f32_16x16x32_bf16 v[10:13], v[26:29], v[238:241], v[10:13]
	v_mfma_f32_16x16x32_bf16 v[86:89], v[22:25], v[182:185], v[86:89]
	v_mfma_f32_16x16x32_bf16 v[82:85], v[30:33], v[182:185], v[82:85]
	v_mfma_f32_16x16x32_bf16 v[70:73], v[22:25], v[226:229], v[70:73]
	v_mfma_f32_16x16x32_bf16 v[66:69], v[30:33], v[226:229], v[66:69]
	v_mfma_f32_16x16x32_bf16 v[50:53], v[22:25], v[234:237], v[50:53]
	v_mfma_f32_16x16x32_bf16 v[42:45], v[30:33], v[234:237], v[42:45]
	v_mfma_f32_16x16x32_bf16 v[14:17], v[22:25], v[242:245], v[14:17]
	v_mfma_f32_16x16x32_bf16 v[10:13], v[30:33], v[242:245], v[10:13]
	s_setprio 0
	s_setprio 1
	v_mfma_f32_16x16x32_bf16 v[38:41], v[46:49], v[230:233], v[38:41]
	v_mfma_f32_16x16x32_bf16 v[34:37], v[170:173], v[230:233], v[34:37]
	v_mfma_f32_16x16x32_bf16 v[6:9], v[46:49], v[238:241], v[6:9]
	v_mfma_f32_16x16x32_bf16 v[2:5], v[170:173], v[238:241], v[2:5]
	v_mfma_f32_16x16x32_bf16 v[18:21], v[46:49], v[178:181], v[78:81]
	v_mfma_f32_16x16x32_bf16 v[22:25], v[170:173], v[178:181], v[74:77]
	v_mfma_f32_16x16x32_bf16 v[26:29], v[46:49], v[186:189], v[62:65]
	v_mfma_f32_16x16x32_bf16 v[30:33], v[170:173], v[186:189], v[58:61]
	v_mfma_f32_16x16x32_bf16 v[38:41], v[54:57], v[234:237], v[38:41]
	v_mfma_f32_16x16x32_bf16 v[34:37], v[174:177], v[234:237], v[34:37]
	v_mfma_f32_16x16x32_bf16 v[6:9], v[54:57], v[242:245], v[6:9]
	v_mfma_f32_16x16x32_bf16 v[2:5], v[174:177], v[242:245], v[2:5]
	v_mfma_f32_16x16x32_bf16 v[18:21], v[54:57], v[182:185], v[18:21]
	v_mfma_f32_16x16x32_bf16 v[22:25], v[174:177], v[182:185], v[22:25]
	v_mfma_f32_16x16x32_bf16 v[26:29], v[54:57], v[226:229], v[26:29]
	v_mfma_f32_16x16x32_bf16 v[30:33], v[174:177], v[226:229], v[30:33]
	s_setprio 0
	s_barrier
; #define PG8_STAGE(bufoff, gbase, voff) do { _Pragma("unroll") for (int _i = 0; _i < 2; ++_i) \
;         __builtin_amdgcn_global_load_lds((const unsigned*)((const char*)(gbase) + (voff)[_i]), (PG8_LAS unsigned*)(lds + (bufoff) + ldsw + _i * 8192), 16, 0, 0); } while (0)
; #define PG8_LDA(dst, b, h) do { _Pragma("unroll") for (int m = 0; m < 4; ++m) _Pragma("unroll") for (int k = 0; k < 2; ++k) dst[m][k] = *(const PG8_LAS bf16x8*)(lds + PG8_SA(b, h) + aoff + m * 2048 + k * 1024); } while (0)
; #define PG8_LDB(dst, b, h) do { _Pragma("unroll") for (int n = 0; n < 2; ++n) _Pragma("unroll") for (int k = 0; k < 2; ++k) dst[n][k] = *(const PG8_LAS bf16x8*)(lds + PG8_SB(b, h) + boff + n * 2048 + k * 1024); } while (0)
; #define PG8_MMA(ai, bj, At, Bt) do { __builtin_amdgcn_s_setprio(1); _Pragma("unroll") for (int m = 0; m < 4; ++m) _Pragma("unroll") for (int n = 0; n < 2; ++n) _Pragma("unroll") for (int k = 0; k < 2; ++k) \
;         acc[ai][bj][m][n] = __builtin_amdgcn_mfma_f32_16x16x32_bf16(Bt[n][k], At[m][k], acc[ai][bj][m][n], 0, 0, 0); __builtin_amdgcn_s_setprio(0); } while (0)
; #define PG8_WAIT_V(n) asm volatile("s_waitcnt vmcnt(" #n ")" ::: "memory")
; #define PG8_WAIT_L(n) asm volatile("s_waitcnt lgkmcnt(" #n ")" ::: "memory")
; #define PG8_BAR __builtin_amdgcn_s_barrier()
; #define PG8_SCHED __builtin_amdgcn_sched_barrier(0)
; template <class Epi, class Sched, bool ALIGN_EPI = false, bool SP2 = false>
; __device__ __forceinline__ void gemm_phase(PG8_LAS unsigned char* lds, const Gemm g, const Sched& S, const Epi& E) {
;     ...
;             PG8_LDB(B0, 1, 0); PG8_LDB(B1, 1, 1); PG8_SCHED; PG8_LDA(At, 1, 0); PG8_STAGE(PG8_SA(0, 1), a2 + hstep, voffA);
;             PG8_WAIT_V(8); PG8_WAIT_L(0); PG8_BAR; PG8_MMA(0, 0, At, B0); PG8_MMA(0, 1, At, B1); PG8_BAR; PG8_SCHED;
	s_add_i32 s30, 0, 0x18000
	v_add_u32_e32 v0, s30, v204
	s_add_i32 s31, 0, 0x1c000
	ds_read_b128 v[46:49], v0
	ds_read_b128 v[54:57], v0 offset:1024
	ds_read_b128 v[58:61], v0 offset:2048
	ds_read_b128 v[62:65], v0 offset:3072
	v_add_u32_e32 v0, s31, v204
	ds_read_b128 v[170:173], v0
	ds_read_b128 v[174:177], v0 offset:1024
	ds_read_b128 v[178:181], v0 offset:2048
	ds_read_b128 v[182:185], v0 offset:3072
	s_add_u32 s14, s14, 0x40000
	s_addc_u32 s15, s15, 0
	s_mov_b32 m0, s62
	v_lshl_add_u64 v[246:247], s[14:15], 0, v[154:155]
	ds_read_b128 v[74:77], v225 offset:32768
	ds_read_b128 v[78:81], v225 offset:33792
	ds_read_b128 v[186:189], v225 offset:34816
	ds_read_b128 v[226:229], v225 offset:35840
	ds_read_b128 v[230:233], v225 offset:36864
	ds_read_b128 v[234:237], v225 offset:37888
	ds_read_b128 v[238:241], v225 offset:38912
	ds_read_b128 v[242:245], v225 offset:39936
	global_load_lds_dwordx4 v[246:247], off
	v_lshl_add_u64 v[246:247], s[14:15], 0, v[158:159]
	s_mov_b32 m0, s63
	s_nop 0
	global_load_lds_dwordx4 v[246:247], off
	s_waitcnt vmcnt(8)
	s_waitcnt lgkmcnt(0)
	s_barrier
	s_nop 0
	s_setprio 1
	s_waitcnt lgkmcnt(0)
	v_mfma_f32_16x16x32_bf16 v[150:153], v[46:49], v[74:77], v[150:153]
	v_mfma_f32_16x16x32_bf16 v[146:149], v[58:61], v[74:77], v[146:149]
	v_mfma_f32_16x16x32_bf16 v[134:137], v[46:49], v[186:189], v[134:137]
	v_mfma_f32_16x16x32_bf16 v[130:133], v[58:61], v[186:189], v[130:133]
	v_mfma_f32_16x16x32_bf16 v[118:121], v[46:49], v[230:233], v[118:121]
	v_mfma_f32_16x16x32_bf16 v[114:117], v[58:61], v[230:233], v[114:117]
	v_mfma_f32_16x16x32_bf16 v[102:105], v[46:49], v[238:241], v[102:105]
	v_mfma_f32_16x16x32_bf16 v[98:101], v[58:61], v[238:241], v[98:101]
	v_mfma_f32_16x16x32_bf16 v[150:153], v[54:57], v[78:81], v[150:153]
	v_mfma_f32_16x16x32_bf16 v[146:149], v[62:65], v[78:81], v[146:149]
	v_mfma_f32_16x16x32_bf16 v[134:137], v[54:57], v[226:229], v[134:137]
	v_mfma_f32_16x16x32_bf16 v[130:133], v[62:65], v[226:229], v[130:133]
	v_mfma_f32_16x16x32_bf16 v[118:121], v[54:57], v[234:237], v[118:121]
	v_mfma_f32_16x16x32_bf16 v[114:117], v[62:65], v[234:237], v[114:117]
	v_mfma_f32_16x16x32_bf16 v[102:105], v[54:57], v[242:245], v[102:105]
	v_mfma_f32_16x16x32_bf16 v[98:101], v[62:65], v[242:245], v[98:101]
	s_setprio 0
	s_setprio 1
	v_mfma_f32_16x16x32_bf16 v[142:145], v[170:173], v[74:77], v[142:145]
	v_mfma_f32_16x16x32_bf16 v[74:77], v[178:181], v[74:77], v[138:141]
	v_mfma_f32_16x16x32_bf16 v[138:141], v[182:185], v[78:81], v[74:77]
	v_mfma_f32_16x16x32_bf16 v[74:77], v[170:173], v[186:189], v[126:129]
	v_mfma_f32_16x16x32_bf16 v[126:129], v[174:177], v[226:229], v[74:77]
	v_mfma_f32_16x16x32_bf16 v[74:77], v[178:181], v[186:189], v[122:125]
	v_mfma_f32_16x16x32_bf16 v[122:125], v[182:185], v[226:229], v[74:77]
	v_mfma_f32_16x16x32_bf16 v[74:77], v[170:173], v[230:233], v[110:113]
	v_mfma_f32_16x16x32_bf16 v[110:113], v[174:177], v[234:237], v[74:77]
	v_mfma_f32_16x16x32_bf16 v[74:77], v[178:181], v[230:233], v[106:109]
	v_mfma_f32_16x16x32_bf16 v[106:109], v[182:185], v[234:237], v[74:77]
	v_mfma_f32_16x16x32_bf16 v[74:77], v[170:173], v[238:241], v[94:97]
	v_mfma_f32_16x16x32_bf16 v[94:97], v[174:177], v[242:245], v[74:77]
	v_mfma_f32_16x16x32_bf16 v[74:77], v[178:181], v[238:241], v[90:93]
	v_mfma_f32_16x16x32_bf16 v[142:145], v[174:177], v[78:81], v[142:145]
	v_mfma_f32_16x16x32_bf16 v[90:93], v[182:185], v[242:245], v[74:77]
	s_setprio 0
	s_barrier
; #define PG8_STAGE(bufoff, gbase, voff) do { _Pragma("unroll") for (int _i = 0; _i < 2; ++_i) \
;         __builtin_amdgcn_global_load_lds((const unsigned*)((const char*)(gbase) + (voff)[_i]), (PG8_LAS unsigned*)(lds + (bufoff) + ldsw + _i * 8192), 16, 0, 0); } while (0)
; #define PG8_LDA(dst, b, h) do { _Pragma("unroll") for (int m = 0; m < 4; ++m) _Pragma("unroll") for (int k = 0; k < 2; ++k) dst[m][k] = *(const PG8_LAS bf16x8*)(lds + PG8_SA(b, h) + aoff + m * 2048 + k * 1024); } while (0)
; #define PG8_MMA(ai, bj, At, Bt) do { __builtin_amdgcn_s_setprio(1); _Pragma("unroll") for (int m = 0; m < 4; ++m) _Pragma("unroll") for (int n = 0; n < 2; ++n) _Pragma("unroll") for (int k = 0; k < 2; ++k) \
;         acc[ai][bj][m][n] = __builtin_amdgcn_mfma_f32_16x16x32_bf16(Bt[n][k], At[m][k], acc[ai][bj][m][n], 0, 0, 0); __builtin_amdgcn_s_setprio(0); } while (0)
; #define PG8_WAIT_V(n) asm volatile("s_waitcnt vmcnt(" #n ")" ::: "memory")
; #define PG8_WAIT_L(n) asm volatile("s_waitcnt lgkmcnt(" #n ")" ::: "memory")
; #define PG8_BAR __builtin_amdgcn_s_barrier()
; #define PG8_SCHED __builtin_amdgcn_sched_barrier(0)
; template <class Epi, class Sched, bool ALIGN_EPI = false, bool SP2 = false>
; __device__ __forceinline__ void gemm_phase(PG8_LAS unsigned char* lds, const Gemm g, const Sched& S, const Epi& E) {
;     ...
;         for (int t = 0; t < nt; t += 2) {
;             const bool last = (t == nt - 2);
;             const char* a1 = cA + (size_t)(t + 1) * kstep;
;             const char* a2 = last ? nA : cA + (size_t)(t + 2) * kstep; const char* b2 = last ? nB : cB + (size_t)(t + 2) * kstep;
;     ...
;             PG8_LDA(At, 1, 1); PG8_STAGE(PG8_SB(1, 0), b3, voffB); PG8_STAGE(PG8_SB(1, 1), b3 + hstep, voffB); PG8_STAGE(PG8_SA(1, 0), a3, voffA);
;             PG8_WAIT_V(8); PG8_WAIT_L(0); PG8_BAR; PG8_MMA(1, 0, At, B0); PG8_MMA(1, 1, At, B1); PG8_BAR; PG8_SCHED;
	s_add_i32 s14, s30, s20
	v_lshl_add_u64 v[78:79], v[190:191], 0, s[0:1]
	s_mov_b32 m0, s14
	s_nop 0
	ds_read_b128 v[74:77], v225 offset:49152
	ds_read_b128 v[186:189], v225 offset:50176
	ds_read_b128 v[226:229], v225 offset:51200
	ds_read_b128 v[230:233], v225 offset:52224
	ds_read_b128 v[234:237], v225 offset:53248
	ds_read_b128 v[238:241], v225 offset:54272
	ds_read_b128 v[242:245], v225 offset:55296
	ds_read_b128 v[246:249], v225 offset:56320
	global_load_lds_dwordx4 v[78:79], off
	s_add_i32 m0, s14, 0x2000
	s_add_u32 s10, s10, 0x40080
	v_lshl_add_u64 v[78:79], v[198:199], 0, s[0:1]
	s_addc_u32 s11, s11, 0
	s_add_i32 s14, s31, s20
	global_load_lds_dwordx4 v[78:79], off
	v_lshl_add_u64 v[78:79], s[10:11], 0, v[156:157]
	s_mov_b32 m0, s14
	s_nop 0
	global_load_lds_dwordx4 v[78:79], off
	v_lshl_add_u64 v[78:79], s[10:11], 0, v[160:161]
	s_add_i32 m0, s14, 0x2000
	s_nop 0
	global_load_lds_dwordx4 v[78:79], off
	v_lshl_add_u64 v[78:79], v[200:201], 0, s[0:1]
	s_mov_b32 m0, s64
	s_nop 0
	global_load_lds_dwordx4 v[78:79], off
	v_lshl_add_u64 v[78:79], v[250:251], 0, s[0:1]
	s_mov_b32 m0, s65
	s_nop 0
	global_load_lds_dwordx4 v[78:79], off
	s_waitcnt vmcnt(8)
	s_waitcnt lgkmcnt(0)
	s_barrier
	s_nop 0
	s_setprio 1
	s_waitcnt lgkmcnt(0)
	v_mfma_f32_16x16x32_bf16 v[78:81], v[46:49], v[74:77], v[86:89]
	v_mfma_f32_16x16x32_bf16 v[86:89], v[54:57], v[186:189], v[78:81]
	v_mfma_f32_16x16x32_bf16 v[78:81], v[58:61], v[74:77], v[82:85]
	v_mfma_f32_16x16x32_bf16 v[70:73], v[46:49], v[226:229], v[70:73]
	v_mfma_f32_16x16x32_bf16 v[66:69], v[58:61], v[226:229], v[66:69]
	v_mfma_f32_16x16x32_bf16 v[50:53], v[46:49], v[234:237], v[50:53]
	v_mfma_f32_16x16x32_bf16 v[42:45], v[58:61], v[234:237], v[42:45]
	v_mfma_f32_16x16x32_bf16 v[14:17], v[46:49], v[242:245], v[14:17]
	v_mfma_f32_16x16x32_bf16 v[10:13], v[58:61], v[242:245], v[10:13]
	v_mfma_f32_16x16x32_bf16 v[82:85], v[62:65], v[186:189], v[78:81]
	v_mfma_f32_16x16x32_bf16 v[70:73], v[54:57], v[230:233], v[70:73]
	v_mfma_f32_16x16x32_bf16 v[66:69], v[62:65], v[230:233], v[66:69]
	v_mfma_f32_16x16x32_bf16 v[50:53], v[54:57], v[238:241], v[50:53]
	v_mfma_f32_16x16x32_bf16 v[42:45], v[62:65], v[238:241], v[42:45]
	v_mfma_f32_16x16x32_bf16 v[14:17], v[54:57], v[246:249], v[14:17]
	v_mfma_f32_16x16x32_bf16 v[10:13], v[62:65], v[246:249], v[10:13]
	s_setprio 0
	s_setprio 1
	v_mfma_f32_16x16x32_bf16 v[18:21], v[170:173], v[74:77], v[18:21]
	v_mfma_f32_16x16x32_bf16 v[78:81], v[174:177], v[186:189], v[18:21]
	v_mfma_f32_16x16x32_bf16 v[18:21], v[178:181], v[74:77], v[22:25]
	v_mfma_f32_16x16x32_bf16 v[74:77], v[182:185], v[186:189], v[18:21]
	v_mfma_f32_16x16x32_bf16 v[18:21], v[170:173], v[226:229], v[26:29]
	v_mfma_f32_16x16x32_bf16 v[62:65], v[174:177], v[230:233], v[18:21]
	v_mfma_f32_16x16x32_bf16 v[18:21], v[178:181], v[226:229], v[30:33]
	v_mfma_f32_16x16x32_bf16 v[58:61], v[182:185], v[230:233], v[18:21]
	v_mfma_f32_16x16x32_bf16 v[18:21], v[170:173], v[234:237], v[38:41]
	v_mfma_f32_16x16x32_bf16 v[38:41], v[174:177], v[238:241], v[18:21]
	v_mfma_f32_16x16x32_bf16 v[18:21], v[178:181], v[234:237], v[34:37]
	v_mfma_f32_16x16x32_bf16 v[6:9], v[170:173], v[242:245], v[6:9]
	v_mfma_f32_16x16x32_bf16 v[2:5], v[178:181], v[242:245], v[2:5]
	v_mfma_f32_16x16x32_bf16 v[34:37], v[182:185], v[238:241], v[18:21]
	v_mfma_f32_16x16x32_bf16 v[6:9], v[174:177], v[246:249], v[6:9]
	v_mfma_f32_16x16x32_bf16 v[2:5], v[182:185], v[246:249], v[2:5]
	s_setprio 0
	s_barrier
	s_add_i32 s43, s43, 2
	s_add_u32 s8, s8, 0x100
	s_addc_u32 s9, s9, 0
	s_add_u32 s41, s41, 0x100
	s_addc_u32 s42, s42, 0
	s_cmp_gt_u32 s43, 13
	s_cbranch_scc0 .LBB0_188

; #define PG8_STAGE(bufoff, gbase, voff) do { _Pragma("unroll") for (int _i = 0; _i < 2; ++_i) \
;         __builtin_amdgcn_global_load_lds((const unsigned*)((const char*)(gbase) + (voff)[_i]), (PG8_LAS unsigned*)(lds + (bufoff) + ldsw + _i * 8192), 16, 0, 0); } while (0)
; #define PG8_LDA(dst, b, h) do { _Pragma("unroll") for (int m = 0; m < 4; ++m) _Pragma("unroll") for (int k = 0; k < 2; ++k) dst[m][k] = *(const PG8_LAS bf16x8*)(lds + PG8_SA(b, h) + aoff + m * 2048 + k * 1024); } while (0)
; #define PG8_LDB(dst, b, h) do { _Pragma("unroll") for (int n = 0; n < 2; ++n) _Pragma("unroll") for (int k = 0; k < 2; ++k) dst[n][k] = *(const PG8_LAS bf16x8*)(lds + PG8_SB(b, h) + boff + n * 2048 + k * 1024); } while (0)
; #define PG8_MMA(ai, bj, At, Bt) do { __builtin_amdgcn_s_setprio(1); _Pragma("unroll") for (int m = 0; m < 4; ++m) _Pragma("unroll") for (int n = 0; n < 2; ++n) _Pragma("unroll") for (int k = 0; k < 2; ++k) \
;         acc[ai][bj][m][n] = __builtin_amdgcn_mfma_f32_16x16x32_bf16(Bt[n][k], At[m][k], acc[ai][bj][m][n], 0, 0, 0); __builtin_amdgcn_s_setprio(0); } while (0)
; #define PG8_WAIT_V(n) asm volatile("s_waitcnt vmcnt(" #n ")" ::: "memory")
; template <class Epi, class Sched, bool ALIGN_EPI = false, bool SP2 = false>
; __device__ __forceinline__ void gemm_phase(PG8_LAS unsigned char* lds, const Gemm g, const Sched& S, const Epi& E) {
;     ...
;         const char* nA = has_next ? (const char*)g.A + (size_t)nxt.pm * tstep : cA; const char* nB = has_next ? (const char*)g.Bt + (size_t)nxt.pn * tstep : cB;
;         for (int t = 0; t < nt; t += 2) {
;             const bool last = (t == nt - 2);
;             const char* a1 = cA + (size_t)(t + 1) * kstep;
;             const char* a2 = last ? nA : cA + (size_t)(t + 2) * kstep; const char* b2 = last ? nB : cB + (size_t)(t + 2) * kstep;
;             const char* a3 = a2 + kstep; const char* b3 = b2 + kstep;
;             if (last && has_next) S.a_ready(nxt);
;             if constexpr (SP2) {
;             PG8_LDB(B0, 0, 0); PG8_LDB(B1, 0, 1); PG8_SCHED; PG8_LDA(At, 0, 0); PG8_STAGE(PG8_SA(1, 1), a1 + hstep, voffA);
;             PG8_WAIT_V(8); PG8_WAIT_L(0); PG8_BAR; PG8_MMA(0, 0, At, B0); PG8_MMA(0, 1, At, B1); PG8_BAR; PG8_SCHED;
;             PG8_LDA(At, 0, 1); PG8_STAGE(PG8_SB(0, 0), b2, voffB); PG8_STAGE(PG8_SB(0, 1), b2 + hstep, voffB); PG8_STAGE(PG8_SA(0, 0), a2, voffA);
.Lpeel_p3:
	s_add_u32 s30, s44, 0xfffc0080
	s_addc_u32 s31, s45, -1
	s_add_i32 s62, 0, 0x10000
	s_cmp_eq_u32 s61, 12
	s_cselect_b32 s49, s15, s31
	s_cselect_b32 s48, s34, s30
	s_cselect_b32 s47, s11, s60
	s_cselect_b32 s46, s35, s59
	s_add_i32 s63, 0, 0x14000
	v_add_u32_e32 v134, s62, v185
	v_add_u32_e32 v168, s63, v185
	ds_read_b128 v[114:117], v134
	ds_read_b128 v[118:121], v134 offset:1024
	ds_read_b128 v[126:129], v134 offset:2048
	ds_read_b128 v[134:137], v134 offset:3072
	ds_read_b128 v[146:149], v168
	ds_read_b128 v[150:153], v168 offset:1024
	ds_read_b128 v[164:167], v168 offset:2048
	ds_read_b128 v[168:171], v168 offset:3072
	v_lshl_add_u64 v[210:211], s[44:45], 0, v[160:161]
	s_add_i32 m0, s50, 0xc000
	ds_read_b128 v[172:175], v187
	ds_read_b128 v[176:179], v187 offset:1024
	ds_read_b128 v[180:183], v187 offset:2048
	ds_read_b128 v[188:191], v187 offset:3072
	ds_read_b128 v[198:201], v187 offset:4096
	ds_read_b128 v[202:205], v187 offset:5120
	ds_read_b128 v[206:209], v187 offset:6144
	ds_read_b128 v[222:225], v187 offset:7168
	global_load_lds_dwordx4 v[210:211], off
	v_lshl_add_u64 v[210:211], s[44:45], 0, v[162:163]
	s_add_i32 m0, s50, 0xe000
	s_nop 0
	global_load_lds_dwordx4 v[210:211], off
	s_waitcnt vmcnt(8)
	s_waitcnt lgkmcnt(0)
	s_barrier
	s_nop 0
	s_setprio 1
	s_waitcnt lgkmcnt(0)
	v_mfma_f32_16x16x32_bf16 v[142:145], v[114:117], v[172:175], 0
	v_mfma_f32_16x16x32_bf16 v[138:141], v[126:129], v[172:175], 0
	v_mfma_f32_16x16x32_bf16 v[110:113], v[114:117], v[180:183], 0
	v_mfma_f32_16x16x32_bf16 v[106:109], v[126:129], v[180:183], 0
	v_mfma_f32_16x16x32_bf16 v[94:97], v[114:117], v[198:201], 0
	v_mfma_f32_16x16x32_bf16 v[90:93], v[126:129], v[198:201], 0
	v_mfma_f32_16x16x32_bf16 v[78:81], v[114:117], v[206:209], 0
	v_mfma_f32_16x16x32_bf16 v[74:77], v[126:129], v[206:209], 0
	v_mfma_f32_16x16x32_bf16 v[142:145], v[118:121], v[176:179], v[142:145]
	v_mfma_f32_16x16x32_bf16 v[138:141], v[134:137], v[176:179], v[138:141]
	v_mfma_f32_16x16x32_bf16 v[110:113], v[118:121], v[188:191], v[110:113]
	v_mfma_f32_16x16x32_bf16 v[106:109], v[134:137], v[188:191], v[106:109]
	v_mfma_f32_16x16x32_bf16 v[94:97], v[118:121], v[202:205], v[94:97]
	v_mfma_f32_16x16x32_bf16 v[90:93], v[134:137], v[202:205], v[90:93]
	v_mfma_f32_16x16x32_bf16 v[78:81], v[118:121], v[222:225], v[78:81]
	v_mfma_f32_16x16x32_bf16 v[74:77], v[134:137], v[222:225], v[74:77]
	s_setprio 0
	s_setprio 1
	v_mfma_f32_16x16x32_bf16 v[130:133], v[146:149], v[172:175], 0
	v_mfma_f32_16x16x32_bf16 v[122:125], v[164:167], v[172:175], 0
	v_mfma_f32_16x16x32_bf16 v[102:105], v[146:149], v[180:183], 0
	v_mfma_f32_16x16x32_bf16 v[98:101], v[164:167], v[180:183], 0
	v_mfma_f32_16x16x32_bf16 v[86:89], v[146:149], v[198:201], 0
	v_mfma_f32_16x16x32_bf16 v[82:85], v[164:167], v[198:201], 0
	v_mfma_f32_16x16x32_bf16 v[70:73], v[146:149], v[206:209], 0
	v_mfma_f32_16x16x32_bf16 v[66:69], v[164:167], v[206:209], 0
	v_mfma_f32_16x16x32_bf16 v[130:133], v[150:153], v[176:179], v[130:133]
	v_mfma_f32_16x16x32_bf16 v[122:125], v[168:171], v[176:179], v[122:125]
	v_mfma_f32_16x16x32_bf16 v[102:105], v[150:153], v[188:191], v[102:105]
	v_mfma_f32_16x16x32_bf16 v[98:101], v[168:171], v[188:191], v[98:101]
	v_mfma_f32_16x16x32_bf16 v[86:89], v[150:153], v[202:205], v[86:89]
	v_mfma_f32_16x16x32_bf16 v[82:85], v[168:171], v[202:205], v[82:85]
	v_mfma_f32_16x16x32_bf16 v[70:73], v[150:153], v[222:225], v[70:73]
	v_mfma_f32_16x16x32_bf16 v[66:69], v[168:171], v[222:225], v[66:69]
	s_setprio 0
	s_barrier
	s_add_i32 s30, s62, s33
	v_lshl_add_u64 v[210:211], s[46:47], 0, v[0:1]
	s_mov_b32 m0, s30
	ds_read_b128 v[172:175], v187 offset:16384
	ds_read_b128 v[176:179], v187 offset:17408
	ds_read_b128 v[180:183], v187 offset:18432
	ds_read_b128 v[188:191], v187 offset:19456
	ds_read_b128 v[198:201], v187 offset:20480
	ds_read_b128 v[202:205], v187 offset:21504
	ds_read_b128 v[206:209], v187 offset:22528
	ds_read_b128 v[222:225], v187 offset:23552
	global_load_lds_dwordx4 v[210:211], off
	s_add_i32 m0, s30, 0x2000
	s_add_u32 s30, s46, 0x40000
	v_lshl_add_u64 v[226:227], s[46:47], 0, v[154:155]
	s_addc_u32 s31, s47, 0
	s_add_i32 s62, s63, s33
	global_load_lds_dwordx4 v[226:227], off
	v_lshl_add_u64 v[228:229], s[30:31], 0, v[0:1]
	s_mov_b32 m0, s62
	v_lshl_add_u64 v[230:231], s[48:49], 0, v[156:157]
	global_load_lds_dwordx4 v[228:229], off
	v_lshl_add_u64 v[228:229], s[30:31], 0, v[154:155]
	s_add_i32 m0, s62, 0x2000
	s_nop 0
	global_load_lds_dwordx4 v[228:229], off
	v_lshl_add_u64 v[228:229], s[48:49], 0, v[158:159]
	s_mov_b32 m0, s50
	s_nop 0
	global_load_lds_dwordx4 v[228:229], off
	s_mov_b32 m0, s51
	s_nop 0
	global_load_lds_dwordx4 v[230:231], off
	s_waitcnt vmcnt(8)
	s_waitcnt lgkmcnt(0)
	s_barrier
; #define PG8_STAGE(bufoff, gbase, voff) do { _Pragma("unroll") for (int _i = 0; _i < 2; ++_i) \
;         __builtin_amdgcn_global_load_lds((const unsigned*)((const char*)(gbase) + (voff)[_i]), (PG8_LAS unsigned*)(lds + (bufoff) + ldsw + _i * 8192), 16, 0, 0); } while (0)
; #define PG8_LDA(dst, b, h) do { _Pragma("unroll") for (int m = 0; m < 4; ++m) _Pragma("unroll") for (int k = 0; k < 2; ++k) dst[m][k] = *(const PG8_LAS bf16x8*)(lds + PG8_SA(b, h) + aoff + m * 2048 + k * 1024); } while (0)
; #define PG8_LDB(dst, b, h) do { _Pragma("unroll") for (int n = 0; n < 2; ++n) _Pragma("unroll") for (int k = 0; k < 2; ++k) dst[n][k] = *(const PG8_LAS bf16x8*)(lds + PG8_SB(b, h) + boff + n * 2048 + k * 1024); } while (0)
; #define PG8_MMA(ai, bj, At, Bt) do { __builtin_amdgcn_s_setprio(1); _Pragma("unroll") for (int m = 0; m < 4; ++m) _Pragma("unroll") for (int n = 0; n < 2; ++n) _Pragma("unroll") for (int k = 0; k < 2; ++k) \
;         acc[ai][bj][m][n] = __builtin_amdgcn_mfma_f32_16x16x32_bf16(Bt[n][k], At[m][k], acc[ai][bj][m][n], 0, 0, 0); __builtin_amdgcn_s_setprio(0); } while (0)
; #define PG8_WAIT_V(n) asm volatile("s_waitcnt vmcnt(" #n ")" ::: "memory")
; #define PG8_WAIT_L(n) asm volatile("s_waitcnt lgkmcnt(" #n ")" ::: "memory")
; #define PG8_BAR __builtin_amdgcn_s_barrier()
; #define PG8_SCHED __builtin_amdgcn_sched_barrier(0)
; template <class Epi, class Sched, bool ALIGN_EPI = false, bool SP2 = false>
; __device__ __forceinline__ void gemm_phase(PG8_LAS unsigned char* lds, const Gemm g, const Sched& S, const Epi& E) {
;     ...
;             PG8_WAIT_V(8); PG8_WAIT_L(0); PG8_BAR; PG8_MMA(0, 0, At, B0); PG8_MMA(0, 1, At, B1); PG8_BAR; PG8_SCHED;
;             PG8_LDA(At, 0, 1); PG8_STAGE(PG8_SB(0, 0), b2, voffB); PG8_STAGE(PG8_SB(0, 1), b2 + hstep, voffB); PG8_STAGE(PG8_SA(0, 0), a2, voffA);
;             PG8_WAIT_V(8); PG8_WAIT_L(0); PG8_BAR; PG8_MMA(1, 0, At, B0); PG8_MMA(1, 1, At, B1); PG8_BAR; PG8_SCHED;
;             PG8_LDB(B0, 1, 0); PG8_LDB(B1, 1, 1); PG8_SCHED; PG8_LDA(At, 1, 0); PG8_STAGE(PG8_SA(0, 1), a2 + hstep, voffA);
;             PG8_WAIT_V(8); PG8_WAIT_L(0); PG8_BAR; PG8_MMA(0, 0, At, B0); PG8_MMA(0, 1, At, B1); PG8_BAR; PG8_SCHED;
	s_nop 0
	s_setprio 1
	s_waitcnt lgkmcnt(0)
	v_mfma_f32_16x16x32_bf16 v[62:65], v[114:117], v[172:175], 0
	v_mfma_f32_16x16x32_bf16 v[58:61], v[126:129], v[172:175], 0
	v_mfma_f32_16x16x32_bf16 v[46:49], v[114:117], v[180:183], 0
	v_mfma_f32_16x16x32_bf16 v[42:45], v[126:129], v[180:183], 0
	v_mfma_f32_16x16x32_bf16 v[30:33], v[114:117], v[198:201], 0
	v_mfma_f32_16x16x32_bf16 v[26:29], v[126:129], v[198:201], 0
	v_mfma_f32_16x16x32_bf16 v[14:17], v[114:117], v[206:209], 0
	v_mfma_f32_16x16x32_bf16 v[10:13], v[126:129], v[206:209], 0
	v_mfma_f32_16x16x32_bf16 v[62:65], v[118:121], v[176:179], v[62:65]
	v_mfma_f32_16x16x32_bf16 v[58:61], v[134:137], v[176:179], v[58:61]
	v_mfma_f32_16x16x32_bf16 v[46:49], v[118:121], v[188:191], v[46:49]
	v_mfma_f32_16x16x32_bf16 v[42:45], v[134:137], v[188:191], v[42:45]
	v_mfma_f32_16x16x32_bf16 v[30:33], v[118:121], v[202:205], v[30:33]
	v_mfma_f32_16x16x32_bf16 v[26:29], v[134:137], v[202:205], v[26:29]
	v_mfma_f32_16x16x32_bf16 v[14:17], v[118:121], v[222:225], v[14:17]
	v_mfma_f32_16x16x32_bf16 v[10:13], v[134:137], v[222:225], v[10:13]
	s_setprio 0
	s_setprio 1
	v_mfma_f32_16x16x32_bf16 v[54:57], v[146:149], v[172:175], 0
	v_mfma_f32_16x16x32_bf16 v[50:53], v[164:167], v[172:175], 0
	v_mfma_f32_16x16x32_bf16 v[38:41], v[146:149], v[180:183], 0
	v_mfma_f32_16x16x32_bf16 v[34:37], v[164:167], v[180:183], 0
	v_mfma_f32_16x16x32_bf16 v[22:25], v[146:149], v[198:201], 0
	v_mfma_f32_16x16x32_bf16 v[18:21], v[164:167], v[198:201], 0
	v_mfma_f32_16x16x32_bf16 v[6:9], v[146:149], v[206:209], 0
	v_mfma_f32_16x16x32_bf16 v[2:5], v[164:167], v[206:209], 0
	v_mfma_f32_16x16x32_bf16 v[54:57], v[150:153], v[176:179], v[54:57]
	v_mfma_f32_16x16x32_bf16 v[50:53], v[168:171], v[176:179], v[50:53]
	v_mfma_f32_16x16x32_bf16 v[38:41], v[150:153], v[188:191], v[38:41]
	v_mfma_f32_16x16x32_bf16 v[34:37], v[168:171], v[188:191], v[34:37]
	v_mfma_f32_16x16x32_bf16 v[22:25], v[150:153], v[202:205], v[22:25]
	v_mfma_f32_16x16x32_bf16 v[18:21], v[168:171], v[202:205], v[18:21]
	v_mfma_f32_16x16x32_bf16 v[6:9], v[150:153], v[222:225], v[6:9]
	v_mfma_f32_16x16x32_bf16 v[2:5], v[168:171], v[222:225], v[2:5]
	s_setprio 0
	s_barrier
	s_add_i32 s62, 0, 0x18000
	s_add_i32 s63, 0, 0x1c000
	v_add_u32_e32 v134, s62, v185
	v_add_u32_e32 v168, s63, v185
	ds_read_b128 v[114:117], v134
	ds_read_b128 v[118:121], v134 offset:1024
	ds_read_b128 v[126:129], v134 offset:2048
	ds_read_b128 v[134:137], v134 offset:3072
	ds_read_b128 v[146:149], v168
	ds_read_b128 v[150:153], v168 offset:1024
	ds_read_b128 v[164:167], v168 offset:2048
	ds_read_b128 v[168:171], v168 offset:3072
	s_add_u32 s30, s48, 0x40000
	s_addc_u32 s31, s49, 0
	s_mov_b32 m0, s52
	v_lshl_add_u64 v[232:233], s[30:31], 0, v[158:159]
	ds_read_b128 v[172:175], v187 offset:32768
	ds_read_b128 v[176:179], v187 offset:33792
	ds_read_b128 v[180:183], v187 offset:34816
	ds_read_b128 v[188:191], v187 offset:35840
	ds_read_b128 v[198:201], v187 offset:36864
	ds_read_b128 v[202:205], v187 offset:37888
	ds_read_b128 v[206:209], v187 offset:38912
	ds_read_b128 v[222:225], v187 offset:39936
	global_load_lds_dwordx4 v[232:233], off
	v_lshl_add_u64 v[232:233], s[30:31], 0, v[156:157]
	s_mov_b32 m0, s53
	s_nop 0
	global_load_lds_dwordx4 v[232:233], off
	s_waitcnt vmcnt(8)
	s_waitcnt lgkmcnt(0)
	s_barrier
	s_nop 0
	s_setprio 1
	s_waitcnt lgkmcnt(0)
	v_mfma_f32_16x16x32_bf16 v[142:145], v[114:117], v[172:175], v[142:145]
	v_mfma_f32_16x16x32_bf16 v[138:141], v[126:129], v[172:175], v[138:141]
	v_mfma_f32_16x16x32_bf16 v[110:113], v[114:117], v[180:183], v[110:113]
	v_mfma_f32_16x16x32_bf16 v[106:109], v[126:129], v[180:183], v[106:109]
	v_mfma_f32_16x16x32_bf16 v[94:97], v[114:117], v[198:201], v[94:97]
	v_mfma_f32_16x16x32_bf16 v[90:93], v[126:129], v[198:201], v[90:93]
	v_mfma_f32_16x16x32_bf16 v[78:81], v[114:117], v[206:209], v[78:81]
	v_mfma_f32_16x16x32_bf16 v[74:77], v[126:129], v[206:209], v[74:77]
	v_mfma_f32_16x16x32_bf16 v[142:145], v[118:121], v[176:179], v[142:145]
	v_mfma_f32_16x16x32_bf16 v[138:141], v[134:137], v[176:179], v[138:141]
	v_mfma_f32_16x16x32_bf16 v[110:113], v[118:121], v[188:191], v[110:113]
	v_mfma_f32_16x16x32_bf16 v[106:109], v[134:137], v[188:191], v[106:109]
	v_mfma_f32_16x16x32_bf16 v[94:97], v[118:121], v[202:205], v[94:97]
	v_mfma_f32_16x16x32_bf16 v[90:93], v[134:137], v[202:205], v[90:93]
	v_mfma_f32_16x16x32_bf16 v[78:81], v[118:121], v[222:225], v[78:81]
	v_mfma_f32_16x16x32_bf16 v[74:77], v[134:137], v[222:225], v[74:77]
	s_setprio 0
	s_setprio 1
	v_mfma_f32_16x16x32_bf16 v[130:133], v[146:149], v[172:175], v[130:133]
	v_mfma_f32_16x16x32_bf16 v[122:125], v[164:167], v[172:175], v[122:125]
	v_mfma_f32_16x16x32_bf16 v[102:105], v[146:149], v[180:183], v[102:105]
	v_mfma_f32_16x16x32_bf16 v[98:101], v[164:167], v[180:183], v[98:101]
	v_mfma_f32_16x16x32_bf16 v[86:89], v[146:149], v[198:201], v[86:89]
	v_mfma_f32_16x16x32_bf16 v[82:85], v[164:167], v[198:201], v[82:85]
	v_mfma_f32_16x16x32_bf16 v[70:73], v[146:149], v[206:209], v[70:73]
	v_mfma_f32_16x16x32_bf16 v[66:69], v[164:167], v[206:209], v[66:69]
	v_mfma_f32_16x16x32_bf16 v[130:133], v[150:153], v[176:179], v[130:133]
	v_mfma_f32_16x16x32_bf16 v[122:125], v[168:171], v[176:179], v[122:125]
	v_mfma_f32_16x16x32_bf16 v[102:105], v[150:153], v[188:191], v[102:105]
	v_mfma_f32_16x16x32_bf16 v[98:101], v[168:171], v[188:191], v[98:101]
	v_mfma_f32_16x16x32_bf16 v[86:89], v[150:153], v[202:205], v[86:89]
	v_mfma_f32_16x16x32_bf16 v[82:85], v[168:171], v[202:205], v[82:85]
	v_mfma_f32_16x16x32_bf16 v[70:73], v[150:153], v[222:225], v[70:73]
	v_mfma_f32_16x16x32_bf16 v[66:69], v[168:171], v[222:225], v[66:69]
	s_setprio 0
	s_barrier
; #define PG8_STAGE(bufoff, gbase, voff) do { _Pragma("unroll") for (int _i = 0; _i < 2; ++_i) \
;         __builtin_amdgcn_global_load_lds((const unsigned*)((const char*)(gbase) + (voff)[_i]), (PG8_LAS unsigned*)(lds + (bufoff) + ldsw + _i * 8192), 16, 0, 0); } while (0)
; #define PG8_LDA(dst, b, h) do { _Pragma("unroll") for (int m = 0; m < 4; ++m) _Pragma("unroll") for (int k = 0; k < 2; ++k) dst[m][k] = *(const PG8_LAS bf16x8*)(lds + PG8_SA(b, h) + aoff + m * 2048 + k * 1024); } while (0)
; #define PG8_LDB(dst, b, h) do { _Pragma("unroll") for (int n = 0; n < 2; ++n) _Pragma("unroll") for (int k = 0; k < 2; ++k) dst[n][k] = *(const PG8_LAS bf16x8*)(lds + PG8_SB(b, h) + boff + n * 2048 + k * 1024); } while (0)
; #define PG8_MMA(ai, bj, At, Bt) do { __builtin_amdgcn_s_setprio(1); _Pragma("unroll") for (int m = 0; m < 4; ++m) _Pragma("unroll") for (int n = 0; n < 2; ++n) _Pragma("unroll") for (int k = 0; k < 2; ++k) \
;         acc[ai][bj][m][n] = __builtin_amdgcn_mfma_f32_16x16x32_bf16(Bt[n][k], At[m][k], acc[ai][bj][m][n], 0, 0, 0); __builtin_amdgcn_s_setprio(0); } while (0)
; #define PG8_WAIT_V(n) asm volatile("s_waitcnt vmcnt(" #n ")" ::: "memory")
; template <class Epi, class Sched, bool ALIGN_EPI = false, bool SP2 = false>
; __device__ __forceinline__ void gemm_phase(PG8_LAS unsigned char* lds, const Gemm g, const Sched& S, const Epi& E) {
;     ...
;             PG8_LDB(B0, 0, 0); PG8_LDB(B1, 0, 1); PG8_SCHED; PG8_LDA(At, 0, 0); PG8_STAGE(PG8_SA(1, 1), a1 + hstep, voffA);
;             PG8_WAIT_V(8); PG8_WAIT_L(0); PG8_BAR; PG8_MMA(0, 0, At, B0); PG8_MMA(0, 1, At, B1); PG8_BAR; PG8_SCHED;
;             PG8_LDA(At, 0, 1); PG8_STAGE(PG8_SB(0, 0), b2, voffB); PG8_STAGE(PG8_SB(0, 1), b2 + hstep, voffB); PG8_STAGE(PG8_SA(0, 0), a2, voffA);
;             PG8_WAIT_V(8); PG8_WAIT_L(0); PG8_BAR; PG8_MMA(1, 0, At, B0); PG8_MMA(1, 1, At, B1); PG8_BAR; PG8_SCHED;
;             PG8_LDB(B0, 1, 0); PG8_LDB(B1, 1, 1); PG8_SCHED; PG8_LDA(At, 1, 0); PG8_STAGE(PG8_SA(0, 1), a2 + hstep, voffA);
;             PG8_WAIT_V(8); PG8_WAIT_L(0); PG8_BAR; PG8_MMA(0, 0, At, B0); PG8_MMA(0, 1, At, B1); PG8_BAR; PG8_SCHED;
;             PG8_LDA(At, 1, 1); PG8_STAGE(PG8_SB(1, 0), b3, voffB); PG8_STAGE(PG8_SB(1, 1), b3 + hstep, voffB); PG8_STAGE(PG8_SA(1, 0), a3, voffA);
;             PG8_WAIT_V(8); PG8_WAIT_L(0); PG8_BAR; PG8_MMA(1, 0, At, B0); PG8_MMA(1, 1, At, B1); PG8_BAR; PG8_SCHED;
	s_add_i32 s30, s62, s33
	v_lshl_add_u64 v[210:211], v[210:211], 0, s[0:1]
	s_mov_b32 m0, s30
	ds_read_b128 v[172:175], v187 offset:49152
	ds_read_b128 v[176:179], v187 offset:50176
	ds_read_b128 v[180:183], v187 offset:51200
	ds_read_b128 v[188:191], v187 offset:52224
	ds_read_b128 v[198:201], v187 offset:53248
	ds_read_b128 v[202:205], v187 offset:54272
	ds_read_b128 v[206:209], v187 offset:55296
	ds_read_b128 v[222:225], v187 offset:56320
	global_load_lds_dwordx4 v[210:211], off
	s_add_i32 m0, s30, 0x2000
	s_add_u32 s30, s46, 0x40080
	v_lshl_add_u64 v[210:211], v[226:227], 0, s[0:1]
	s_addc_u32 s31, s47, 0
	s_add_i32 s46, s63, s33
	global_load_lds_dwordx4 v[210:211], off
	v_lshl_add_u64 v[210:211], s[30:31], 0, v[0:1]
	s_mov_b32 m0, s46
	s_nop 0
	global_load_lds_dwordx4 v[210:211], off
	v_lshl_add_u64 v[210:211], s[30:31], 0, v[154:155]
	s_add_i32 m0, s46, 0x2000
	s_nop 0
	global_load_lds_dwordx4 v[210:211], off
	v_lshl_add_u64 v[210:211], v[228:229], 0, s[0:1]
	s_mov_b32 m0, s56
	s_nop 0
	global_load_lds_dwordx4 v[210:211], off
	v_lshl_add_u64 v[210:211], v[230:231], 0, s[0:1]
	s_mov_b32 m0, s57
	s_nop 0
	global_load_lds_dwordx4 v[210:211], off
	s_waitcnt vmcnt(8)
	s_waitcnt lgkmcnt(0)
	s_barrier
	s_setprio 1
	s_waitcnt lgkmcnt(0)
	v_mfma_f32_16x16x32_bf16 v[62:65], v[114:117], v[172:175], v[62:65]
	v_mfma_f32_16x16x32_bf16 v[58:61], v[126:129], v[172:175], v[58:61]
	v_mfma_f32_16x16x32_bf16 v[46:49], v[114:117], v[180:183], v[46:49]
	v_mfma_f32_16x16x32_bf16 v[42:45], v[126:129], v[180:183], v[42:45]
	v_mfma_f32_16x16x32_bf16 v[30:33], v[114:117], v[198:201], v[30:33]
	v_mfma_f32_16x16x32_bf16 v[26:29], v[126:129], v[198:201], v[26:29]
	v_mfma_f32_16x16x32_bf16 v[14:17], v[114:117], v[206:209], v[14:17]
	v_mfma_f32_16x16x32_bf16 v[10:13], v[126:129], v[206:209], v[10:13]
	v_mfma_f32_16x16x32_bf16 v[62:65], v[118:121], v[176:179], v[62:65]
	v_mfma_f32_16x16x32_bf16 v[58:61], v[134:137], v[176:179], v[58:61]
	v_mfma_f32_16x16x32_bf16 v[46:49], v[118:121], v[188:191], v[46:49]
	v_mfma_f32_16x16x32_bf16 v[42:45], v[134:137], v[188:191], v[42:45]
	v_mfma_f32_16x16x32_bf16 v[30:33], v[118:121], v[202:205], v[30:33]
	v_mfma_f32_16x16x32_bf16 v[26:29], v[134:137], v[202:205], v[26:29]
	v_mfma_f32_16x16x32_bf16 v[14:17], v[118:121], v[222:225], v[14:17]
	v_mfma_f32_16x16x32_bf16 v[10:13], v[134:137], v[222:225], v[10:13]
	s_setprio 0
	s_setprio 1
	v_mfma_f32_16x16x32_bf16 v[54:57], v[146:149], v[172:175], v[54:57]
	v_mfma_f32_16x16x32_bf16 v[50:53], v[164:167], v[172:175], v[50:53]
	v_mfma_f32_16x16x32_bf16 v[38:41], v[146:149], v[180:183], v[38:41]
	v_mfma_f32_16x16x32_bf16 v[34:37], v[164:167], v[180:183], v[34:37]
	v_mfma_f32_16x16x32_bf16 v[22:25], v[146:149], v[198:201], v[22:25]
	v_mfma_f32_16x16x32_bf16 v[18:21], v[164:167], v[198:201], v[18:21]
	v_mfma_f32_16x16x32_bf16 v[6:9], v[146:149], v[206:209], v[6:9]
	v_mfma_f32_16x16x32_bf16 v[2:5], v[164:167], v[206:209], v[2:5]
	v_mfma_f32_16x16x32_bf16 v[54:57], v[150:153], v[176:179], v[54:57]
	v_mfma_f32_16x16x32_bf16 v[50:53], v[168:171], v[176:179], v[50:53]
	v_mfma_f32_16x16x32_bf16 v[38:41], v[150:153], v[188:191], v[38:41]
	v_mfma_f32_16x16x32_bf16 v[34:37], v[168:171], v[188:191], v[34:37]
	v_mfma_f32_16x16x32_bf16 v[22:25], v[150:153], v[202:205], v[22:25]
	v_mfma_f32_16x16x32_bf16 v[18:21], v[168:171], v[202:205], v[18:21]
	v_mfma_f32_16x16x32_bf16 v[6:9], v[150:153], v[222:225], v[6:9]
	v_mfma_f32_16x16x32_bf16 v[2:5], v[168:171], v[222:225], v[2:5]
	s_setprio 0
	s_barrier
	s_add_i32 s61, s61, 2
	s_add_u32 s44, s44, 0x100
	s_addc_u32 s45, s45, 0
	s_add_u32 s59, s59, 0x100
	s_addc_u32 s60, s60, 0
	s_cmp_gt_u32 s61, 13
	s_cbranch_scc0 .LBB0_676
	s_branch .Lpeel_exit_p3
.LBB0_676:
	s_add_u32 s30, s44, 0xfffc0080
	s_addc_u32 s31, s45, -1
	s_add_i32 s62, 0, 0x10000
	s_cmp_eq_u32 s61, 12
	s_cselect_b32 s49, s15, s31
	s_cselect_b32 s48, s34, s30
	s_cselect_b32 s47, s11, s60
	s_cselect_b32 s46, s35, s59
	s_add_i32 s63, 0, 0x14000
	v_add_u32_e32 v134, s62, v185
	v_add_u32_e32 v168, s63, v185
	ds_read_b128 v[114:117], v134
	ds_read_b128 v[118:121], v134 offset:1024
	ds_read_b128 v[126:129], v134 offset:2048
	ds_read_b128 v[134:137], v134 offset:3072
	ds_read_b128 v[146:149], v168
	ds_read_b128 v[150:153], v168 offset:1024
	ds_read_b128 v[164:167], v168 offset:2048
	ds_read_b128 v[168:171], v168 offset:3072
	v_lshl_add_u64 v[210:211], s[44:45], 0, v[160:161]
	s_add_i32 m0, s50, 0xc000
	ds_read_b128 v[172:175], v187
	ds_read_b128 v[176:179], v187 offset:1024
	ds_read_b128 v[180:183], v187 offset:2048
	ds_read_b128 v[188:191], v187 offset:3072
	ds_read_b128 v[198:201], v187 offset:4096
	ds_read_b128 v[202:205], v187 offset:5120
	ds_read_b128 v[206:209], v187 offset:6144
	ds_read_b128 v[222:225], v187 offset:7168
	global_load_lds_dwordx4 v[210:211], off
	v_lshl_add_u64 v[210:211], s[44:45], 0, v[162:163]
	s_add_i32 m0, s50, 0xe000
	s_nop 0
	global_load_lds_dwordx4 v[210:211], off
	s_waitcnt vmcnt(8)
	s_waitcnt lgkmcnt(0)
	s_barrier
; #define PG8_STAGE(bufoff, gbase, voff) do { _Pragma("unroll") for (int _i = 0; _i < 2; ++_i) \
;         __builtin_amdgcn_global_load_lds((const unsigned*)((const char*)(gbase) + (voff)[_i]), (PG8_LAS unsigned*)(lds + (bufoff) + ldsw + _i * 8192), 16, 0, 0); } while (0)
; #define PG8_LDA(dst, b, h) do { _Pragma("unroll") for (int m = 0; m < 4; ++m) _Pragma("unroll") for (int k = 0; k < 2; ++k) dst[m][k] = *(const PG8_LAS bf16x8*)(lds + PG8_SA(b, h) + aoff + m * 2048 + k * 1024); } while (0)
; #define PG8_MMA(ai, bj, At, Bt) do { __builtin_amdgcn_s_setprio(1); _Pragma("unroll") for (int m = 0; m < 4; ++m) _Pragma("unroll") for (int n = 0; n < 2; ++n) _Pragma("unroll") for (int k = 0; k < 2; ++k) \
;         acc[ai][bj][m][n] = __builtin_amdgcn_mfma_f32_16x16x32_bf16(Bt[n][k], At[m][k], acc[ai][bj][m][n], 0, 0, 0); __builtin_amdgcn_s_setprio(0); } while (0)
; #define PG8_WAIT_V(n) asm volatile("s_waitcnt vmcnt(" #n ")" ::: "memory")
; #define PG8_WAIT_L(n) asm volatile("s_waitcnt lgkmcnt(" #n ")" ::: "memory")
; #define PG8_BAR __builtin_amdgcn_s_barrier()
; #define PG8_SCHED __builtin_amdgcn_sched_barrier(0)
; template <class Epi, class Sched, bool ALIGN_EPI = false, bool SP2 = false>
; __device__ __forceinline__ void gemm_phase(PG8_LAS unsigned char* lds, const Gemm g, const Sched& S, const Epi& E) {
;     ...
;             PG8_WAIT_V(8); PG8_WAIT_L(0); PG8_BAR; PG8_MMA(0, 0, At, B0); PG8_MMA(0, 1, At, B1); PG8_BAR; PG8_SCHED;
;             PG8_LDA(At, 0, 1); PG8_STAGE(PG8_SB(0, 0), b2, voffB); PG8_STAGE(PG8_SB(0, 1), b2 + hstep, voffB); PG8_STAGE(PG8_SA(0, 0), a2, voffA);
;             PG8_WAIT_V(8); PG8_WAIT_L(0); PG8_BAR; PG8_MMA(1, 0, At, B0); PG8_MMA(1, 1, At, B1); PG8_BAR; PG8_SCHED;
	s_setprio 1
	s_waitcnt lgkmcnt(0)
	v_mfma_f32_16x16x32_bf16 v[142:145], v[114:117], v[172:175], v[142:145]
	v_mfma_f32_16x16x32_bf16 v[138:141], v[126:129], v[172:175], v[138:141]
	v_mfma_f32_16x16x32_bf16 v[110:113], v[114:117], v[180:183], v[110:113]
	v_mfma_f32_16x16x32_bf16 v[106:109], v[126:129], v[180:183], v[106:109]
	v_mfma_f32_16x16x32_bf16 v[94:97], v[114:117], v[198:201], v[94:97]
	v_mfma_f32_16x16x32_bf16 v[90:93], v[126:129], v[198:201], v[90:93]
	v_mfma_f32_16x16x32_bf16 v[78:81], v[114:117], v[206:209], v[78:81]
	v_mfma_f32_16x16x32_bf16 v[74:77], v[126:129], v[206:209], v[74:77]
	v_mfma_f32_16x16x32_bf16 v[142:145], v[118:121], v[176:179], v[142:145]
	v_mfma_f32_16x16x32_bf16 v[138:141], v[134:137], v[176:179], v[138:141]
	v_mfma_f32_16x16x32_bf16 v[110:113], v[118:121], v[188:191], v[110:113]
	v_mfma_f32_16x16x32_bf16 v[106:109], v[134:137], v[188:191], v[106:109]
	v_mfma_f32_16x16x32_bf16 v[94:97], v[118:121], v[202:205], v[94:97]
	v_mfma_f32_16x16x32_bf16 v[90:93], v[134:137], v[202:205], v[90:93]
	v_mfma_f32_16x16x32_bf16 v[78:81], v[118:121], v[222:225], v[78:81]
	v_mfma_f32_16x16x32_bf16 v[74:77], v[134:137], v[222:225], v[74:77]
	s_setprio 0
	s_setprio 1
	v_mfma_f32_16x16x32_bf16 v[130:133], v[146:149], v[172:175], v[130:133]
	v_mfma_f32_16x16x32_bf16 v[122:125], v[164:167], v[172:175], v[122:125]
	v_mfma_f32_16x16x32_bf16 v[102:105], v[146:149], v[180:183], v[102:105]
	v_mfma_f32_16x16x32_bf16 v[98:101], v[164:167], v[180:183], v[98:101]
	v_mfma_f32_16x16x32_bf16 v[86:89], v[146:149], v[198:201], v[86:89]
	v_mfma_f32_16x16x32_bf16 v[82:85], v[164:167], v[198:201], v[82:85]
	v_mfma_f32_16x16x32_bf16 v[70:73], v[146:149], v[206:209], v[70:73]
	v_mfma_f32_16x16x32_bf16 v[66:69], v[164:167], v[206:209], v[66:69]
	v_mfma_f32_16x16x32_bf16 v[130:133], v[150:153], v[176:179], v[130:133]
	v_mfma_f32_16x16x32_bf16 v[122:125], v[168:171], v[176:179], v[122:125]
	v_mfma_f32_16x16x32_bf16 v[102:105], v[150:153], v[188:191], v[102:105]
	v_mfma_f32_16x16x32_bf16 v[98:101], v[168:171], v[188:191], v[98:101]
	v_mfma_f32_16x16x32_bf16 v[86:89], v[150:153], v[202:205], v[86:89]
	v_mfma_f32_16x16x32_bf16 v[82:85], v[168:171], v[202:205], v[82:85]
	v_mfma_f32_16x16x32_bf16 v[70:73], v[150:153], v[222:225], v[70:73]
	v_mfma_f32_16x16x32_bf16 v[66:69], v[168:171], v[222:225], v[66:69]
	s_setprio 0
	s_barrier
	s_add_i32 s30, s62, s33
	v_lshl_add_u64 v[210:211], s[46:47], 0, v[0:1]
	s_mov_b32 m0, s30
	ds_read_b128 v[172:175], v187 offset:16384
	ds_read_b128 v[176:179], v187 offset:17408
	ds_read_b128 v[180:183], v187 offset:18432
	ds_read_b128 v[188:191], v187 offset:19456
	ds_read_b128 v[198:201], v187 offset:20480
	ds_read_b128 v[202:205], v187 offset:21504
	ds_read_b128 v[206:209], v187 offset:22528
	ds_read_b128 v[222:225], v187 offset:23552
	global_load_lds_dwordx4 v[210:211], off
	s_add_i32 m0, s30, 0x2000
	s_add_u32 s30, s46, 0x40000
	v_lshl_add_u64 v[226:227], s[46:47], 0, v[154:155]
	s_addc_u32 s31, s47, 0
	s_add_i32 s62, s63, s33
	global_load_lds_dwordx4 v[226:227], off
	v_lshl_add_u64 v[228:229], s[30:31], 0, v[0:1]
	s_mov_b32 m0, s62
	v_lshl_add_u64 v[230:231], s[48:49], 0, v[156:157]
	global_load_lds_dwordx4 v[228:229], off
	v_lshl_add_u64 v[228:229], s[30:31], 0, v[154:155]
	s_add_i32 m0, s62, 0x2000
	s_nop 0
	global_load_lds_dwordx4 v[228:229], off
	v_lshl_add_u64 v[228:229], s[48:49], 0, v[158:159]
	s_mov_b32 m0, s50
	s_nop 0
	global_load_lds_dwordx4 v[228:229], off
	s_mov_b32 m0, s51
	s_nop 0
	global_load_lds_dwordx4 v[230:231], off
	s_waitcnt vmcnt(8)
	s_waitcnt lgkmcnt(0)
	s_barrier
	s_nop 0
	s_setprio 1
	s_waitcnt lgkmcnt(0)
	v_mfma_f32_16x16x32_bf16 v[62:65], v[114:117], v[172:175], v[62:65]
	v_mfma_f32_16x16x32_bf16 v[58:61], v[126:129], v[172:175], v[58:61]
	v_mfma_f32_16x16x32_bf16 v[46:49], v[114:117], v[180:183], v[46:49]
	v_mfma_f32_16x16x32_bf16 v[42:45], v[126:129], v[180:183], v[42:45]
	v_mfma_f32_16x16x32_bf16 v[30:33], v[114:117], v[198:201], v[30:33]
	v_mfma_f32_16x16x32_bf16 v[26:29], v[126:129], v[198:201], v[26:29]
	v_mfma_f32_16x16x32_bf16 v[14:17], v[114:117], v[206:209], v[14:17]
	v_mfma_f32_16x16x32_bf16 v[10:13], v[126:129], v[206:209], v[10:13]
	v_mfma_f32_16x16x32_bf16 v[62:65], v[118:121], v[176:179], v[62:65]
	v_mfma_f32_16x16x32_bf16 v[58:61], v[134:137], v[176:179], v[58:61]
	v_mfma_f32_16x16x32_bf16 v[46:49], v[118:121], v[188:191], v[46:49]
	v_mfma_f32_16x16x32_bf16 v[42:45], v[134:137], v[188:191], v[42:45]
	v_mfma_f32_16x16x32_bf16 v[30:33], v[118:121], v[202:205], v[30:33]
	v_mfma_f32_16x16x32_bf16 v[26:29], v[134:137], v[202:205], v[26:29]
	v_mfma_f32_16x16x32_bf16 v[14:17], v[118:121], v[222:225], v[14:17]
	v_mfma_f32_16x16x32_bf16 v[10:13], v[134:137], v[222:225], v[10:13]
	s_setprio 0
	s_setprio 1
	v_mfma_f32_16x16x32_bf16 v[54:57], v[146:149], v[172:175], v[54:57]
	v_mfma_f32_16x16x32_bf16 v[50:53], v[164:167], v[172:175], v[50:53]
	v_mfma_f32_16x16x32_bf16 v[38:41], v[146:149], v[180:183], v[38:41]
	v_mfma_f32_16x16x32_bf16 v[34:37], v[164:167], v[180:183], v[34:37]
	v_mfma_f32_16x16x32_bf16 v[22:25], v[146:149], v[198:201], v[22:25]
	v_mfma_f32_16x16x32_bf16 v[18:21], v[164:167], v[198:201], v[18:21]
	v_mfma_f32_16x16x32_bf16 v[6:9], v[146:149], v[206:209], v[6:9]
	v_mfma_f32_16x16x32_bf16 v[2:5], v[164:167], v[206:209], v[2:5]
	v_mfma_f32_16x16x32_bf16 v[54:57], v[150:153], v[176:179], v[54:57]
	v_mfma_f32_16x16x32_bf16 v[50:53], v[168:171], v[176:179], v[50:53]
	v_mfma_f32_16x16x32_bf16 v[38:41], v[150:153], v[188:191], v[38:41]
	v_mfma_f32_16x16x32_bf16 v[34:37], v[168:171], v[188:191], v[34:37]
	v_mfma_f32_16x16x32_bf16 v[22:25], v[150:153], v[202:205], v[22:25]
	v_mfma_f32_16x16x32_bf16 v[18:21], v[168:171], v[202:205], v[18:21]
	v_mfma_f32_16x16x32_bf16 v[6:9], v[150:153], v[222:225], v[6:9]
	v_mfma_f32_16x16x32_bf16 v[2:5], v[168:171], v[222:225], v[2:5]
	s_setprio 0
	s_barrier
; #define PG8_STAGE(bufoff, gbase, voff) do { _Pragma("unroll") for (int _i = 0; _i < 2; ++_i) \
;         __builtin_amdgcn_global_load_lds((const unsigned*)((const char*)(gbase) + (voff)[_i]), (PG8_LAS unsigned*)(lds + (bufoff) + ldsw + _i * 8192), 16, 0, 0); } while (0)
; #define PG8_LDA(dst, b, h) do { _Pragma("unroll") for (int m = 0; m < 4; ++m) _Pragma("unroll") for (int k = 0; k < 2; ++k) dst[m][k] = *(const PG8_LAS bf16x8*)(lds + PG8_SA(b, h) + aoff + m * 2048 + k * 1024); } while (0)
; #define PG8_LDB(dst, b, h) do { _Pragma("unroll") for (int n = 0; n < 2; ++n) _Pragma("unroll") for (int k = 0; k < 2; ++k) dst[n][k] = *(const PG8_LAS bf16x8*)(lds + PG8_SB(b, h) + boff + n * 2048 + k * 1024); } while (0)
; #define PG8_MMA(ai, bj, At, Bt) do { __builtin_amdgcn_s_setprio(1); _Pragma("unroll") for (int m = 0; m < 4; ++m) _Pragma("unroll") for (int n = 0; n < 2; ++n) _Pragma("unroll") for (int k = 0; k < 2; ++k) \
;         acc[ai][bj][m][n] = __builtin_amdgcn_mfma_f32_16x16x32_bf16(Bt[n][k], At[m][k], acc[ai][bj][m][n], 0, 0, 0); __builtin_amdgcn_s_setprio(0); } while (0)
; #define PG8_WAIT_V(n) asm volatile("s_waitcnt vmcnt(" #n ")" ::: "memory")
; #define PG8_WAIT_L(n) asm volatile("s_waitcnt lgkmcnt(" #n ")" ::: "memory")
; #define PG8_BAR __builtin_amdgcn_s_barrier()
; #define PG8_SCHED __builtin_amdgcn_sched_barrier(0)
; template <class Epi, class Sched, bool ALIGN_EPI = false, bool SP2 = false>
; __device__ __forceinline__ void gemm_phase(PG8_LAS unsigned char* lds, const Gemm g, const Sched& S, const Epi& E) {
;     ...
;             PG8_LDB(B0, 1, 0); PG8_LDB(B1, 1, 1); PG8_SCHED; PG8_LDA(At, 1, 0); PG8_STAGE(PG8_SA(0, 1), a2 + hstep, voffA);
;             PG8_WAIT_V(8); PG8_WAIT_L(0); PG8_BAR; PG8_MMA(0, 0, At, B0); PG8_MMA(0, 1, At, B1); PG8_BAR; PG8_SCHED;
	s_add_i32 s62, 0, 0x18000
	s_add_i32 s63, 0, 0x1c000
	v_add_u32_e32 v134, s62, v185
	v_add_u32_e32 v168, s63, v185
	ds_read_b128 v[114:117], v134
	ds_read_b128 v[118:121], v134 offset:1024
	ds_read_b128 v[126:129], v134 offset:2048
	ds_read_b128 v[134:137], v134 offset:3072
	ds_read_b128 v[146:149], v168
	ds_read_b128 v[150:153], v168 offset:1024
	ds_read_b128 v[164:167], v168 offset:2048
	ds_read_b128 v[168:171], v168 offset:3072
	s_add_u32 s30, s48, 0x40000
	s_addc_u32 s31, s49, 0
	s_mov_b32 m0, s52
	v_lshl_add_u64 v[232:233], s[30:31], 0, v[158:159]
	ds_read_b128 v[172:175], v187 offset:32768
	ds_read_b128 v[176:179], v187 offset:33792
	ds_read_b128 v[180:183], v187 offset:34816
	ds_read_b128 v[188:191], v187 offset:35840
	ds_read_b128 v[198:201], v187 offset:36864
	ds_read_b128 v[202:205], v187 offset:37888
	ds_read_b128 v[206:209], v187 offset:38912
	ds_read_b128 v[222:225], v187 offset:39936
	global_load_lds_dwordx4 v[232:233], off
	v_lshl_add_u64 v[232:233], s[30:31], 0, v[156:157]
	s_mov_b32 m0, s53
	s_nop 0
	global_load_lds_dwordx4 v[232:233], off
	s_waitcnt vmcnt(8)
	s_waitcnt lgkmcnt(0)
	s_barrier
	s_nop 0
	s_setprio 1
	s_waitcnt lgkmcnt(0)
	v_mfma_f32_16x16x32_bf16 v[142:145], v[114:117], v[172:175], v[142:145]
	v_mfma_f32_16x16x32_bf16 v[138:141], v[126:129], v[172:175], v[138:141]
	v_mfma_f32_16x16x32_bf16 v[110:113], v[114:117], v[180:183], v[110:113]
	v_mfma_f32_16x16x32_bf16 v[106:109], v[126:129], v[180:183], v[106:109]
	v_mfma_f32_16x16x32_bf16 v[94:97], v[114:117], v[198:201], v[94:97]
	v_mfma_f32_16x16x32_bf16 v[90:93], v[126:129], v[198:201], v[90:93]
	v_mfma_f32_16x16x32_bf16 v[78:81], v[114:117], v[206:209], v[78:81]
	v_mfma_f32_16x16x32_bf16 v[74:77], v[126:129], v[206:209], v[74:77]
	v_mfma_f32_16x16x32_bf16 v[142:145], v[118:121], v[176:179], v[142:145]
	v_mfma_f32_16x16x32_bf16 v[138:141], v[134:137], v[176:179], v[138:141]
	v_mfma_f32_16x16x32_bf16 v[110:113], v[118:121], v[188:191], v[110:113]
	v_mfma_f32_16x16x32_bf16 v[106:109], v[134:137], v[188:191], v[106:109]
	v_mfma_f32_16x16x32_bf16 v[94:97], v[118:121], v[202:205], v[94:97]
	v_mfma_f32_16x16x32_bf16 v[90:93], v[134:137], v[202:205], v[90:93]
	v_mfma_f32_16x16x32_bf16 v[78:81], v[118:121], v[222:225], v[78:81]
	v_mfma_f32_16x16x32_bf16 v[74:77], v[134:137], v[222:225], v[74:77]
	s_setprio 0
	s_setprio 1
	v_mfma_f32_16x16x32_bf16 v[130:133], v[146:149], v[172:175], v[130:133]
	v_mfma_f32_16x16x32_bf16 v[122:125], v[164:167], v[172:175], v[122:125]
	v_mfma_f32_16x16x32_bf16 v[102:105], v[146:149], v[180:183], v[102:105]
	v_mfma_f32_16x16x32_bf16 v[98:101], v[164:167], v[180:183], v[98:101]
	v_mfma_f32_16x16x32_bf16 v[86:89], v[146:149], v[198:201], v[86:89]
	v_mfma_f32_16x16x32_bf16 v[82:85], v[164:167], v[198:201], v[82:85]
	v_mfma_f32_16x16x32_bf16 v[70:73], v[146:149], v[206:209], v[70:73]
	v_mfma_f32_16x16x32_bf16 v[66:69], v[164:167], v[206:209], v[66:69]
	v_mfma_f32_16x16x32_bf16 v[130:133], v[150:153], v[176:179], v[130:133]
	v_mfma_f32_16x16x32_bf16 v[122:125], v[168:171], v[176:179], v[122:125]
	v_mfma_f32_16x16x32_bf16 v[102:105], v[150:153], v[188:191], v[102:105]
	v_mfma_f32_16x16x32_bf16 v[98:101], v[168:171], v[188:191], v[98:101]
	v_mfma_f32_16x16x32_bf16 v[86:89], v[150:153], v[202:205], v[86:89]
	v_mfma_f32_16x16x32_bf16 v[82:85], v[168:171], v[202:205], v[82:85]
	v_mfma_f32_16x16x32_bf16 v[70:73], v[150:153], v[222:225], v[70:73]
	v_mfma_f32_16x16x32_bf16 v[66:69], v[168:171], v[222:225], v[66:69]
	s_setprio 0
	s_barrier
; #define PG8_STAGE(bufoff, gbase, voff) do { _Pragma("unroll") for (int _i = 0; _i < 2; ++_i) \
;         __builtin_amdgcn_global_load_lds((const unsigned*)((const char*)(gbase) + (voff)[_i]), (PG8_LAS unsigned*)(lds + (bufoff) + ldsw + _i * 8192), 16, 0, 0); } while (0)
; #define PG8_LDA(dst, b, h) do { _Pragma("unroll") for (int m = 0; m < 4; ++m) _Pragma("unroll") for (int k = 0; k < 2; ++k) dst[m][k] = *(const PG8_LAS bf16x8*)(lds + PG8_SA(b, h) + aoff + m * 2048 + k * 1024); } while (0)
; #define PG8_MMA(ai, bj, At, Bt) do { __builtin_amdgcn_s_setprio(1); _Pragma("unroll") for (int m = 0; m < 4; ++m) _Pragma("unroll") for (int n = 0; n < 2; ++n) _Pragma("unroll") for (int k = 0; k < 2; ++k) \
;         acc[ai][bj][m][n] = __builtin_amdgcn_mfma_f32_16x16x32_bf16(Bt[n][k], At[m][k], acc[ai][bj][m][n], 0, 0, 0); __builtin_amdgcn_s_setprio(0); } while (0)
; #define PG8_WAIT_V(n) asm volatile("s_waitcnt vmcnt(" #n ")" ::: "memory")
; #define PG8_WAIT_L(n) asm volatile("s_waitcnt lgkmcnt(" #n ")" ::: "memory")
; #define PG8_BAR __builtin_amdgcn_s_barrier()
; #define PG8_SCHED __builtin_amdgcn_sched_barrier(0)
; template <class Epi, class Sched, bool ALIGN_EPI = false, bool SP2 = false>
; __device__ __forceinline__ void gemm_phase(PG8_LAS unsigned char* lds, const Gemm g, const Sched& S, const Epi& E) {
;     ...
;             PG8_LDA(At, 1, 1); PG8_STAGE(PG8_SB(1, 0), b3, voffB); PG8_STAGE(PG8_SB(1, 1), b3 + hstep, voffB); PG8_STAGE(PG8_SA(1, 0), a3, voffA);
;             PG8_WAIT_V(8); PG8_WAIT_L(0); PG8_BAR; PG8_MMA(1, 0, At, B0); PG8_MMA(1, 1, At, B1); PG8_BAR; PG8_SCHED;
	s_add_i32 s30, s62, s33
	v_lshl_add_u64 v[210:211], v[210:211], 0, s[0:1]
	s_mov_b32 m0, s30
	ds_read_b128 v[172:175], v187 offset:49152
	ds_read_b128 v[176:179], v187 offset:50176
	ds_read_b128 v[180:183], v187 offset:51200
	ds_read_b128 v[188:191], v187 offset:52224
	ds_read_b128 v[198:201], v187 offset:53248
	ds_read_b128 v[202:205], v187 offset:54272
	ds_read_b128 v[206:209], v187 offset:55296
	ds_read_b128 v[222:225], v187 offset:56320
	global_load_lds_dwordx4 v[210:211], off
	s_add_i32 m0, s30, 0x2000
	s_add_u32 s30, s46, 0x40080
	v_lshl_add_u64 v[210:211], v[226:227], 0, s[0:1]
	s_addc_u32 s31, s47, 0
	s_add_i32 s46, s63, s33
	global_load_lds_dwordx4 v[210:211], off
	v_lshl_add_u64 v[210:211], s[30:31], 0, v[0:1]
	s_mov_b32 m0, s46
	s_nop 0
	global_load_lds_dwordx4 v[210:211], off
	v_lshl_add_u64 v[210:211], s[30:31], 0, v[154:155]
	s_add_i32 m0, s46, 0x2000
	s_nop 0
	global_load_lds_dwordx4 v[210:211], off
	v_lshl_add_u64 v[210:211], v[228:229], 0, s[0:1]
	s_mov_b32 m0, s56
	s_nop 0
	global_load_lds_dwordx4 v[210:211], off
	v_lshl_add_u64 v[210:211], v[230:231], 0, s[0:1]
	s_mov_b32 m0, s57
	s_nop 0
	global_load_lds_dwordx4 v[210:211], off
	s_waitcnt vmcnt(8)
	s_waitcnt lgkmcnt(0)
	s_barrier
	s_setprio 1
	s_waitcnt lgkmcnt(0)
	v_mfma_f32_16x16x32_bf16 v[62:65], v[114:117], v[172:175], v[62:65]
	v_mfma_f32_16x16x32_bf16 v[58:61], v[126:129], v[172:175], v[58:61]
	v_mfma_f32_16x16x32_bf16 v[46:49], v[114:117], v[180:183], v[46:49]
	v_mfma_f32_16x16x32_bf16 v[42:45], v[126:129], v[180:183], v[42:45]
	v_mfma_f32_16x16x32_bf16 v[30:33], v[114:117], v[198:201], v[30:33]
	v_mfma_f32_16x16x32_bf16 v[26:29], v[126:129], v[198:201], v[26:29]
	v_mfma_f32_16x16x32_bf16 v[14:17], v[114:117], v[206:209], v[14:17]
	v_mfma_f32_16x16x32_bf16 v[10:13], v[126:129], v[206:209], v[10:13]
	v_mfma_f32_16x16x32_bf16 v[62:65], v[118:121], v[176:179], v[62:65]
	v_mfma_f32_16x16x32_bf16 v[58:61], v[134:137], v[176:179], v[58:61]
	v_mfma_f32_16x16x32_bf16 v[46:49], v[118:121], v[188:191], v[46:49]
	v_mfma_f32_16x16x32_bf16 v[42:45], v[134:137], v[188:191], v[42:45]
	v_mfma_f32_16x16x32_bf16 v[30:33], v[118:121], v[202:205], v[30:33]
	v_mfma_f32_16x16x32_bf16 v[26:29], v[134:137], v[202:205], v[26:29]
	v_mfma_f32_16x16x32_bf16 v[14:17], v[118:121], v[222:225], v[14:17]
	v_mfma_f32_16x16x32_bf16 v[10:13], v[134:137], v[222:225], v[10:13]
	s_setprio 0
	s_setprio 1
	v_mfma_f32_16x16x32_bf16 v[54:57], v[146:149], v[172:175], v[54:57]
	v_mfma_f32_16x16x32_bf16 v[50:53], v[164:167], v[172:175], v[50:53]
	v_mfma_f32_16x16x32_bf16 v[38:41], v[146:149], v[180:183], v[38:41]
	v_mfma_f32_16x16x32_bf16 v[34:37], v[164:167], v[180:183], v[34:37]
	v_mfma_f32_16x16x32_bf16 v[22:25], v[146:149], v[198:201], v[22:25]
	v_mfma_f32_16x16x32_bf16 v[18:21], v[164:167], v[198:201], v[18:21]
	v_mfma_f32_16x16x32_bf16 v[6:9], v[146:149], v[206:209], v[6:9]
	v_mfma_f32_16x16x32_bf16 v[2:5], v[164:167], v[206:209], v[2:5]
	v_mfma_f32_16x16x32_bf16 v[54:57], v[150:153], v[176:179], v[54:57]
	v_mfma_f32_16x16x32_bf16 v[50:53], v[168:171], v[176:179], v[50:53]
	v_mfma_f32_16x16x32_bf16 v[38:41], v[150:153], v[188:191], v[38:41]
	v_mfma_f32_16x16x32_bf16 v[34:37], v[168:171], v[188:191], v[34:37]
	v_mfma_f32_16x16x32_bf16 v[22:25], v[150:153], v[202:205], v[22:25]
	v_mfma_f32_16x16x32_bf16 v[18:21], v[168:171], v[202:205], v[18:21]
	v_mfma_f32_16x16x32_bf16 v[6:9], v[150:153], v[222:225], v[6:9]
	v_mfma_f32_16x16x32_bf16 v[2:5], v[168:171], v[222:225], v[2:5]
	s_setprio 0
	s_barrier
	s_add_i32 s61, s61, 2
	s_add_u32 s44, s44, 0x100
	s_addc_u32 s45, s45, 0
	s_add_u32 s59, s59, 0x100
	s_addc_u32 s60, s60, 0
	s_cmp_gt_u32 s61, 13
	s_cbranch_scc0 .LBB0_676

; #define PG8_STAGE(bufoff, gbase, voff) do { _Pragma("unroll") for (int _i = 0; _i < 2; ++_i) \
;         __builtin_amdgcn_global_load_lds((const unsigned*)((const char*)(gbase) + (voff)[_i]), (PG8_LAS unsigned*)(lds + (bufoff) + ldsw + _i * 8192), 16, 0, 0); } while (0)
; #define PG8_LDA(dst, b, h) do { _Pragma("unroll") for (int m = 0; m < 4; ++m) _Pragma("unroll") for (int k = 0; k < 2; ++k) dst[m][k] = *(const PG8_LAS bf16x8*)(lds + PG8_SA(b, h) + aoff + m * 2048 + k * 1024); } while (0)
; #define PG8_LDB(dst, b, h) do { _Pragma("unroll") for (int n = 0; n < 2; ++n) _Pragma("unroll") for (int k = 0; k < 2; ++k) dst[n][k] = *(const PG8_LAS bf16x8*)(lds + PG8_SB(b, h) + boff + n * 2048 + k * 1024); } while (0)
; #define PG8_MMA(ai, bj, At, Bt) do { __builtin_amdgcn_s_setprio(1); _Pragma("unroll") for (int m = 0; m < 4; ++m) _Pragma("unroll") for (int n = 0; n < 2; ++n) _Pragma("unroll") for (int k = 0; k < 2; ++k) \
;         acc[ai][bj][m][n] = __builtin_amdgcn_mfma_f32_16x16x32_bf16(Bt[n][k], At[m][k], acc[ai][bj][m][n], 0, 0, 0); __builtin_amdgcn_s_setprio(0); } while (0)
; #define PG8_WAIT_V(n) asm volatile("s_waitcnt vmcnt(" #n ")" ::: "memory")
; #define PG8_WAIT_L(n) asm volatile("s_waitcnt lgkmcnt(" #n ")" ::: "memory")
; template <class Epi, class Sched, bool ALIGN_EPI = false, bool SP2 = false>
; __device__ __forceinline__ void gemm_phase(PG8_LAS unsigned char* lds, const Gemm g, const Sched& S, const Epi& E) {
;     ...
;             const bool last = (t == nt - 2);
;             const char* a1 = cA + (size_t)(t + 1) * kstep;
;             const char* a2 = last ? nA : cA + (size_t)(t + 2) * kstep; const char* b2 = last ? nB : cB + (size_t)(t + 2) * kstep;
;             const char* a3 = a2 + kstep; const char* b3 = b2 + kstep;
;             if (last && has_next) S.a_ready(nxt);
;             if constexpr (SP2) {
;             PG8_LDB(B0, 0, 0); PG8_LDB(B1, 0, 1); PG8_SCHED; PG8_LDA(At, 0, 0); PG8_STAGE(PG8_SA(1, 1), a1 + hstep, voffA);
;             PG8_WAIT_V(8); PG8_WAIT_L(0); PG8_BAR; PG8_MMA(0, 0, At, B0); PG8_MMA(0, 1, At, B1); PG8_BAR; PG8_SCHED;
;             PG8_LDA(At, 0, 1); PG8_STAGE(PG8_SB(0, 0), b2, voffB); PG8_STAGE(PG8_SB(0, 1), b2 + hstep, voffB); PG8_STAGE(PG8_SA(0, 0), a2, voffA);
;             PG8_WAIT_V(8); PG8_WAIT_L(0); PG8_BAR; PG8_MMA(1, 0, At, B0); PG8_MMA(1, 1, At, B1); PG8_BAR; PG8_SCHED;
.Lpeel_p4:
	s_add_u32 s30, s46, 0xfffc0080
	s_addc_u32 s31, s47, -1
	s_add_i32 s65, 0, 0x10000
	s_cmp_eq_u32 s64, 12
	s_cselect_b32 s51, s15, s31
	s_cselect_b32 s50, s60, s30
	v_add_u32_e32 v152, s65, v157
	s_cselect_b32 s49, s11, s63
	s_cselect_b32 s48, s61, s62
	s_add_i32 s66, 0, 0x14000
	ds_read_b128 v[50:53], v152
	ds_read_b128 v[54:57], v152 offset:1024
	ds_read_b128 v[162:165], v152 offset:2048
	ds_read_b128 v[166:169], v152 offset:3072
	v_add_u32_e32 v152, s66, v157
	ds_read_b128 v[170:173], v152
	ds_read_b128 v[174:177], v152 offset:1024
	ds_read_b128 v[178:181], v152 offset:2048
	ds_read_b128 v[182:185], v152 offset:3072
	v_lshl_add_u64 v[152:153], s[46:47], 0, v[148:149]
	s_add_i32 m0, s52, 0xc000
	ds_read_b128 v[186:189], v160
	ds_read_b128 v[198:201], v160 offset:1024
	ds_read_b128 v[202:205], v160 offset:2048
	ds_read_b128 v[206:209], v160 offset:3072
	ds_read_b128 v[222:225], v160 offset:4096
	ds_read_b128 v[226:229], v160 offset:5120
	ds_read_b128 v[230:233], v160 offset:6144
	ds_read_b128 v[234:237], v160 offset:7168
	global_load_lds_dwordx4 v[152:153], off
	v_lshl_add_u64 v[152:153], s[46:47], 0, v[150:151]
	s_add_i32 m0, s52, 0xe000
	s_nop 0
	global_load_lds_dwordx4 v[152:153], off
	s_waitcnt vmcnt(8)
	s_waitcnt lgkmcnt(0)
	s_barrier
	s_nop 0
	s_setprio 1
	s_waitcnt lgkmcnt(0)
	v_mfma_f32_16x16x32_bf16 v[134:137], v[50:53], v[186:189], 0
	v_mfma_f32_16x16x32_bf16 v[126:129], v[162:165], v[186:189], 0
	v_mfma_f32_16x16x32_bf16 v[118:121], v[50:53], v[202:205], 0
	v_mfma_f32_16x16x32_bf16 v[110:113], v[162:165], v[202:205], 0
	v_mfma_f32_16x16x32_bf16 v[102:105], v[50:53], v[222:225], 0
	v_mfma_f32_16x16x32_bf16 v[94:97], v[162:165], v[222:225], 0
	v_mfma_f32_16x16x32_bf16 v[86:89], v[50:53], v[230:233], 0
	v_mfma_f32_16x16x32_bf16 v[78:81], v[162:165], v[230:233], 0
	v_mfma_f32_16x16x32_bf16 v[134:137], v[54:57], v[198:201], v[134:137]
	v_mfma_f32_16x16x32_bf16 v[126:129], v[166:169], v[198:201], v[126:129]
	v_mfma_f32_16x16x32_bf16 v[118:121], v[54:57], v[206:209], v[118:121]
	v_mfma_f32_16x16x32_bf16 v[110:113], v[166:169], v[206:209], v[110:113]
	v_mfma_f32_16x16x32_bf16 v[102:105], v[54:57], v[226:229], v[102:105]
	v_mfma_f32_16x16x32_bf16 v[94:97], v[166:169], v[226:229], v[94:97]
	v_mfma_f32_16x16x32_bf16 v[86:89], v[54:57], v[234:237], v[86:89]
	v_mfma_f32_16x16x32_bf16 v[78:81], v[166:169], v[234:237], v[78:81]
	s_setprio 0
	s_setprio 1
	v_mfma_f32_16x16x32_bf16 v[130:133], v[170:173], v[186:189], 0
	v_mfma_f32_16x16x32_bf16 v[122:125], v[178:181], v[186:189], 0
	v_mfma_f32_16x16x32_bf16 v[114:117], v[170:173], v[202:205], 0
	v_mfma_f32_16x16x32_bf16 v[106:109], v[178:181], v[202:205], 0
	v_mfma_f32_16x16x32_bf16 v[98:101], v[170:173], v[222:225], 0
	v_mfma_f32_16x16x32_bf16 v[90:93], v[178:181], v[222:225], 0
	v_mfma_f32_16x16x32_bf16 v[82:85], v[170:173], v[230:233], 0
	v_mfma_f32_16x16x32_bf16 v[74:77], v[178:181], v[230:233], 0
	v_mfma_f32_16x16x32_bf16 v[130:133], v[174:177], v[198:201], v[130:133]
	v_mfma_f32_16x16x32_bf16 v[122:125], v[182:185], v[198:201], v[122:125]
	v_mfma_f32_16x16x32_bf16 v[114:117], v[174:177], v[206:209], v[114:117]
	v_mfma_f32_16x16x32_bf16 v[106:109], v[182:185], v[206:209], v[106:109]
	v_mfma_f32_16x16x32_bf16 v[98:101], v[174:177], v[226:229], v[98:101]
	v_mfma_f32_16x16x32_bf16 v[90:93], v[182:185], v[226:229], v[90:93]
	v_mfma_f32_16x16x32_bf16 v[82:85], v[174:177], v[234:237], v[82:85]
	v_mfma_f32_16x16x32_bf16 v[74:77], v[182:185], v[234:237], v[74:77]
	s_setprio 0
	s_barrier
	s_add_i32 s30, s65, s33
	v_lshl_add_u64 v[152:153], s[48:49], 0, v[140:141]
	s_mov_b32 m0, s30
	ds_read_b128 v[186:189], v160 offset:16384
	ds_read_b128 v[198:201], v160 offset:17408
	ds_read_b128 v[202:205], v160 offset:18432
	ds_read_b128 v[206:209], v160 offset:19456
	ds_read_b128 v[222:225], v160 offset:20480
	ds_read_b128 v[226:229], v160 offset:21504
	ds_read_b128 v[230:233], v160 offset:22528
	ds_read_b128 v[234:237], v160 offset:23552
	global_load_lds_dwordx4 v[152:153], off
	s_add_i32 m0, s30, 0x2000
	s_add_u32 s30, s48, 0x40000
	v_lshl_add_u64 v[190:191], s[48:49], 0, v[144:145]
	s_addc_u32 s31, s49, 0
	s_add_i32 s65, s66, s33
	global_load_lds_dwordx4 v[190:191], off
	v_lshl_add_u64 v[210:211], s[30:31], 0, v[140:141]
	s_mov_b32 m0, s65
	v_lshl_add_u64 v[238:239], s[50:51], 0, v[142:143]
	global_load_lds_dwordx4 v[210:211], off
	v_lshl_add_u64 v[210:211], s[30:31], 0, v[144:145]
	s_add_i32 m0, s65, 0x2000
	s_nop 0
	global_load_lds_dwordx4 v[210:211], off
	v_lshl_add_u64 v[210:211], s[50:51], 0, v[138:139]
	s_mov_b32 m0, s52
	s_nop 0
	global_load_lds_dwordx4 v[210:211], off
	s_mov_b32 m0, s53
	s_nop 0
	global_load_lds_dwordx4 v[238:239], off
	s_waitcnt vmcnt(8)
	s_waitcnt lgkmcnt(0)
	s_barrier
; #define PG8_STAGE(bufoff, gbase, voff) do { _Pragma("unroll") for (int _i = 0; _i < 2; ++_i) \
;         __builtin_amdgcn_global_load_lds((const unsigned*)((const char*)(gbase) + (voff)[_i]), (PG8_LAS unsigned*)(lds + (bufoff) + ldsw + _i * 8192), 16, 0, 0); } while (0)
; #define PG8_LDA(dst, b, h) do { _Pragma("unroll") for (int m = 0; m < 4; ++m) _Pragma("unroll") for (int k = 0; k < 2; ++k) dst[m][k] = *(const PG8_LAS bf16x8*)(lds + PG8_SA(b, h) + aoff + m * 2048 + k * 1024); } while (0)
; #define PG8_LDB(dst, b, h) do { _Pragma("unroll") for (int n = 0; n < 2; ++n) _Pragma("unroll") for (int k = 0; k < 2; ++k) dst[n][k] = *(const PG8_LAS bf16x8*)(lds + PG8_SB(b, h) + boff + n * 2048 + k * 1024); } while (0)
; #define PG8_MMA(ai, bj, At, Bt) do { __builtin_amdgcn_s_setprio(1); _Pragma("unroll") for (int m = 0; m < 4; ++m) _Pragma("unroll") for (int n = 0; n < 2; ++n) _Pragma("unroll") for (int k = 0; k < 2; ++k) \
;         acc[ai][bj][m][n] = __builtin_amdgcn_mfma_f32_16x16x32_bf16(Bt[n][k], At[m][k], acc[ai][bj][m][n], 0, 0, 0); __builtin_amdgcn_s_setprio(0); } while (0)
; #define PG8_WAIT_V(n) asm volatile("s_waitcnt vmcnt(" #n ")" ::: "memory")
; #define PG8_WAIT_L(n) asm volatile("s_waitcnt lgkmcnt(" #n ")" ::: "memory")
; #define PG8_BAR __builtin_amdgcn_s_barrier()
; #define PG8_SCHED __builtin_amdgcn_sched_barrier(0)
; template <class Epi, class Sched, bool ALIGN_EPI = false, bool SP2 = false>
; __device__ __forceinline__ void gemm_phase(PG8_LAS unsigned char* lds, const Gemm g, const Sched& S, const Epi& E) {
;     ...
;             PG8_WAIT_V(8); PG8_WAIT_L(0); PG8_BAR; PG8_MMA(1, 0, At, B0); PG8_MMA(1, 1, At, B1); PG8_BAR; PG8_SCHED;
;             PG8_LDB(B0, 1, 0); PG8_LDB(B1, 1, 1); PG8_SCHED; PG8_LDA(At, 1, 0); PG8_STAGE(PG8_SA(0, 1), a2 + hstep, voffA);
;             PG8_WAIT_V(8); PG8_WAIT_L(0); PG8_BAR; PG8_MMA(0, 0, At, B0); PG8_MMA(0, 1, At, B1); PG8_BAR; PG8_SCHED;
	s_nop 0
	s_setprio 1
	s_waitcnt lgkmcnt(0)
	v_mfma_f32_16x16x32_bf16 v[70:73], v[50:53], v[186:189], 0
	v_mfma_f32_16x16x32_bf16 v[62:65], v[162:165], v[186:189], 0
	v_mfma_f32_16x16x32_bf16 v[46:49], v[50:53], v[202:205], 0
	v_mfma_f32_16x16x32_bf16 v[38:41], v[162:165], v[202:205], 0
	v_mfma_f32_16x16x32_bf16 v[30:33], v[50:53], v[222:225], 0
	v_mfma_f32_16x16x32_bf16 v[22:25], v[162:165], v[222:225], 0
	v_mfma_f32_16x16x32_bf16 v[14:17], v[50:53], v[230:233], 0
	v_mfma_f32_16x16x32_bf16 v[6:9], v[162:165], v[230:233], 0
	v_mfma_f32_16x16x32_bf16 v[70:73], v[54:57], v[198:201], v[70:73]
	v_mfma_f32_16x16x32_bf16 v[62:65], v[166:169], v[198:201], v[62:65]
	v_mfma_f32_16x16x32_bf16 v[46:49], v[54:57], v[206:209], v[46:49]
	v_mfma_f32_16x16x32_bf16 v[38:41], v[166:169], v[206:209], v[38:41]
	v_mfma_f32_16x16x32_bf16 v[30:33], v[54:57], v[226:229], v[30:33]
	v_mfma_f32_16x16x32_bf16 v[22:25], v[166:169], v[226:229], v[22:25]
	v_mfma_f32_16x16x32_bf16 v[14:17], v[54:57], v[234:237], v[14:17]
	v_mfma_f32_16x16x32_bf16 v[6:9], v[166:169], v[234:237], v[6:9]
	s_setprio 0
	s_setprio 1
	v_mfma_f32_16x16x32_bf16 v[42:45], v[170:173], v[202:205], 0
	v_mfma_f32_16x16x32_bf16 v[34:37], v[178:181], v[202:205], 0
	v_mfma_f32_16x16x32_bf16 v[26:29], v[170:173], v[222:225], 0
	v_mfma_f32_16x16x32_bf16 v[18:21], v[178:181], v[222:225], 0
	v_mfma_f32_16x16x32_bf16 v[10:13], v[170:173], v[230:233], 0
	v_mfma_f32_16x16x32_bf16 v[2:5], v[178:181], v[230:233], 0
	v_mfma_f32_16x16x32_bf16 v[50:53], v[170:173], v[186:189], 0
	v_mfma_f32_16x16x32_bf16 v[54:57], v[178:181], v[186:189], 0
	v_mfma_f32_16x16x32_bf16 v[42:45], v[174:177], v[206:209], v[42:45]
	v_mfma_f32_16x16x32_bf16 v[34:37], v[182:185], v[206:209], v[34:37]
	v_mfma_f32_16x16x32_bf16 v[26:29], v[174:177], v[226:229], v[26:29]
	v_mfma_f32_16x16x32_bf16 v[18:21], v[182:185], v[226:229], v[18:21]
	v_mfma_f32_16x16x32_bf16 v[10:13], v[174:177], v[234:237], v[10:13]
	v_mfma_f32_16x16x32_bf16 v[2:5], v[182:185], v[234:237], v[2:5]
	v_mfma_f32_16x16x32_bf16 v[50:53], v[174:177], v[198:201], v[50:53]
	v_mfma_f32_16x16x32_bf16 v[54:57], v[182:185], v[198:201], v[54:57]
	s_setprio 0
	s_barrier
	s_add_i32 s65, 0, 0x18000
	v_add_u32_e32 v161, s65, v157
	s_add_i32 s66, 0, 0x1c000
	ds_read_b128 v[58:61], v161
	ds_read_b128 v[66:69], v161 offset:1024
	ds_read_b128 v[162:165], v161 offset:2048
	ds_read_b128 v[166:169], v161 offset:3072
	v_add_u32_e32 v161, s66, v157
	ds_read_b128 v[170:173], v161
	ds_read_b128 v[174:177], v161 offset:1024
	ds_read_b128 v[178:181], v161 offset:2048
	ds_read_b128 v[182:185], v161 offset:3072
	s_add_u32 s30, s50, 0x40000
	s_addc_u32 s31, s51, 0
	s_mov_b32 m0, s54
	v_lshl_add_u64 v[240:241], s[30:31], 0, v[138:139]
	ds_read_b128 v[186:189], v160 offset:32768
	ds_read_b128 v[198:201], v160 offset:33792
	ds_read_b128 v[202:205], v160 offset:34816
	ds_read_b128 v[206:209], v160 offset:35840
	ds_read_b128 v[222:225], v160 offset:36864
	ds_read_b128 v[226:229], v160 offset:37888
	ds_read_b128 v[230:233], v160 offset:38912
	ds_read_b128 v[234:237], v160 offset:39936
	global_load_lds_dwordx4 v[240:241], off
	v_lshl_add_u64 v[240:241], s[30:31], 0, v[142:143]
	s_mov_b32 m0, s55
	s_nop 0
	global_load_lds_dwordx4 v[240:241], off
	s_waitcnt vmcnt(8)
	s_waitcnt lgkmcnt(0)
	s_barrier
	s_nop 0
	s_setprio 1
	s_waitcnt lgkmcnt(0)
	v_mfma_f32_16x16x32_bf16 v[134:137], v[58:61], v[186:189], v[134:137]
	v_mfma_f32_16x16x32_bf16 v[126:129], v[162:165], v[186:189], v[126:129]
	v_mfma_f32_16x16x32_bf16 v[118:121], v[58:61], v[202:205], v[118:121]
	v_mfma_f32_16x16x32_bf16 v[110:113], v[162:165], v[202:205], v[110:113]
	v_mfma_f32_16x16x32_bf16 v[102:105], v[58:61], v[222:225], v[102:105]
	v_mfma_f32_16x16x32_bf16 v[94:97], v[162:165], v[222:225], v[94:97]
	v_mfma_f32_16x16x32_bf16 v[86:89], v[58:61], v[230:233], v[86:89]
	v_mfma_f32_16x16x32_bf16 v[78:81], v[162:165], v[230:233], v[78:81]
	v_mfma_f32_16x16x32_bf16 v[134:137], v[66:69], v[198:201], v[134:137]
	v_mfma_f32_16x16x32_bf16 v[126:129], v[166:169], v[198:201], v[126:129]
	v_mfma_f32_16x16x32_bf16 v[118:121], v[66:69], v[206:209], v[118:121]
	v_mfma_f32_16x16x32_bf16 v[110:113], v[166:169], v[206:209], v[110:113]
	v_mfma_f32_16x16x32_bf16 v[102:105], v[66:69], v[226:229], v[102:105]
	v_mfma_f32_16x16x32_bf16 v[94:97], v[166:169], v[226:229], v[94:97]
	v_mfma_f32_16x16x32_bf16 v[86:89], v[66:69], v[234:237], v[86:89]
	v_mfma_f32_16x16x32_bf16 v[78:81], v[166:169], v[234:237], v[78:81]
	s_setprio 0
	s_setprio 1
	v_mfma_f32_16x16x32_bf16 v[130:133], v[170:173], v[186:189], v[130:133]
	v_mfma_f32_16x16x32_bf16 v[122:125], v[178:181], v[186:189], v[122:125]
	v_mfma_f32_16x16x32_bf16 v[114:117], v[170:173], v[202:205], v[114:117]
	v_mfma_f32_16x16x32_bf16 v[106:109], v[178:181], v[202:205], v[106:109]
	v_mfma_f32_16x16x32_bf16 v[98:101], v[170:173], v[222:225], v[98:101]
	v_mfma_f32_16x16x32_bf16 v[90:93], v[178:181], v[222:225], v[90:93]
	v_mfma_f32_16x16x32_bf16 v[82:85], v[170:173], v[230:233], v[82:85]
	v_mfma_f32_16x16x32_bf16 v[74:77], v[178:181], v[230:233], v[74:77]
	v_mfma_f32_16x16x32_bf16 v[130:133], v[174:177], v[198:201], v[130:133]
	v_mfma_f32_16x16x32_bf16 v[122:125], v[182:185], v[198:201], v[122:125]
	v_mfma_f32_16x16x32_bf16 v[114:117], v[174:177], v[206:209], v[114:117]
	v_mfma_f32_16x16x32_bf16 v[106:109], v[182:185], v[206:209], v[106:109]
	v_mfma_f32_16x16x32_bf16 v[98:101], v[174:177], v[226:229], v[98:101]
	v_mfma_f32_16x16x32_bf16 v[90:93], v[182:185], v[226:229], v[90:93]
	v_mfma_f32_16x16x32_bf16 v[82:85], v[174:177], v[234:237], v[82:85]
	v_mfma_f32_16x16x32_bf16 v[74:77], v[182:185], v[234:237], v[74:77]
	s_setprio 0
	s_barrier
; #define PG8_STAGE(bufoff, gbase, voff) do { _Pragma("unroll") for (int _i = 0; _i < 2; ++_i) \
;         __builtin_amdgcn_global_load_lds((const unsigned*)((const char*)(gbase) + (voff)[_i]), (PG8_LAS unsigned*)(lds + (bufoff) + ldsw + _i * 8192), 16, 0, 0); } while (0)
; #define PG8_LDA(dst, b, h) do { _Pragma("unroll") for (int m = 0; m < 4; ++m) _Pragma("unroll") for (int k = 0; k < 2; ++k) dst[m][k] = *(const PG8_LAS bf16x8*)(lds + PG8_SA(b, h) + aoff + m * 2048 + k * 1024); } while (0)
; #define PG8_LDB(dst, b, h) do { _Pragma("unroll") for (int n = 0; n < 2; ++n) _Pragma("unroll") for (int k = 0; k < 2; ++k) dst[n][k] = *(const PG8_LAS bf16x8*)(lds + PG8_SB(b, h) + boff + n * 2048 + k * 1024); } while (0)
; #define PG8_MMA(ai, bj, At, Bt) do { __builtin_amdgcn_s_setprio(1); _Pragma("unroll") for (int m = 0; m < 4; ++m) _Pragma("unroll") for (int n = 0; n < 2; ++n) _Pragma("unroll") for (int k = 0; k < 2; ++k) \
;         acc[ai][bj][m][n] = __builtin_amdgcn_mfma_f32_16x16x32_bf16(Bt[n][k], At[m][k], acc[ai][bj][m][n], 0, 0, 0); __builtin_amdgcn_s_setprio(0); } while (0)
; #define PG8_WAIT_V(n) asm volatile("s_waitcnt vmcnt(" #n ")" ::: "memory")
; template <class Epi, class Sched, bool ALIGN_EPI = false, bool SP2 = false>
; __device__ __forceinline__ void gemm_phase(PG8_LAS unsigned char* lds, const Gemm g, const Sched& S, const Epi& E) {
;     ...
;             PG8_LDB(B0, 0, 0); PG8_LDB(B1, 0, 1); PG8_SCHED; PG8_LDA(At, 0, 0); PG8_STAGE(PG8_SA(1, 1), a1 + hstep, voffA);
;             PG8_WAIT_V(8); PG8_WAIT_L(0); PG8_BAR; PG8_MMA(0, 0, At, B0); PG8_MMA(0, 1, At, B1); PG8_BAR; PG8_SCHED;
;             PG8_LDA(At, 0, 1); PG8_STAGE(PG8_SB(0, 0), b2, voffB); PG8_STAGE(PG8_SB(0, 1), b2 + hstep, voffB); PG8_STAGE(PG8_SA(0, 0), a2, voffA);
;             PG8_WAIT_V(8); PG8_WAIT_L(0); PG8_BAR; PG8_MMA(1, 0, At, B0); PG8_MMA(1, 1, At, B1); PG8_BAR; PG8_SCHED;
;             PG8_LDB(B0, 1, 0); PG8_LDB(B1, 1, 1); PG8_SCHED; PG8_LDA(At, 1, 0); PG8_STAGE(PG8_SA(0, 1), a2 + hstep, voffA);
;             PG8_WAIT_V(8); PG8_WAIT_L(0); PG8_BAR; PG8_MMA(0, 0, At, B0); PG8_MMA(0, 1, At, B1); PG8_BAR; PG8_SCHED;
;             PG8_LDA(At, 1, 1); PG8_STAGE(PG8_SB(1, 0), b3, voffB); PG8_STAGE(PG8_SB(1, 1), b3 + hstep, voffB); PG8_STAGE(PG8_SA(1, 0), a3, voffA);
;             PG8_WAIT_V(8); PG8_WAIT_L(0); PG8_BAR; PG8_MMA(1, 0, At, B0); PG8_MMA(1, 1, At, B1); PG8_BAR; PG8_SCHED;
	s_add_i32 s30, s65, s33
	v_lshl_add_u64 v[152:153], v[152:153], 0, s[0:1]
	s_mov_b32 m0, s30
	ds_read_b128 v[186:189], v160 offset:49152
	ds_read_b128 v[198:201], v160 offset:50176
	ds_read_b128 v[202:205], v160 offset:51200
	ds_read_b128 v[206:209], v160 offset:52224
	ds_read_b128 v[222:225], v160 offset:53248
	ds_read_b128 v[226:229], v160 offset:54272
	ds_read_b128 v[230:233], v160 offset:55296
	ds_read_b128 v[234:237], v160 offset:56320
	global_load_lds_dwordx4 v[152:153], off
	s_add_i32 m0, s30, 0x2000
	s_add_u32 s30, s48, 0x40080
	v_lshl_add_u64 v[152:153], v[190:191], 0, s[0:1]
	s_addc_u32 s31, s49, 0
	s_add_i32 s48, s66, s33
	global_load_lds_dwordx4 v[152:153], off
	v_lshl_add_u64 v[152:153], s[30:31], 0, v[140:141]
	s_mov_b32 m0, s48
	s_nop 0
	global_load_lds_dwordx4 v[152:153], off
	v_lshl_add_u64 v[152:153], s[30:31], 0, v[144:145]
	s_add_i32 m0, s48, 0x2000
	s_nop 0
	global_load_lds_dwordx4 v[152:153], off
	v_lshl_add_u64 v[152:153], v[210:211], 0, s[0:1]
	s_mov_b32 m0, s56
	s_nop 0
	global_load_lds_dwordx4 v[152:153], off
	v_lshl_add_u64 v[152:153], v[238:239], 0, s[0:1]
	s_mov_b32 m0, s57
	s_nop 0
	global_load_lds_dwordx4 v[152:153], off
	s_waitcnt vmcnt(8)
	s_waitcnt lgkmcnt(0)
	s_barrier
	s_setprio 1
	s_waitcnt lgkmcnt(0)
	v_mfma_f32_16x16x32_bf16 v[70:73], v[58:61], v[186:189], v[70:73]
	v_mfma_f32_16x16x32_bf16 v[62:65], v[162:165], v[186:189], v[62:65]
	v_mfma_f32_16x16x32_bf16 v[46:49], v[58:61], v[202:205], v[46:49]
	v_mfma_f32_16x16x32_bf16 v[38:41], v[162:165], v[202:205], v[38:41]
	v_mfma_f32_16x16x32_bf16 v[30:33], v[58:61], v[222:225], v[30:33]
	v_mfma_f32_16x16x32_bf16 v[22:25], v[162:165], v[222:225], v[22:25]
	v_mfma_f32_16x16x32_bf16 v[14:17], v[58:61], v[230:233], v[14:17]
	v_mfma_f32_16x16x32_bf16 v[6:9], v[162:165], v[230:233], v[6:9]
	v_mfma_f32_16x16x32_bf16 v[70:73], v[66:69], v[198:201], v[70:73]
	v_mfma_f32_16x16x32_bf16 v[62:65], v[166:169], v[198:201], v[62:65]
	v_mfma_f32_16x16x32_bf16 v[46:49], v[66:69], v[206:209], v[46:49]
	v_mfma_f32_16x16x32_bf16 v[38:41], v[166:169], v[206:209], v[38:41]
	v_mfma_f32_16x16x32_bf16 v[30:33], v[66:69], v[226:229], v[30:33]
	v_mfma_f32_16x16x32_bf16 v[22:25], v[166:169], v[226:229], v[22:25]
	v_mfma_f32_16x16x32_bf16 v[14:17], v[66:69], v[234:237], v[14:17]
	v_mfma_f32_16x16x32_bf16 v[6:9], v[166:169], v[234:237], v[6:9]
	s_setprio 0
	s_setprio 1
	v_mfma_f32_16x16x32_bf16 v[50:53], v[170:173], v[186:189], v[50:53]
	v_mfma_f32_16x16x32_bf16 v[66:69], v[174:177], v[198:201], v[50:53]
	v_mfma_f32_16x16x32_bf16 v[50:53], v[178:181], v[186:189], v[54:57]
	v_mfma_f32_16x16x32_bf16 v[42:45], v[170:173], v[202:205], v[42:45]
	v_mfma_f32_16x16x32_bf16 v[34:37], v[178:181], v[202:205], v[34:37]
	v_mfma_f32_16x16x32_bf16 v[26:29], v[170:173], v[222:225], v[26:29]
	v_mfma_f32_16x16x32_bf16 v[18:21], v[178:181], v[222:225], v[18:21]
	v_mfma_f32_16x16x32_bf16 v[10:13], v[170:173], v[230:233], v[10:13]
	v_mfma_f32_16x16x32_bf16 v[2:5], v[178:181], v[230:233], v[2:5]
	v_mfma_f32_16x16x32_bf16 v[58:61], v[182:185], v[198:201], v[50:53]
	v_mfma_f32_16x16x32_bf16 v[42:45], v[174:177], v[206:209], v[42:45]
	v_mfma_f32_16x16x32_bf16 v[34:37], v[182:185], v[206:209], v[34:37]
	v_mfma_f32_16x16x32_bf16 v[26:29], v[174:177], v[226:229], v[26:29]
	v_mfma_f32_16x16x32_bf16 v[18:21], v[182:185], v[226:229], v[18:21]
	v_mfma_f32_16x16x32_bf16 v[10:13], v[174:177], v[234:237], v[10:13]
	v_mfma_f32_16x16x32_bf16 v[2:5], v[182:185], v[234:237], v[2:5]
	s_setprio 0
	s_barrier
	s_add_i32 s64, s64, 2
	s_add_u32 s46, s46, 0x100
	s_addc_u32 s47, s47, 0
	s_add_u32 s62, s62, 0x100
	s_addc_u32 s63, s63, 0
	s_cmp_gt_u32 s64, 13
	s_cbranch_scc0 .LBB0_781
	s_branch .Lpeel_exit_p4
.LBB0_781:
	s_add_u32 s30, s46, 0xfffc0080
	s_addc_u32 s31, s47, -1
	s_add_i32 s65, 0, 0x10000
	s_cmp_eq_u32 s64, 12
	s_cselect_b32 s51, s15, s31
	s_cselect_b32 s50, s60, s30
	v_add_u32_e32 v152, s65, v157
	s_cselect_b32 s49, s11, s63
	s_cselect_b32 s48, s61, s62
	s_add_i32 s66, 0, 0x14000
	ds_read_b128 v[50:53], v152
	ds_read_b128 v[54:57], v152 offset:1024
	ds_read_b128 v[162:165], v152 offset:2048
	ds_read_b128 v[166:169], v152 offset:3072
	v_add_u32_e32 v152, s66, v157
	ds_read_b128 v[170:173], v152
	ds_read_b128 v[174:177], v152 offset:1024
	ds_read_b128 v[178:181], v152 offset:2048
	ds_read_b128 v[182:185], v152 offset:3072
	v_lshl_add_u64 v[152:153], s[46:47], 0, v[148:149]
	s_add_i32 m0, s52, 0xc000
	ds_read_b128 v[186:189], v160
	ds_read_b128 v[198:201], v160 offset:1024
	ds_read_b128 v[202:205], v160 offset:2048
	ds_read_b128 v[206:209], v160 offset:3072
	ds_read_b128 v[222:225], v160 offset:4096
	ds_read_b128 v[226:229], v160 offset:5120
	ds_read_b128 v[230:233], v160 offset:6144
	ds_read_b128 v[234:237], v160 offset:7168
	global_load_lds_dwordx4 v[152:153], off
	v_lshl_add_u64 v[152:153], s[46:47], 0, v[150:151]
	s_add_i32 m0, s52, 0xe000
	s_nop 0
	global_load_lds_dwordx4 v[152:153], off
	s_waitcnt vmcnt(8)
	s_waitcnt lgkmcnt(0)
	s_barrier
; #define PG8_STAGE(bufoff, gbase, voff) do { _Pragma("unroll") for (int _i = 0; _i < 2; ++_i) \
;         __builtin_amdgcn_global_load_lds((const unsigned*)((const char*)(gbase) + (voff)[_i]), (PG8_LAS unsigned*)(lds + (bufoff) + ldsw + _i * 8192), 16, 0, 0); } while (0)
; #define PG8_LDA(dst, b, h) do { _Pragma("unroll") for (int m = 0; m < 4; ++m) _Pragma("unroll") for (int k = 0; k < 2; ++k) dst[m][k] = *(const PG8_LAS bf16x8*)(lds + PG8_SA(b, h) + aoff + m * 2048 + k * 1024); } while (0)
; #define PG8_MMA(ai, bj, At, Bt) do { __builtin_amdgcn_s_setprio(1); _Pragma("unroll") for (int m = 0; m < 4; ++m) _Pragma("unroll") for (int n = 0; n < 2; ++n) _Pragma("unroll") for (int k = 0; k < 2; ++k) \
;         acc[ai][bj][m][n] = __builtin_amdgcn_mfma_f32_16x16x32_bf16(Bt[n][k], At[m][k], acc[ai][bj][m][n], 0, 0, 0); __builtin_amdgcn_s_setprio(0); } while (0)
; #define PG8_WAIT_V(n) asm volatile("s_waitcnt vmcnt(" #n ")" ::: "memory")
; #define PG8_WAIT_L(n) asm volatile("s_waitcnt lgkmcnt(" #n ")" ::: "memory")
; #define PG8_BAR __builtin_amdgcn_s_barrier()
; #define PG8_SCHED __builtin_amdgcn_sched_barrier(0)
; template <class Epi, class Sched, bool ALIGN_EPI = false, bool SP2 = false>
; __device__ __forceinline__ void gemm_phase(PG8_LAS unsigned char* lds, const Gemm g, const Sched& S, const Epi& E) {
;     ...
;             PG8_WAIT_V(8); PG8_WAIT_L(0); PG8_BAR; PG8_MMA(0, 0, At, B0); PG8_MMA(0, 1, At, B1); PG8_BAR; PG8_SCHED;
;             PG8_LDA(At, 0, 1); PG8_STAGE(PG8_SB(0, 0), b2, voffB); PG8_STAGE(PG8_SB(0, 1), b2 + hstep, voffB); PG8_STAGE(PG8_SA(0, 0), a2, voffA);
;             PG8_WAIT_V(8); PG8_WAIT_L(0); PG8_BAR; PG8_MMA(1, 0, At, B0); PG8_MMA(1, 1, At, B1); PG8_BAR; PG8_SCHED;
	s_setprio 1
	s_waitcnt lgkmcnt(0)
	v_mfma_f32_16x16x32_bf16 v[134:137], v[50:53], v[186:189], v[134:137]
	v_mfma_f32_16x16x32_bf16 v[126:129], v[162:165], v[186:189], v[126:129]
	v_mfma_f32_16x16x32_bf16 v[118:121], v[50:53], v[202:205], v[118:121]
	v_mfma_f32_16x16x32_bf16 v[110:113], v[162:165], v[202:205], v[110:113]
	v_mfma_f32_16x16x32_bf16 v[102:105], v[50:53], v[222:225], v[102:105]
	v_mfma_f32_16x16x32_bf16 v[94:97], v[162:165], v[222:225], v[94:97]
	v_mfma_f32_16x16x32_bf16 v[86:89], v[50:53], v[230:233], v[86:89]
	v_mfma_f32_16x16x32_bf16 v[78:81], v[162:165], v[230:233], v[78:81]
	v_mfma_f32_16x16x32_bf16 v[134:137], v[54:57], v[198:201], v[134:137]
	v_mfma_f32_16x16x32_bf16 v[126:129], v[166:169], v[198:201], v[126:129]
	v_mfma_f32_16x16x32_bf16 v[118:121], v[54:57], v[206:209], v[118:121]
	v_mfma_f32_16x16x32_bf16 v[110:113], v[166:169], v[206:209], v[110:113]
	v_mfma_f32_16x16x32_bf16 v[102:105], v[54:57], v[226:229], v[102:105]
	v_mfma_f32_16x16x32_bf16 v[94:97], v[166:169], v[226:229], v[94:97]
	v_mfma_f32_16x16x32_bf16 v[86:89], v[54:57], v[234:237], v[86:89]
	v_mfma_f32_16x16x32_bf16 v[78:81], v[166:169], v[234:237], v[78:81]
	s_setprio 0
	s_setprio 1
	v_mfma_f32_16x16x32_bf16 v[130:133], v[170:173], v[186:189], v[130:133]
	v_mfma_f32_16x16x32_bf16 v[122:125], v[178:181], v[186:189], v[122:125]
	v_mfma_f32_16x16x32_bf16 v[114:117], v[170:173], v[202:205], v[114:117]
	v_mfma_f32_16x16x32_bf16 v[106:109], v[178:181], v[202:205], v[106:109]
	v_mfma_f32_16x16x32_bf16 v[98:101], v[170:173], v[222:225], v[98:101]
	v_mfma_f32_16x16x32_bf16 v[90:93], v[178:181], v[222:225], v[90:93]
	v_mfma_f32_16x16x32_bf16 v[82:85], v[170:173], v[230:233], v[82:85]
	v_mfma_f32_16x16x32_bf16 v[74:77], v[178:181], v[230:233], v[74:77]
	v_mfma_f32_16x16x32_bf16 v[130:133], v[174:177], v[198:201], v[130:133]
	v_mfma_f32_16x16x32_bf16 v[122:125], v[182:185], v[198:201], v[122:125]
	v_mfma_f32_16x16x32_bf16 v[114:117], v[174:177], v[206:209], v[114:117]
	v_mfma_f32_16x16x32_bf16 v[106:109], v[182:185], v[206:209], v[106:109]
	v_mfma_f32_16x16x32_bf16 v[98:101], v[174:177], v[226:229], v[98:101]
	v_mfma_f32_16x16x32_bf16 v[90:93], v[182:185], v[226:229], v[90:93]
	v_mfma_f32_16x16x32_bf16 v[82:85], v[174:177], v[234:237], v[82:85]
	v_mfma_f32_16x16x32_bf16 v[74:77], v[182:185], v[234:237], v[74:77]
	s_setprio 0
	s_barrier
	s_add_i32 s30, s65, s33
	v_lshl_add_u64 v[152:153], s[48:49], 0, v[140:141]
	s_mov_b32 m0, s30
	ds_read_b128 v[186:189], v160 offset:16384
	ds_read_b128 v[198:201], v160 offset:17408
	ds_read_b128 v[202:205], v160 offset:18432
	ds_read_b128 v[206:209], v160 offset:19456
	ds_read_b128 v[222:225], v160 offset:20480
	ds_read_b128 v[226:229], v160 offset:21504
	ds_read_b128 v[230:233], v160 offset:22528
	ds_read_b128 v[234:237], v160 offset:23552
	global_load_lds_dwordx4 v[152:153], off
	s_add_i32 m0, s30, 0x2000
	s_add_u32 s30, s48, 0x40000
	v_lshl_add_u64 v[190:191], s[48:49], 0, v[144:145]
	s_addc_u32 s31, s49, 0
	s_add_i32 s65, s66, s33
	global_load_lds_dwordx4 v[190:191], off
	v_lshl_add_u64 v[210:211], s[30:31], 0, v[140:141]
	s_mov_b32 m0, s65
	v_lshl_add_u64 v[238:239], s[50:51], 0, v[142:143]
	global_load_lds_dwordx4 v[210:211], off
	v_lshl_add_u64 v[210:211], s[30:31], 0, v[144:145]
	s_add_i32 m0, s65, 0x2000
	s_nop 0
	global_load_lds_dwordx4 v[210:211], off
	v_lshl_add_u64 v[210:211], s[50:51], 0, v[138:139]
	s_mov_b32 m0, s52
	s_nop 0
	global_load_lds_dwordx4 v[210:211], off
	s_mov_b32 m0, s53
	s_nop 0
	global_load_lds_dwordx4 v[238:239], off
	s_waitcnt vmcnt(8)
	s_waitcnt lgkmcnt(0)
	s_barrier
	s_nop 0
	s_setprio 1
	s_waitcnt lgkmcnt(0)
	v_mfma_f32_16x16x32_bf16 v[70:73], v[50:53], v[186:189], v[70:73]
	v_mfma_f32_16x16x32_bf16 v[62:65], v[162:165], v[186:189], v[62:65]
	v_mfma_f32_16x16x32_bf16 v[46:49], v[50:53], v[202:205], v[46:49]
	v_mfma_f32_16x16x32_bf16 v[38:41], v[162:165], v[202:205], v[38:41]
	v_mfma_f32_16x16x32_bf16 v[30:33], v[50:53], v[222:225], v[30:33]
	v_mfma_f32_16x16x32_bf16 v[22:25], v[162:165], v[222:225], v[22:25]
	v_mfma_f32_16x16x32_bf16 v[14:17], v[50:53], v[230:233], v[14:17]
	v_mfma_f32_16x16x32_bf16 v[6:9], v[162:165], v[230:233], v[6:9]
	v_mfma_f32_16x16x32_bf16 v[70:73], v[54:57], v[198:201], v[70:73]
	v_mfma_f32_16x16x32_bf16 v[62:65], v[166:169], v[198:201], v[62:65]
	v_mfma_f32_16x16x32_bf16 v[46:49], v[54:57], v[206:209], v[46:49]
	v_mfma_f32_16x16x32_bf16 v[38:41], v[166:169], v[206:209], v[38:41]
	v_mfma_f32_16x16x32_bf16 v[30:33], v[54:57], v[226:229], v[30:33]
	v_mfma_f32_16x16x32_bf16 v[22:25], v[166:169], v[226:229], v[22:25]
	v_mfma_f32_16x16x32_bf16 v[14:17], v[54:57], v[234:237], v[14:17]
	v_mfma_f32_16x16x32_bf16 v[6:9], v[166:169], v[234:237], v[6:9]
	s_setprio 0
	s_setprio 1
	v_mfma_f32_16x16x32_bf16 v[42:45], v[170:173], v[202:205], v[42:45]
	v_mfma_f32_16x16x32_bf16 v[34:37], v[178:181], v[202:205], v[34:37]
	v_mfma_f32_16x16x32_bf16 v[26:29], v[170:173], v[222:225], v[26:29]
	v_mfma_f32_16x16x32_bf16 v[18:21], v[178:181], v[222:225], v[18:21]
	v_mfma_f32_16x16x32_bf16 v[10:13], v[170:173], v[230:233], v[10:13]
	v_mfma_f32_16x16x32_bf16 v[2:5], v[178:181], v[230:233], v[2:5]
	v_mfma_f32_16x16x32_bf16 v[50:53], v[170:173], v[186:189], v[66:69]
	v_mfma_f32_16x16x32_bf16 v[54:57], v[178:181], v[186:189], v[58:61]
	v_mfma_f32_16x16x32_bf16 v[42:45], v[174:177], v[206:209], v[42:45]
	v_mfma_f32_16x16x32_bf16 v[34:37], v[182:185], v[206:209], v[34:37]
	v_mfma_f32_16x16x32_bf16 v[26:29], v[174:177], v[226:229], v[26:29]
	v_mfma_f32_16x16x32_bf16 v[18:21], v[182:185], v[226:229], v[18:21]
	v_mfma_f32_16x16x32_bf16 v[10:13], v[174:177], v[234:237], v[10:13]
	v_mfma_f32_16x16x32_bf16 v[2:5], v[182:185], v[234:237], v[2:5]
	v_mfma_f32_16x16x32_bf16 v[50:53], v[174:177], v[198:201], v[50:53]
	v_mfma_f32_16x16x32_bf16 v[54:57], v[182:185], v[198:201], v[54:57]
	s_setprio 0
	s_barrier
; #define PG8_STAGE(bufoff, gbase, voff) do { _Pragma("unroll") for (int _i = 0; _i < 2; ++_i) \
;         __builtin_amdgcn_global_load_lds((const unsigned*)((const char*)(gbase) + (voff)[_i]), (PG8_LAS unsigned*)(lds + (bufoff) + ldsw + _i * 8192), 16, 0, 0); } while (0)
; #define PG8_LDA(dst, b, h) do { _Pragma("unroll") for (int m = 0; m < 4; ++m) _Pragma("unroll") for (int k = 0; k < 2; ++k) dst[m][k] = *(const PG8_LAS bf16x8*)(lds + PG8_SA(b, h) + aoff + m * 2048 + k * 1024); } while (0)
; #define PG8_LDB(dst, b, h) do { _Pragma("unroll") for (int n = 0; n < 2; ++n) _Pragma("unroll") for (int k = 0; k < 2; ++k) dst[n][k] = *(const PG8_LAS bf16x8*)(lds + PG8_SB(b, h) + boff + n * 2048 + k * 1024); } while (0)
; #define PG8_MMA(ai, bj, At, Bt) do { __builtin_amdgcn_s_setprio(1); _Pragma("unroll") for (int m = 0; m < 4; ++m) _Pragma("unroll") for (int n = 0; n < 2; ++n) _Pragma("unroll") for (int k = 0; k < 2; ++k) \
;         acc[ai][bj][m][n] = __builtin_amdgcn_mfma_f32_16x16x32_bf16(Bt[n][k], At[m][k], acc[ai][bj][m][n], 0, 0, 0); __builtin_amdgcn_s_setprio(0); } while (0)
; #define PG8_WAIT_V(n) asm volatile("s_waitcnt vmcnt(" #n ")" ::: "memory")
; #define PG8_WAIT_L(n) asm volatile("s_waitcnt lgkmcnt(" #n ")" ::: "memory")
; #define PG8_BAR __builtin_amdgcn_s_barrier()
; #define PG8_SCHED __builtin_amdgcn_sched_barrier(0)
; template <class Epi, class Sched, bool ALIGN_EPI = false, bool SP2 = false>
; __device__ __forceinline__ void gemm_phase(PG8_LAS unsigned char* lds, const Gemm g, const Sched& S, const Epi& E) {
;     ...
;             PG8_LDB(B0, 1, 0); PG8_LDB(B1, 1, 1); PG8_SCHED; PG8_LDA(At, 1, 0); PG8_STAGE(PG8_SA(0, 1), a2 + hstep, voffA);
;             PG8_WAIT_V(8); PG8_WAIT_L(0); PG8_BAR; PG8_MMA(0, 0, At, B0); PG8_MMA(0, 1, At, B1); PG8_BAR; PG8_SCHED;
	s_add_i32 s65, 0, 0x18000
	v_add_u32_e32 v161, s65, v157
	s_add_i32 s66, 0, 0x1c000
	ds_read_b128 v[58:61], v161
	ds_read_b128 v[66:69], v161 offset:1024
	ds_read_b128 v[162:165], v161 offset:2048
	ds_read_b128 v[166:169], v161 offset:3072
	v_add_u32_e32 v161, s66, v157
	ds_read_b128 v[170:173], v161
	ds_read_b128 v[174:177], v161 offset:1024
	ds_read_b128 v[178:181], v161 offset:2048
	ds_read_b128 v[182:185], v161 offset:3072
	s_add_u32 s30, s50, 0x40000
	s_addc_u32 s31, s51, 0
	s_mov_b32 m0, s54
	v_lshl_add_u64 v[240:241], s[30:31], 0, v[138:139]
	ds_read_b128 v[186:189], v160 offset:32768
	ds_read_b128 v[198:201], v160 offset:33792
	ds_read_b128 v[202:205], v160 offset:34816
	ds_read_b128 v[206:209], v160 offset:35840
	ds_read_b128 v[222:225], v160 offset:36864
	ds_read_b128 v[226:229], v160 offset:37888
	ds_read_b128 v[230:233], v160 offset:38912
	ds_read_b128 v[234:237], v160 offset:39936
	global_load_lds_dwordx4 v[240:241], off
	v_lshl_add_u64 v[240:241], s[30:31], 0, v[142:143]
	s_mov_b32 m0, s55
	s_nop 0
	global_load_lds_dwordx4 v[240:241], off
	s_waitcnt vmcnt(8)
	s_waitcnt lgkmcnt(0)
	s_barrier
	s_nop 0
	s_setprio 1
	s_waitcnt lgkmcnt(0)
	v_mfma_f32_16x16x32_bf16 v[134:137], v[58:61], v[186:189], v[134:137]
	v_mfma_f32_16x16x32_bf16 v[126:129], v[162:165], v[186:189], v[126:129]
	v_mfma_f32_16x16x32_bf16 v[118:121], v[58:61], v[202:205], v[118:121]
	v_mfma_f32_16x16x32_bf16 v[110:113], v[162:165], v[202:205], v[110:113]
	v_mfma_f32_16x16x32_bf16 v[102:105], v[58:61], v[222:225], v[102:105]
	v_mfma_f32_16x16x32_bf16 v[94:97], v[162:165], v[222:225], v[94:97]
	v_mfma_f32_16x16x32_bf16 v[86:89], v[58:61], v[230:233], v[86:89]
	v_mfma_f32_16x16x32_bf16 v[78:81], v[162:165], v[230:233], v[78:81]
	v_mfma_f32_16x16x32_bf16 v[134:137], v[66:69], v[198:201], v[134:137]
	v_mfma_f32_16x16x32_bf16 v[126:129], v[166:169], v[198:201], v[126:129]
	v_mfma_f32_16x16x32_bf16 v[118:121], v[66:69], v[206:209], v[118:121]
	v_mfma_f32_16x16x32_bf16 v[110:113], v[166:169], v[206:209], v[110:113]
	v_mfma_f32_16x16x32_bf16 v[102:105], v[66:69], v[226:229], v[102:105]
	v_mfma_f32_16x16x32_bf16 v[94:97], v[166:169], v[226:229], v[94:97]
	v_mfma_f32_16x16x32_bf16 v[86:89], v[66:69], v[234:237], v[86:89]
	v_mfma_f32_16x16x32_bf16 v[78:81], v[166:169], v[234:237], v[78:81]
	s_setprio 0
	s_setprio 1
	v_mfma_f32_16x16x32_bf16 v[130:133], v[170:173], v[186:189], v[130:133]
	v_mfma_f32_16x16x32_bf16 v[122:125], v[178:181], v[186:189], v[122:125]
	v_mfma_f32_16x16x32_bf16 v[114:117], v[170:173], v[202:205], v[114:117]
	v_mfma_f32_16x16x32_bf16 v[106:109], v[178:181], v[202:205], v[106:109]
	v_mfma_f32_16x16x32_bf16 v[98:101], v[170:173], v[222:225], v[98:101]
	v_mfma_f32_16x16x32_bf16 v[90:93], v[178:181], v[222:225], v[90:93]
	v_mfma_f32_16x16x32_bf16 v[82:85], v[170:173], v[230:233], v[82:85]
	v_mfma_f32_16x16x32_bf16 v[74:77], v[178:181], v[230:233], v[74:77]
	v_mfma_f32_16x16x32_bf16 v[130:133], v[174:177], v[198:201], v[130:133]
	v_mfma_f32_16x16x32_bf16 v[122:125], v[182:185], v[198:201], v[122:125]
	v_mfma_f32_16x16x32_bf16 v[114:117], v[174:177], v[206:209], v[114:117]
	v_mfma_f32_16x16x32_bf16 v[106:109], v[182:185], v[206:209], v[106:109]
	v_mfma_f32_16x16x32_bf16 v[98:101], v[174:177], v[226:229], v[98:101]
	v_mfma_f32_16x16x32_bf16 v[90:93], v[182:185], v[226:229], v[90:93]
	v_mfma_f32_16x16x32_bf16 v[82:85], v[174:177], v[234:237], v[82:85]
	v_mfma_f32_16x16x32_bf16 v[74:77], v[182:185], v[234:237], v[74:77]
	s_setprio 0
	s_barrier
; #define PG8_STAGE(bufoff, gbase, voff) do { _Pragma("unroll") for (int _i = 0; _i < 2; ++_i) \
;         __builtin_amdgcn_global_load_lds((const unsigned*)((const char*)(gbase) + (voff)[_i]), (PG8_LAS unsigned*)(lds + (bufoff) + ldsw + _i * 8192), 16, 0, 0); } while (0)
; #define PG8_LDA(dst, b, h) do { _Pragma("unroll") for (int m = 0; m < 4; ++m) _Pragma("unroll") for (int k = 0; k < 2; ++k) dst[m][k] = *(const PG8_LAS bf16x8*)(lds + PG8_SA(b, h) + aoff + m * 2048 + k * 1024); } while (0)
; #define PG8_MMA(ai, bj, At, Bt) do { __builtin_amdgcn_s_setprio(1); _Pragma("unroll") for (int m = 0; m < 4; ++m) _Pragma("unroll") for (int n = 0; n < 2; ++n) _Pragma("unroll") for (int k = 0; k < 2; ++k) \
;         acc[ai][bj][m][n] = __builtin_amdgcn_mfma_f32_16x16x32_bf16(Bt[n][k], At[m][k], acc[ai][bj][m][n], 0, 0, 0); __builtin_amdgcn_s_setprio(0); } while (0)
; #define PG8_WAIT_V(n) asm volatile("s_waitcnt vmcnt(" #n ")" ::: "memory")
; #define PG8_WAIT_L(n) asm volatile("s_waitcnt lgkmcnt(" #n ")" ::: "memory")
; #define PG8_BAR __builtin_amdgcn_s_barrier()
; #define PG8_SCHED __builtin_amdgcn_sched_barrier(0)
; template <class Epi, class Sched, bool ALIGN_EPI = false, bool SP2 = false>
; __device__ __forceinline__ void gemm_phase(PG8_LAS unsigned char* lds, const Gemm g, const Sched& S, const Epi& E) {
;     ...
;             PG8_LDA(At, 1, 1); PG8_STAGE(PG8_SB(1, 0), b3, voffB); PG8_STAGE(PG8_SB(1, 1), b3 + hstep, voffB); PG8_STAGE(PG8_SA(1, 0), a3, voffA);
;             PG8_WAIT_V(8); PG8_WAIT_L(0); PG8_BAR; PG8_MMA(1, 0, At, B0); PG8_MMA(1, 1, At, B1); PG8_BAR; PG8_SCHED;
	s_add_i32 s30, s65, s33
	v_lshl_add_u64 v[152:153], v[152:153], 0, s[0:1]
	s_mov_b32 m0, s30
	ds_read_b128 v[186:189], v160 offset:49152
	ds_read_b128 v[198:201], v160 offset:50176
	ds_read_b128 v[202:205], v160 offset:51200
	ds_read_b128 v[206:209], v160 offset:52224
	ds_read_b128 v[222:225], v160 offset:53248
	ds_read_b128 v[226:229], v160 offset:54272
	ds_read_b128 v[230:233], v160 offset:55296
	ds_read_b128 v[234:237], v160 offset:56320
	global_load_lds_dwordx4 v[152:153], off
	s_add_i32 m0, s30, 0x2000
	s_add_u32 s30, s48, 0x40080
	v_lshl_add_u64 v[152:153], v[190:191], 0, s[0:1]
	s_addc_u32 s31, s49, 0
	s_add_i32 s48, s66, s33
	global_load_lds_dwordx4 v[152:153], off
	v_lshl_add_u64 v[152:153], s[30:31], 0, v[140:141]
	s_mov_b32 m0, s48
	s_nop 0
	global_load_lds_dwordx4 v[152:153], off
	v_lshl_add_u64 v[152:153], s[30:31], 0, v[144:145]
	s_add_i32 m0, s48, 0x2000
	s_nop 0
	global_load_lds_dwordx4 v[152:153], off
	v_lshl_add_u64 v[152:153], v[210:211], 0, s[0:1]
	s_mov_b32 m0, s56
	s_nop 0
	global_load_lds_dwordx4 v[152:153], off
	v_lshl_add_u64 v[152:153], v[238:239], 0, s[0:1]
	s_mov_b32 m0, s57
	s_nop 0
	global_load_lds_dwordx4 v[152:153], off
	s_waitcnt vmcnt(8)
	s_waitcnt lgkmcnt(0)
	s_barrier
	s_setprio 1
	s_waitcnt lgkmcnt(0)
	v_mfma_f32_16x16x32_bf16 v[70:73], v[58:61], v[186:189], v[70:73]
	v_mfma_f32_16x16x32_bf16 v[62:65], v[162:165], v[186:189], v[62:65]
	v_mfma_f32_16x16x32_bf16 v[46:49], v[58:61], v[202:205], v[46:49]
	v_mfma_f32_16x16x32_bf16 v[38:41], v[162:165], v[202:205], v[38:41]
	v_mfma_f32_16x16x32_bf16 v[30:33], v[58:61], v[222:225], v[30:33]
	v_mfma_f32_16x16x32_bf16 v[22:25], v[162:165], v[222:225], v[22:25]
	v_mfma_f32_16x16x32_bf16 v[14:17], v[58:61], v[230:233], v[14:17]
	v_mfma_f32_16x16x32_bf16 v[6:9], v[162:165], v[230:233], v[6:9]
	v_mfma_f32_16x16x32_bf16 v[70:73], v[66:69], v[198:201], v[70:73]
	v_mfma_f32_16x16x32_bf16 v[62:65], v[166:169], v[198:201], v[62:65]
	v_mfma_f32_16x16x32_bf16 v[46:49], v[66:69], v[206:209], v[46:49]
	v_mfma_f32_16x16x32_bf16 v[38:41], v[166:169], v[206:209], v[38:41]
	v_mfma_f32_16x16x32_bf16 v[30:33], v[66:69], v[226:229], v[30:33]
	v_mfma_f32_16x16x32_bf16 v[22:25], v[166:169], v[226:229], v[22:25]
	v_mfma_f32_16x16x32_bf16 v[14:17], v[66:69], v[234:237], v[14:17]
	v_mfma_f32_16x16x32_bf16 v[6:9], v[166:169], v[234:237], v[6:9]
	s_setprio 0
	s_setprio 1
	v_mfma_f32_16x16x32_bf16 v[50:53], v[170:173], v[186:189], v[50:53]
	v_mfma_f32_16x16x32_bf16 v[66:69], v[174:177], v[198:201], v[50:53]
	v_mfma_f32_16x16x32_bf16 v[50:53], v[178:181], v[186:189], v[54:57]
	v_mfma_f32_16x16x32_bf16 v[42:45], v[170:173], v[202:205], v[42:45]
	v_mfma_f32_16x16x32_bf16 v[34:37], v[178:181], v[202:205], v[34:37]
	v_mfma_f32_16x16x32_bf16 v[26:29], v[170:173], v[222:225], v[26:29]
	v_mfma_f32_16x16x32_bf16 v[18:21], v[178:181], v[222:225], v[18:21]
	v_mfma_f32_16x16x32_bf16 v[10:13], v[170:173], v[230:233], v[10:13]
	v_mfma_f32_16x16x32_bf16 v[2:5], v[178:181], v[230:233], v[2:5]
	v_mfma_f32_16x16x32_bf16 v[58:61], v[182:185], v[198:201], v[50:53]
	v_mfma_f32_16x16x32_bf16 v[42:45], v[174:177], v[206:209], v[42:45]
	v_mfma_f32_16x16x32_bf16 v[34:37], v[182:185], v[206:209], v[34:37]
	v_mfma_f32_16x16x32_bf16 v[26:29], v[174:177], v[226:229], v[26:29]
	v_mfma_f32_16x16x32_bf16 v[18:21], v[182:185], v[226:229], v[18:21]
	v_mfma_f32_16x16x32_bf16 v[10:13], v[174:177], v[234:237], v[10:13]
	v_mfma_f32_16x16x32_bf16 v[2:5], v[182:185], v[234:237], v[2:5]
	s_setprio 0
	s_barrier
	s_add_i32 s64, s64, 2
	s_add_u32 s46, s46, 0x100
	s_addc_u32 s47, s47, 0
	s_add_u32 s62, s62, 0x100
	s_addc_u32 s63, s63, 0
	s_cmp_gt_u32 s64, 13
	s_cbranch_scc0 .LBB0_781

; #define PG8_STAGE(bufoff, gbase, voff) do { _Pragma("unroll") for (int _i = 0; _i < 2; ++_i) \
;         __builtin_amdgcn_global_load_lds((const unsigned*)((const char*)(gbase) + (voff)[_i]), (PG8_LAS unsigned*)(lds + (bufoff) + ldsw + _i * 8192), 16, 0, 0); } while (0)
; #define PG8_LDA(dst, b, h) do { _Pragma("unroll") for (int m = 0; m < 4; ++m) _Pragma("unroll") for (int k = 0; k < 2; ++k) dst[m][k] = *(const PG8_LAS bf16x8*)(lds + PG8_SA(b, h) + aoff + m * 2048 + k * 1024); } while (0)
; #define PG8_LDB(dst, b, h) do { _Pragma("unroll") for (int n = 0; n < 2; ++n) _Pragma("unroll") for (int k = 0; k < 2; ++k) dst[n][k] = *(const PG8_LAS bf16x8*)(lds + PG8_SB(b, h) + boff + n * 2048 + k * 1024); } while (0)
; #define PG8_MMA(ai, bj, At, Bt) do { __builtin_amdgcn_s_setprio(1); _Pragma("unroll") for (int m = 0; m < 4; ++m) _Pragma("unroll") for (int n = 0; n < 2; ++n) _Pragma("unroll") for (int k = 0; k < 2; ++k) \
;         acc[ai][bj][m][n] = __builtin_amdgcn_mfma_f32_16x16x32_bf16(Bt[n][k], At[m][k], acc[ai][bj][m][n], 0, 0, 0); __builtin_amdgcn_s_setprio(0); } while (0)
; #define PG8_WAIT_V(n) asm volatile("s_waitcnt vmcnt(" #n ")" ::: "memory")
; #define PG8_WAIT_L(n) asm volatile("s_waitcnt lgkmcnt(" #n ")" ::: "memory")
; template <class Epi, class Sched, bool ALIGN_EPI = false, bool SP2 = false>
; __device__ __forceinline__ void gemm_phase(PG8_LAS unsigned char* lds, const Gemm g, const Sched& S, const Epi& E) {
;     ...
;             const bool last = (t == nt - 2);
;             const char* a1 = cA + (size_t)(t + 1) * kstep;
;             const char* a2 = last ? nA : cA + (size_t)(t + 2) * kstep; const char* b2 = last ? nB : cB + (size_t)(t + 2) * kstep;
;             const char* a3 = a2 + kstep; const char* b3 = b2 + kstep;
;             if (last && has_next) S.a_ready(nxt);
;             if constexpr (SP2) {
;             PG8_LDB(B0, 0, 0); PG8_LDB(B1, 0, 1); PG8_SCHED; PG8_LDA(At, 0, 0); PG8_STAGE(PG8_SA(1, 1), a1 + hstep, voffA);
;             PG8_WAIT_V(8); PG8_WAIT_L(0); PG8_BAR; PG8_MMA(0, 0, At, B0); PG8_MMA(0, 1, At, B1); PG8_BAR; PG8_SCHED;
;             PG8_LDA(At, 0, 1); PG8_STAGE(PG8_SB(0, 0), b2, voffB); PG8_STAGE(PG8_SB(0, 1), b2 + hstep, voffB); PG8_STAGE(PG8_SA(0, 0), a2, voffA);
;             PG8_WAIT_V(8); PG8_WAIT_L(0); PG8_BAR; PG8_MMA(1, 0, At, B0); PG8_MMA(1, 1, At, B1); PG8_BAR; PG8_SCHED;
.Lpeel_p5:
	s_add_u32 s42, s20, 0x100
	s_addc_u32 s43, s21, 0
	s_add_i32 s30, 0, 0x10000
	s_cmp_eq_u32 s59, 40
	s_cselect_b32 s47, s11, s43
	s_cselect_b32 s46, s10, s42
	s_cselect_b32 s45, s15, s35
	s_cselect_b32 s44, s14, s34
	s_add_i32 s31, 0, 0x14000
	v_add_u32_e32 v134, s30, v191
	v_add_u32_e32 v168, s31, v191
	ds_read_b128 v[114:117], v134
	ds_read_b128 v[126:129], v134 offset:1024
	ds_read_b128 v[130:133], v134 offset:2048
	ds_read_b128 v[134:137], v134 offset:3072
	ds_read_b128 v[146:149], v168
	ds_read_b128 v[150:153], v168 offset:1024
	ds_read_b128 v[154:157], v168 offset:2048
	ds_read_b128 v[168:171], v168 offset:3072
	v_lshl_add_u64 v[188:189], s[20:21], 0, v[164:165]
	s_add_i32 m0, s48, 0xc000
	ds_read_b128 v[172:175], v202
	ds_read_b128 v[176:179], v202 offset:1024
	ds_read_b128 v[180:183], v202 offset:2048
	ds_read_b128 v[184:187], v202 offset:3072
	ds_read_b128 v[198:201], v202 offset:4096
	ds_read_b128 v[204:207], v202 offset:5120
	ds_read_b128 v[208:211], v202 offset:6144
	ds_read_b128 v[222:225], v202 offset:7168
	global_load_lds_dwordx4 v[188:189], off
	v_lshl_add_u64 v[188:189], s[20:21], 0, v[166:167]
	s_add_i32 m0, s48, 0xe000
	s_nop 0
	global_load_lds_dwordx4 v[188:189], off
	s_waitcnt vmcnt(8)
	s_waitcnt lgkmcnt(0)
	s_barrier
	s_nop 0
	s_setprio 1
	s_waitcnt lgkmcnt(0)
	v_mfma_f32_16x16x32_bf16 v[142:145], v[114:117], v[172:175], 0
	v_mfma_f32_16x16x32_bf16 v[138:141], v[130:133], v[172:175], 0
	v_mfma_f32_16x16x32_bf16 v[110:113], v[114:117], v[180:183], 0
	v_mfma_f32_16x16x32_bf16 v[106:109], v[130:133], v[180:183], 0
	v_mfma_f32_16x16x32_bf16 v[94:97], v[114:117], v[198:201], 0
	v_mfma_f32_16x16x32_bf16 v[90:93], v[130:133], v[198:201], 0
	v_mfma_f32_16x16x32_bf16 v[78:81], v[114:117], v[208:211], 0
	v_mfma_f32_16x16x32_bf16 v[74:77], v[130:133], v[208:211], 0
	v_mfma_f32_16x16x32_bf16 v[142:145], v[126:129], v[176:179], v[142:145]
	v_mfma_f32_16x16x32_bf16 v[138:141], v[134:137], v[176:179], v[138:141]
	v_mfma_f32_16x16x32_bf16 v[110:113], v[126:129], v[184:187], v[110:113]
	v_mfma_f32_16x16x32_bf16 v[106:109], v[134:137], v[184:187], v[106:109]
	v_mfma_f32_16x16x32_bf16 v[94:97], v[126:129], v[204:207], v[94:97]
	v_mfma_f32_16x16x32_bf16 v[90:93], v[134:137], v[204:207], v[90:93]
	v_mfma_f32_16x16x32_bf16 v[78:81], v[126:129], v[222:225], v[78:81]
	v_mfma_f32_16x16x32_bf16 v[74:77], v[134:137], v[222:225], v[74:77]
	s_setprio 0
	s_setprio 1
	v_mfma_f32_16x16x32_bf16 v[122:125], v[146:149], v[172:175], 0
	v_mfma_f32_16x16x32_bf16 v[118:121], v[154:157], v[172:175], 0
	v_mfma_f32_16x16x32_bf16 v[102:105], v[146:149], v[180:183], 0
	v_mfma_f32_16x16x32_bf16 v[98:101], v[154:157], v[180:183], 0
	v_mfma_f32_16x16x32_bf16 v[86:89], v[146:149], v[198:201], 0
	v_mfma_f32_16x16x32_bf16 v[82:85], v[154:157], v[198:201], 0
	v_mfma_f32_16x16x32_bf16 v[70:73], v[146:149], v[208:211], 0
	v_mfma_f32_16x16x32_bf16 v[66:69], v[154:157], v[208:211], 0
	v_mfma_f32_16x16x32_bf16 v[122:125], v[150:153], v[176:179], v[122:125]
	v_mfma_f32_16x16x32_bf16 v[118:121], v[168:171], v[176:179], v[118:121]
	v_mfma_f32_16x16x32_bf16 v[102:105], v[150:153], v[184:187], v[102:105]
	v_mfma_f32_16x16x32_bf16 v[98:101], v[168:171], v[184:187], v[98:101]
	v_mfma_f32_16x16x32_bf16 v[86:89], v[150:153], v[204:207], v[86:89]
	v_mfma_f32_16x16x32_bf16 v[82:85], v[168:171], v[204:207], v[82:85]
	v_mfma_f32_16x16x32_bf16 v[70:73], v[150:153], v[222:225], v[70:73]
	v_mfma_f32_16x16x32_bf16 v[66:69], v[168:171], v[222:225], v[66:69]
	s_setprio 0
	s_barrier
	s_add_i32 s20, s30, s33
	v_lshl_add_u64 v[188:189], s[44:45], 0, v[0:1]
	s_mov_b32 m0, s20
	ds_read_b128 v[172:175], v202 offset:16384
	ds_read_b128 v[176:179], v202 offset:17408
	ds_read_b128 v[180:183], v202 offset:18432
	ds_read_b128 v[184:187], v202 offset:19456
	ds_read_b128 v[198:201], v202 offset:20480
	ds_read_b128 v[204:207], v202 offset:21504
	ds_read_b128 v[208:211], v202 offset:22528
	ds_read_b128 v[222:225], v202 offset:23552
	global_load_lds_dwordx4 v[188:189], off
	s_add_i32 m0, s20, 0x2000
	s_add_u32 s20, s44, 0xb0000
	v_lshl_add_u64 v[226:227], s[44:45], 0, v[158:159]
	s_addc_u32 s21, s45, 0
	s_add_i32 s30, s31, s33
	global_load_lds_dwordx4 v[226:227], off
	v_lshl_add_u64 v[228:229], s[20:21], 0, v[0:1]
	s_mov_b32 m0, s30
	v_lshl_add_u64 v[230:231], s[46:47], 0, v[160:161]
	global_load_lds_dwordx4 v[228:229], off
	v_lshl_add_u64 v[228:229], s[20:21], 0, v[158:159]
	s_add_i32 m0, s30, 0x2000
	s_nop 0
	global_load_lds_dwordx4 v[228:229], off
	v_lshl_add_u64 v[228:229], s[46:47], 0, v[162:163]
	s_mov_b32 m0, s48
	s_nop 0
	global_load_lds_dwordx4 v[228:229], off
	s_mov_b32 m0, s49
	s_nop 0
	global_load_lds_dwordx4 v[230:231], off
	s_waitcnt vmcnt(8)
	s_waitcnt lgkmcnt(0)
	s_barrier
; #define PG8_STAGE(bufoff, gbase, voff) do { _Pragma("unroll") for (int _i = 0; _i < 2; ++_i) \
;         __builtin_amdgcn_global_load_lds((const unsigned*)((const char*)(gbase) + (voff)[_i]), (PG8_LAS unsigned*)(lds + (bufoff) + ldsw + _i * 8192), 16, 0, 0); } while (0)
; #define PG8_LDA(dst, b, h) do { _Pragma("unroll") for (int m = 0; m < 4; ++m) _Pragma("unroll") for (int k = 0; k < 2; ++k) dst[m][k] = *(const PG8_LAS bf16x8*)(lds + PG8_SA(b, h) + aoff + m * 2048 + k * 1024); } while (0)
; #define PG8_LDB(dst, b, h) do { _Pragma("unroll") for (int n = 0; n < 2; ++n) _Pragma("unroll") for (int k = 0; k < 2; ++k) dst[n][k] = *(const PG8_LAS bf16x8*)(lds + PG8_SB(b, h) + boff + n * 2048 + k * 1024); } while (0)
; #define PG8_MMA(ai, bj, At, Bt) do { __builtin_amdgcn_s_setprio(1); _Pragma("unroll") for (int m = 0; m < 4; ++m) _Pragma("unroll") for (int n = 0; n < 2; ++n) _Pragma("unroll") for (int k = 0; k < 2; ++k) \
;         acc[ai][bj][m][n] = __builtin_amdgcn_mfma_f32_16x16x32_bf16(Bt[n][k], At[m][k], acc[ai][bj][m][n], 0, 0, 0); __builtin_amdgcn_s_setprio(0); } while (0)
; #define PG8_WAIT_V(n) asm volatile("s_waitcnt vmcnt(" #n ")" ::: "memory")
; #define PG8_WAIT_L(n) asm volatile("s_waitcnt lgkmcnt(" #n ")" ::: "memory")
; #define PG8_BAR __builtin_amdgcn_s_barrier()
; #define PG8_SCHED __builtin_amdgcn_sched_barrier(0)
; template <class Epi, class Sched, bool ALIGN_EPI = false, bool SP2 = false>
; __device__ __forceinline__ void gemm_phase(PG8_LAS unsigned char* lds, const Gemm g, const Sched& S, const Epi& E) {
;     ...
;             PG8_WAIT_V(8); PG8_WAIT_L(0); PG8_BAR; PG8_MMA(1, 0, At, B0); PG8_MMA(1, 1, At, B1); PG8_BAR; PG8_SCHED;
;             PG8_LDB(B0, 1, 0); PG8_LDB(B1, 1, 1); PG8_SCHED; PG8_LDA(At, 1, 0); PG8_STAGE(PG8_SA(0, 1), a2 + hstep, voffA);
;             PG8_WAIT_V(8); PG8_WAIT_L(0); PG8_BAR; PG8_MMA(0, 0, At, B0); PG8_MMA(0, 1, At, B1); PG8_BAR; PG8_SCHED;
	s_nop 0
	s_setprio 1
	s_waitcnt lgkmcnt(0)
	v_mfma_f32_16x16x32_bf16 v[62:65], v[114:117], v[172:175], 0
	v_mfma_f32_16x16x32_bf16 v[58:61], v[130:133], v[172:175], 0
	v_mfma_f32_16x16x32_bf16 v[46:49], v[114:117], v[180:183], 0
	v_mfma_f32_16x16x32_bf16 v[42:45], v[130:133], v[180:183], 0
	v_mfma_f32_16x16x32_bf16 v[30:33], v[114:117], v[198:201], 0
	v_mfma_f32_16x16x32_bf16 v[26:29], v[130:133], v[198:201], 0
	v_mfma_f32_16x16x32_bf16 v[14:17], v[114:117], v[208:211], 0
	v_mfma_f32_16x16x32_bf16 v[10:13], v[130:133], v[208:211], 0
	v_mfma_f32_16x16x32_bf16 v[62:65], v[126:129], v[176:179], v[62:65]
	v_mfma_f32_16x16x32_bf16 v[58:61], v[134:137], v[176:179], v[58:61]
	v_mfma_f32_16x16x32_bf16 v[46:49], v[126:129], v[184:187], v[46:49]
	v_mfma_f32_16x16x32_bf16 v[42:45], v[134:137], v[184:187], v[42:45]
	v_mfma_f32_16x16x32_bf16 v[30:33], v[126:129], v[204:207], v[30:33]
	v_mfma_f32_16x16x32_bf16 v[26:29], v[134:137], v[204:207], v[26:29]
	v_mfma_f32_16x16x32_bf16 v[14:17], v[126:129], v[222:225], v[14:17]
	v_mfma_f32_16x16x32_bf16 v[10:13], v[134:137], v[222:225], v[10:13]
	s_setprio 0
	s_setprio 1
	v_mfma_f32_16x16x32_bf16 v[54:57], v[146:149], v[172:175], 0
	v_mfma_f32_16x16x32_bf16 v[50:53], v[154:157], v[172:175], 0
	v_mfma_f32_16x16x32_bf16 v[38:41], v[146:149], v[180:183], 0
	v_mfma_f32_16x16x32_bf16 v[34:37], v[154:157], v[180:183], 0
	v_mfma_f32_16x16x32_bf16 v[22:25], v[146:149], v[198:201], 0
	v_mfma_f32_16x16x32_bf16 v[18:21], v[154:157], v[198:201], 0
	v_mfma_f32_16x16x32_bf16 v[6:9], v[146:149], v[208:211], 0
	v_mfma_f32_16x16x32_bf16 v[2:5], v[154:157], v[208:211], 0
	v_mfma_f32_16x16x32_bf16 v[54:57], v[150:153], v[176:179], v[54:57]
	v_mfma_f32_16x16x32_bf16 v[50:53], v[168:171], v[176:179], v[50:53]
	v_mfma_f32_16x16x32_bf16 v[38:41], v[150:153], v[184:187], v[38:41]
	v_mfma_f32_16x16x32_bf16 v[34:37], v[168:171], v[184:187], v[34:37]
	v_mfma_f32_16x16x32_bf16 v[22:25], v[150:153], v[204:207], v[22:25]
	v_mfma_f32_16x16x32_bf16 v[18:21], v[168:171], v[204:207], v[18:21]
	v_mfma_f32_16x16x32_bf16 v[6:9], v[150:153], v[222:225], v[6:9]
	v_mfma_f32_16x16x32_bf16 v[2:5], v[168:171], v[222:225], v[2:5]
	s_setprio 0
	s_barrier
	s_add_i32 s30, 0, 0x18000
	s_add_i32 s31, 0, 0x1c000
	v_add_u32_e32 v134, s30, v191
	v_add_u32_e32 v168, s31, v191
	ds_read_b128 v[114:117], v134
	ds_read_b128 v[126:129], v134 offset:1024
	ds_read_b128 v[130:133], v134 offset:2048
	ds_read_b128 v[134:137], v134 offset:3072
	ds_read_b128 v[146:149], v168
	ds_read_b128 v[150:153], v168 offset:1024
	ds_read_b128 v[154:157], v168 offset:2048
	ds_read_b128 v[168:171], v168 offset:3072
	s_add_u32 s20, s46, 0xb0000
	s_addc_u32 s21, s47, 0
	s_mov_b32 m0, s50
	v_lshl_add_u64 v[232:233], s[20:21], 0, v[162:163]
	ds_read_b128 v[172:175], v202 offset:32768
	ds_read_b128 v[176:179], v202 offset:33792
	ds_read_b128 v[180:183], v202 offset:34816
	ds_read_b128 v[184:187], v202 offset:35840
	ds_read_b128 v[198:201], v202 offset:36864
	ds_read_b128 v[204:207], v202 offset:37888
	ds_read_b128 v[208:211], v202 offset:38912
	ds_read_b128 v[222:225], v202 offset:39936
	global_load_lds_dwordx4 v[232:233], off
	v_lshl_add_u64 v[232:233], s[20:21], 0, v[160:161]
	s_mov_b32 m0, s51
	s_nop 0
	global_load_lds_dwordx4 v[232:233], off
	s_waitcnt vmcnt(8)
	s_waitcnt lgkmcnt(0)
	s_barrier
	s_nop 0
	s_setprio 1
	s_waitcnt lgkmcnt(0)
	v_mfma_f32_16x16x32_bf16 v[142:145], v[114:117], v[172:175], v[142:145]
	v_mfma_f32_16x16x32_bf16 v[138:141], v[130:133], v[172:175], v[138:141]
	v_mfma_f32_16x16x32_bf16 v[110:113], v[114:117], v[180:183], v[110:113]
	v_mfma_f32_16x16x32_bf16 v[106:109], v[130:133], v[180:183], v[106:109]
	v_mfma_f32_16x16x32_bf16 v[94:97], v[114:117], v[198:201], v[94:97]
	v_mfma_f32_16x16x32_bf16 v[90:93], v[130:133], v[198:201], v[90:93]
	v_mfma_f32_16x16x32_bf16 v[78:81], v[114:117], v[208:211], v[78:81]
	v_mfma_f32_16x16x32_bf16 v[74:77], v[130:133], v[208:211], v[74:77]
	v_mfma_f32_16x16x32_bf16 v[142:145], v[126:129], v[176:179], v[142:145]
	v_mfma_f32_16x16x32_bf16 v[138:141], v[134:137], v[176:179], v[138:141]
	v_mfma_f32_16x16x32_bf16 v[110:113], v[126:129], v[184:187], v[110:113]
	v_mfma_f32_16x16x32_bf16 v[106:109], v[134:137], v[184:187], v[106:109]
	v_mfma_f32_16x16x32_bf16 v[94:97], v[126:129], v[204:207], v[94:97]
	v_mfma_f32_16x16x32_bf16 v[90:93], v[134:137], v[204:207], v[90:93]
	v_mfma_f32_16x16x32_bf16 v[78:81], v[126:129], v[222:225], v[78:81]
	v_mfma_f32_16x16x32_bf16 v[74:77], v[134:137], v[222:225], v[74:77]
	s_setprio 0
	s_setprio 1
	v_mfma_f32_16x16x32_bf16 v[122:125], v[146:149], v[172:175], v[122:125]
	v_mfma_f32_16x16x32_bf16 v[118:121], v[154:157], v[172:175], v[118:121]
	v_mfma_f32_16x16x32_bf16 v[102:105], v[146:149], v[180:183], v[102:105]
	v_mfma_f32_16x16x32_bf16 v[98:101], v[154:157], v[180:183], v[98:101]
	v_mfma_f32_16x16x32_bf16 v[86:89], v[146:149], v[198:201], v[86:89]
	v_mfma_f32_16x16x32_bf16 v[82:85], v[154:157], v[198:201], v[82:85]
	v_mfma_f32_16x16x32_bf16 v[70:73], v[146:149], v[208:211], v[70:73]
	v_mfma_f32_16x16x32_bf16 v[66:69], v[154:157], v[208:211], v[66:69]
	v_mfma_f32_16x16x32_bf16 v[122:125], v[150:153], v[176:179], v[122:125]
	v_mfma_f32_16x16x32_bf16 v[118:121], v[168:171], v[176:179], v[118:121]
	v_mfma_f32_16x16x32_bf16 v[102:105], v[150:153], v[184:187], v[102:105]
	v_mfma_f32_16x16x32_bf16 v[98:101], v[168:171], v[184:187], v[98:101]
	v_mfma_f32_16x16x32_bf16 v[86:89], v[150:153], v[204:207], v[86:89]
	v_mfma_f32_16x16x32_bf16 v[82:85], v[168:171], v[204:207], v[82:85]
	v_mfma_f32_16x16x32_bf16 v[70:73], v[150:153], v[222:225], v[70:73]
	v_mfma_f32_16x16x32_bf16 v[66:69], v[168:171], v[222:225], v[66:69]
	s_setprio 0
	s_barrier
; #define PG8_STAGE(bufoff, gbase, voff) do { _Pragma("unroll") for (int _i = 0; _i < 2; ++_i) \
;         __builtin_amdgcn_global_load_lds((const unsigned*)((const char*)(gbase) + (voff)[_i]), (PG8_LAS unsigned*)(lds + (bufoff) + ldsw + _i * 8192), 16, 0, 0); } while (0)
; #define PG8_LDA(dst, b, h) do { _Pragma("unroll") for (int m = 0; m < 4; ++m) _Pragma("unroll") for (int k = 0; k < 2; ++k) dst[m][k] = *(const PG8_LAS bf16x8*)(lds + PG8_SA(b, h) + aoff + m * 2048 + k * 1024); } while (0)
; #define PG8_LDB(dst, b, h) do { _Pragma("unroll") for (int n = 0; n < 2; ++n) _Pragma("unroll") for (int k = 0; k < 2; ++k) dst[n][k] = *(const PG8_LAS bf16x8*)(lds + PG8_SB(b, h) + boff + n * 2048 + k * 1024); } while (0)
; #define PG8_MMA(ai, bj, At, Bt) do { __builtin_amdgcn_s_setprio(1); _Pragma("unroll") for (int m = 0; m < 4; ++m) _Pragma("unroll") for (int n = 0; n < 2; ++n) _Pragma("unroll") for (int k = 0; k < 2; ++k) \
;         acc[ai][bj][m][n] = __builtin_amdgcn_mfma_f32_16x16x32_bf16(Bt[n][k], At[m][k], acc[ai][bj][m][n], 0, 0, 0); __builtin_amdgcn_s_setprio(0); } while (0)
; #define PG8_WAIT_V(n) asm volatile("s_waitcnt vmcnt(" #n ")" ::: "memory")
; template <class Epi, class Sched, bool ALIGN_EPI = false, bool SP2 = false>
; __device__ __forceinline__ void gemm_phase(PG8_LAS unsigned char* lds, const Gemm g, const Sched& S, const Epi& E) {
;     ...
;             PG8_LDB(B0, 0, 0); PG8_LDB(B1, 0, 1); PG8_SCHED; PG8_LDA(At, 0, 0); PG8_STAGE(PG8_SA(1, 1), a1 + hstep, voffA);
;             PG8_WAIT_V(8); PG8_WAIT_L(0); PG8_BAR; PG8_MMA(0, 0, At, B0); PG8_MMA(0, 1, At, B1); PG8_BAR; PG8_SCHED;
;             PG8_LDA(At, 0, 1); PG8_STAGE(PG8_SB(0, 0), b2, voffB); PG8_STAGE(PG8_SB(0, 1), b2 + hstep, voffB); PG8_STAGE(PG8_SA(0, 0), a2, voffA);
;             PG8_WAIT_V(8); PG8_WAIT_L(0); PG8_BAR; PG8_MMA(1, 0, At, B0); PG8_MMA(1, 1, At, B1); PG8_BAR; PG8_SCHED;
;             PG8_LDB(B0, 1, 0); PG8_LDB(B1, 1, 1); PG8_SCHED; PG8_LDA(At, 1, 0); PG8_STAGE(PG8_SA(0, 1), a2 + hstep, voffA);
;             PG8_WAIT_V(8); PG8_WAIT_L(0); PG8_BAR; PG8_MMA(0, 0, At, B0); PG8_MMA(0, 1, At, B1); PG8_BAR; PG8_SCHED;
;             PG8_LDA(At, 1, 1); PG8_STAGE(PG8_SB(1, 0), b3, voffB); PG8_STAGE(PG8_SB(1, 1), b3 + hstep, voffB); PG8_STAGE(PG8_SA(1, 0), a3, voffA);
;             PG8_WAIT_V(8); PG8_WAIT_L(0); PG8_BAR; PG8_MMA(1, 0, At, B0); PG8_MMA(1, 1, At, B1); PG8_BAR; PG8_SCHED;
	s_add_i32 s20, s30, s33
	v_lshl_add_u64 v[188:189], v[188:189], 0, s[0:1]
	s_mov_b32 m0, s20
	ds_read_b128 v[172:175], v202 offset:49152
	ds_read_b128 v[176:179], v202 offset:50176
	ds_read_b128 v[180:183], v202 offset:51200
	ds_read_b128 v[184:187], v202 offset:52224
	ds_read_b128 v[198:201], v202 offset:53248
	ds_read_b128 v[204:207], v202 offset:54272
	ds_read_b128 v[208:211], v202 offset:55296
	ds_read_b128 v[222:225], v202 offset:56320
	global_load_lds_dwordx4 v[188:189], off
	s_add_i32 m0, s20, 0x2000
	s_add_u32 s20, s44, 0xb0080
	v_lshl_add_u64 v[188:189], v[226:227], 0, s[0:1]
	s_addc_u32 s21, s45, 0
	s_add_i32 s30, s31, s33
	global_load_lds_dwordx4 v[188:189], off
	v_lshl_add_u64 v[188:189], s[20:21], 0, v[0:1]
	s_mov_b32 m0, s30
	s_nop 0
	global_load_lds_dwordx4 v[188:189], off
	v_lshl_add_u64 v[188:189], s[20:21], 0, v[158:159]
	s_add_i32 m0, s30, 0x2000
	s_nop 0
	global_load_lds_dwordx4 v[188:189], off
	v_lshl_add_u64 v[188:189], v[228:229], 0, s[0:1]
	s_mov_b32 m0, s54
	s_nop 0
	global_load_lds_dwordx4 v[188:189], off
	v_lshl_add_u64 v[188:189], v[230:231], 0, s[0:1]
	s_mov_b32 m0, s55
	s_nop 0
	global_load_lds_dwordx4 v[188:189], off
	s_waitcnt vmcnt(8)
	s_waitcnt lgkmcnt(0)
	s_barrier
	s_setprio 1
	s_waitcnt lgkmcnt(0)
	v_mfma_f32_16x16x32_bf16 v[62:65], v[114:117], v[172:175], v[62:65]
	v_mfma_f32_16x16x32_bf16 v[58:61], v[130:133], v[172:175], v[58:61]
	v_mfma_f32_16x16x32_bf16 v[46:49], v[114:117], v[180:183], v[46:49]
	v_mfma_f32_16x16x32_bf16 v[42:45], v[130:133], v[180:183], v[42:45]
	v_mfma_f32_16x16x32_bf16 v[30:33], v[114:117], v[198:201], v[30:33]
	v_mfma_f32_16x16x32_bf16 v[26:29], v[130:133], v[198:201], v[26:29]
	v_mfma_f32_16x16x32_bf16 v[14:17], v[114:117], v[208:211], v[14:17]
	v_mfma_f32_16x16x32_bf16 v[10:13], v[130:133], v[208:211], v[10:13]
	v_mfma_f32_16x16x32_bf16 v[62:65], v[126:129], v[176:179], v[62:65]
	v_mfma_f32_16x16x32_bf16 v[58:61], v[134:137], v[176:179], v[58:61]
	v_mfma_f32_16x16x32_bf16 v[46:49], v[126:129], v[184:187], v[46:49]
	v_mfma_f32_16x16x32_bf16 v[42:45], v[134:137], v[184:187], v[42:45]
	v_mfma_f32_16x16x32_bf16 v[30:33], v[126:129], v[204:207], v[30:33]
	v_mfma_f32_16x16x32_bf16 v[26:29], v[134:137], v[204:207], v[26:29]
	v_mfma_f32_16x16x32_bf16 v[14:17], v[126:129], v[222:225], v[14:17]
	v_mfma_f32_16x16x32_bf16 v[10:13], v[134:137], v[222:225], v[10:13]
	s_setprio 0
	s_setprio 1
	v_mfma_f32_16x16x32_bf16 v[54:57], v[146:149], v[172:175], v[54:57]
	v_mfma_f32_16x16x32_bf16 v[50:53], v[154:157], v[172:175], v[50:53]
	v_mfma_f32_16x16x32_bf16 v[38:41], v[146:149], v[180:183], v[38:41]
	v_mfma_f32_16x16x32_bf16 v[34:37], v[154:157], v[180:183], v[34:37]
	v_mfma_f32_16x16x32_bf16 v[22:25], v[146:149], v[198:201], v[22:25]
	v_mfma_f32_16x16x32_bf16 v[18:21], v[154:157], v[198:201], v[18:21]
	v_mfma_f32_16x16x32_bf16 v[6:9], v[146:149], v[208:211], v[6:9]
	v_mfma_f32_16x16x32_bf16 v[2:5], v[154:157], v[208:211], v[2:5]
	v_mfma_f32_16x16x32_bf16 v[54:57], v[150:153], v[176:179], v[54:57]
	v_mfma_f32_16x16x32_bf16 v[50:53], v[168:171], v[176:179], v[50:53]
	v_mfma_f32_16x16x32_bf16 v[38:41], v[150:153], v[184:187], v[38:41]
	v_mfma_f32_16x16x32_bf16 v[34:37], v[168:171], v[184:187], v[34:37]
	v_mfma_f32_16x16x32_bf16 v[22:25], v[150:153], v[204:207], v[22:25]
	v_mfma_f32_16x16x32_bf16 v[18:21], v[168:171], v[204:207], v[18:21]
	v_mfma_f32_16x16x32_bf16 v[6:9], v[150:153], v[222:225], v[6:9]
	v_mfma_f32_16x16x32_bf16 v[2:5], v[168:171], v[222:225], v[2:5]
	s_setprio 0
	s_barrier
	s_add_i32 s59, s59, 2
	s_add_u32 s34, s34, 0x100
	s_addc_u32 s35, s35, 0
	s_cmp_gt_u32 s59, 41
	s_mov_b64 s[20:21], s[42:43]
	s_cbranch_scc0 .LBB0_868
	s_branch .Lpeel_exit_p5
.LBB0_868:
	s_add_u32 s42, s20, 0x100
	s_addc_u32 s43, s21, 0
	s_add_i32 s30, 0, 0x10000
	s_cmp_eq_u32 s59, 40
	s_cselect_b32 s47, s11, s43
	s_cselect_b32 s46, s10, s42
	s_cselect_b32 s45, s15, s35
	s_cselect_b32 s44, s14, s34
	s_add_i32 s31, 0, 0x14000
	v_add_u32_e32 v134, s30, v191
	v_add_u32_e32 v168, s31, v191
	ds_read_b128 v[114:117], v134
	ds_read_b128 v[126:129], v134 offset:1024
	ds_read_b128 v[130:133], v134 offset:2048
	ds_read_b128 v[134:137], v134 offset:3072
	ds_read_b128 v[146:149], v168
	ds_read_b128 v[150:153], v168 offset:1024
	ds_read_b128 v[154:157], v168 offset:2048
	ds_read_b128 v[168:171], v168 offset:3072
	v_lshl_add_u64 v[188:189], s[20:21], 0, v[164:165]
	s_add_i32 m0, s48, 0xc000
	ds_read_b128 v[172:175], v202
	ds_read_b128 v[176:179], v202 offset:1024
	ds_read_b128 v[180:183], v202 offset:2048
	ds_read_b128 v[184:187], v202 offset:3072
	ds_read_b128 v[198:201], v202 offset:4096
	ds_read_b128 v[204:207], v202 offset:5120
	ds_read_b128 v[208:211], v202 offset:6144
	ds_read_b128 v[222:225], v202 offset:7168
	global_load_lds_dwordx4 v[188:189], off
	v_lshl_add_u64 v[188:189], s[20:21], 0, v[166:167]
	s_add_i32 m0, s48, 0xe000
	s_nop 0
	global_load_lds_dwordx4 v[188:189], off
	s_waitcnt vmcnt(8)
	s_waitcnt lgkmcnt(0)
	s_barrier
; #define PG8_STAGE(bufoff, gbase, voff) do { _Pragma("unroll") for (int _i = 0; _i < 2; ++_i) \
;         __builtin_amdgcn_global_load_lds((const unsigned*)((const char*)(gbase) + (voff)[_i]), (PG8_LAS unsigned*)(lds + (bufoff) + ldsw + _i * 8192), 16, 0, 0); } while (0)
; #define PG8_LDA(dst, b, h) do { _Pragma("unroll") for (int m = 0; m < 4; ++m) _Pragma("unroll") for (int k = 0; k < 2; ++k) dst[m][k] = *(const PG8_LAS bf16x8*)(lds + PG8_SA(b, h) + aoff + m * 2048 + k * 1024); } while (0)
; #define PG8_MMA(ai, bj, At, Bt) do { __builtin_amdgcn_s_setprio(1); _Pragma("unroll") for (int m = 0; m < 4; ++m) _Pragma("unroll") for (int n = 0; n < 2; ++n) _Pragma("unroll") for (int k = 0; k < 2; ++k) \
;         acc[ai][bj][m][n] = __builtin_amdgcn_mfma_f32_16x16x32_bf16(Bt[n][k], At[m][k], acc[ai][bj][m][n], 0, 0, 0); __builtin_amdgcn_s_setprio(0); } while (0)
; #define PG8_WAIT_V(n) asm volatile("s_waitcnt vmcnt(" #n ")" ::: "memory")
; #define PG8_WAIT_L(n) asm volatile("s_waitcnt lgkmcnt(" #n ")" ::: "memory")
; #define PG8_BAR __builtin_amdgcn_s_barrier()
; #define PG8_SCHED __builtin_amdgcn_sched_barrier(0)
; template <class Epi, class Sched, bool ALIGN_EPI = false, bool SP2 = false>
; __device__ __forceinline__ void gemm_phase(PG8_LAS unsigned char* lds, const Gemm g, const Sched& S, const Epi& E) {
;     ...
;             PG8_WAIT_V(8); PG8_WAIT_L(0); PG8_BAR; PG8_MMA(0, 0, At, B0); PG8_MMA(0, 1, At, B1); PG8_BAR; PG8_SCHED;
;             PG8_LDA(At, 0, 1); PG8_STAGE(PG8_SB(0, 0), b2, voffB); PG8_STAGE(PG8_SB(0, 1), b2 + hstep, voffB); PG8_STAGE(PG8_SA(0, 0), a2, voffA);
;             PG8_WAIT_V(8); PG8_WAIT_L(0); PG8_BAR; PG8_MMA(1, 0, At, B0); PG8_MMA(1, 1, At, B1); PG8_BAR; PG8_SCHED;
	s_setprio 1
	s_waitcnt lgkmcnt(0)
	v_mfma_f32_16x16x32_bf16 v[142:145], v[114:117], v[172:175], v[142:145]
	v_mfma_f32_16x16x32_bf16 v[138:141], v[130:133], v[172:175], v[138:141]
	v_mfma_f32_16x16x32_bf16 v[110:113], v[114:117], v[180:183], v[110:113]
	v_mfma_f32_16x16x32_bf16 v[106:109], v[130:133], v[180:183], v[106:109]
	v_mfma_f32_16x16x32_bf16 v[94:97], v[114:117], v[198:201], v[94:97]
	v_mfma_f32_16x16x32_bf16 v[90:93], v[130:133], v[198:201], v[90:93]
	v_mfma_f32_16x16x32_bf16 v[78:81], v[114:117], v[208:211], v[78:81]
	v_mfma_f32_16x16x32_bf16 v[74:77], v[130:133], v[208:211], v[74:77]
	v_mfma_f32_16x16x32_bf16 v[142:145], v[126:129], v[176:179], v[142:145]
	v_mfma_f32_16x16x32_bf16 v[138:141], v[134:137], v[176:179], v[138:141]
	v_mfma_f32_16x16x32_bf16 v[110:113], v[126:129], v[184:187], v[110:113]
	v_mfma_f32_16x16x32_bf16 v[106:109], v[134:137], v[184:187], v[106:109]
	v_mfma_f32_16x16x32_bf16 v[94:97], v[126:129], v[204:207], v[94:97]
	v_mfma_f32_16x16x32_bf16 v[90:93], v[134:137], v[204:207], v[90:93]
	v_mfma_f32_16x16x32_bf16 v[78:81], v[126:129], v[222:225], v[78:81]
	v_mfma_f32_16x16x32_bf16 v[74:77], v[134:137], v[222:225], v[74:77]
	s_setprio 0
	s_setprio 1
	v_mfma_f32_16x16x32_bf16 v[122:125], v[146:149], v[172:175], v[122:125]
	v_mfma_f32_16x16x32_bf16 v[118:121], v[154:157], v[172:175], v[118:121]
	v_mfma_f32_16x16x32_bf16 v[102:105], v[146:149], v[180:183], v[102:105]
	v_mfma_f32_16x16x32_bf16 v[98:101], v[154:157], v[180:183], v[98:101]
	v_mfma_f32_16x16x32_bf16 v[86:89], v[146:149], v[198:201], v[86:89]
	v_mfma_f32_16x16x32_bf16 v[82:85], v[154:157], v[198:201], v[82:85]
	v_mfma_f32_16x16x32_bf16 v[70:73], v[146:149], v[208:211], v[70:73]
	v_mfma_f32_16x16x32_bf16 v[66:69], v[154:157], v[208:211], v[66:69]
	v_mfma_f32_16x16x32_bf16 v[122:125], v[150:153], v[176:179], v[122:125]
	v_mfma_f32_16x16x32_bf16 v[118:121], v[168:171], v[176:179], v[118:121]
	v_mfma_f32_16x16x32_bf16 v[102:105], v[150:153], v[184:187], v[102:105]
	v_mfma_f32_16x16x32_bf16 v[98:101], v[168:171], v[184:187], v[98:101]
	v_mfma_f32_16x16x32_bf16 v[86:89], v[150:153], v[204:207], v[86:89]
	v_mfma_f32_16x16x32_bf16 v[82:85], v[168:171], v[204:207], v[82:85]
	v_mfma_f32_16x16x32_bf16 v[70:73], v[150:153], v[222:225], v[70:73]
	v_mfma_f32_16x16x32_bf16 v[66:69], v[168:171], v[222:225], v[66:69]
	s_setprio 0
	s_barrier
	s_add_i32 s20, s30, s33
	v_lshl_add_u64 v[188:189], s[44:45], 0, v[0:1]
	s_mov_b32 m0, s20
	ds_read_b128 v[172:175], v202 offset:16384
	ds_read_b128 v[176:179], v202 offset:17408
	ds_read_b128 v[180:183], v202 offset:18432
	ds_read_b128 v[184:187], v202 offset:19456
	ds_read_b128 v[198:201], v202 offset:20480
	ds_read_b128 v[204:207], v202 offset:21504
	ds_read_b128 v[208:211], v202 offset:22528
	ds_read_b128 v[222:225], v202 offset:23552
	global_load_lds_dwordx4 v[188:189], off
	s_add_i32 m0, s20, 0x2000
	s_add_u32 s20, s44, 0xb0000
	v_lshl_add_u64 v[226:227], s[44:45], 0, v[158:159]
	s_addc_u32 s21, s45, 0
	s_add_i32 s30, s31, s33
	global_load_lds_dwordx4 v[226:227], off
	v_lshl_add_u64 v[228:229], s[20:21], 0, v[0:1]
	s_mov_b32 m0, s30
	v_lshl_add_u64 v[230:231], s[46:47], 0, v[160:161]
	global_load_lds_dwordx4 v[228:229], off
	v_lshl_add_u64 v[228:229], s[20:21], 0, v[158:159]
	s_add_i32 m0, s30, 0x2000
	s_nop 0
	global_load_lds_dwordx4 v[228:229], off
	v_lshl_add_u64 v[228:229], s[46:47], 0, v[162:163]
	s_mov_b32 m0, s48
	s_nop 0
	global_load_lds_dwordx4 v[228:229], off
	s_mov_b32 m0, s49
	s_nop 0
	global_load_lds_dwordx4 v[230:231], off
	s_waitcnt vmcnt(8)
	s_waitcnt lgkmcnt(0)
	s_barrier
	s_nop 0
	s_setprio 1
	s_waitcnt lgkmcnt(0)
	v_mfma_f32_16x16x32_bf16 v[62:65], v[114:117], v[172:175], v[62:65]
	v_mfma_f32_16x16x32_bf16 v[58:61], v[130:133], v[172:175], v[58:61]
	v_mfma_f32_16x16x32_bf16 v[46:49], v[114:117], v[180:183], v[46:49]
	v_mfma_f32_16x16x32_bf16 v[42:45], v[130:133], v[180:183], v[42:45]
	v_mfma_f32_16x16x32_bf16 v[30:33], v[114:117], v[198:201], v[30:33]
	v_mfma_f32_16x16x32_bf16 v[26:29], v[130:133], v[198:201], v[26:29]
	v_mfma_f32_16x16x32_bf16 v[14:17], v[114:117], v[208:211], v[14:17]
	v_mfma_f32_16x16x32_bf16 v[10:13], v[130:133], v[208:211], v[10:13]
	v_mfma_f32_16x16x32_bf16 v[62:65], v[126:129], v[176:179], v[62:65]
	v_mfma_f32_16x16x32_bf16 v[58:61], v[134:137], v[176:179], v[58:61]
	v_mfma_f32_16x16x32_bf16 v[46:49], v[126:129], v[184:187], v[46:49]
	v_mfma_f32_16x16x32_bf16 v[42:45], v[134:137], v[184:187], v[42:45]
	v_mfma_f32_16x16x32_bf16 v[30:33], v[126:129], v[204:207], v[30:33]
	v_mfma_f32_16x16x32_bf16 v[26:29], v[134:137], v[204:207], v[26:29]
	v_mfma_f32_16x16x32_bf16 v[14:17], v[126:129], v[222:225], v[14:17]
	v_mfma_f32_16x16x32_bf16 v[10:13], v[134:137], v[222:225], v[10:13]
	s_setprio 0
	s_setprio 1
	v_mfma_f32_16x16x32_bf16 v[54:57], v[146:149], v[172:175], v[54:57]
	v_mfma_f32_16x16x32_bf16 v[50:53], v[154:157], v[172:175], v[50:53]
	v_mfma_f32_16x16x32_bf16 v[38:41], v[146:149], v[180:183], v[38:41]
	v_mfma_f32_16x16x32_bf16 v[34:37], v[154:157], v[180:183], v[34:37]
	v_mfma_f32_16x16x32_bf16 v[22:25], v[146:149], v[198:201], v[22:25]
	v_mfma_f32_16x16x32_bf16 v[18:21], v[154:157], v[198:201], v[18:21]
	v_mfma_f32_16x16x32_bf16 v[6:9], v[146:149], v[208:211], v[6:9]
	v_mfma_f32_16x16x32_bf16 v[2:5], v[154:157], v[208:211], v[2:5]
	v_mfma_f32_16x16x32_bf16 v[54:57], v[150:153], v[176:179], v[54:57]
	v_mfma_f32_16x16x32_bf16 v[50:53], v[168:171], v[176:179], v[50:53]
	v_mfma_f32_16x16x32_bf16 v[38:41], v[150:153], v[184:187], v[38:41]
	v_mfma_f32_16x16x32_bf16 v[34:37], v[168:171], v[184:187], v[34:37]
	v_mfma_f32_16x16x32_bf16 v[22:25], v[150:153], v[204:207], v[22:25]
	v_mfma_f32_16x16x32_bf16 v[18:21], v[168:171], v[204:207], v[18:21]
	v_mfma_f32_16x16x32_bf16 v[6:9], v[150:153], v[222:225], v[6:9]
	v_mfma_f32_16x16x32_bf16 v[2:5], v[168:171], v[222:225], v[2:5]
	s_setprio 0
	s_barrier
; #define PG8_STAGE(bufoff, gbase, voff) do { _Pragma("unroll") for (int _i = 0; _i < 2; ++_i) \
;         __builtin_amdgcn_global_load_lds((const unsigned*)((const char*)(gbase) + (voff)[_i]), (PG8_LAS unsigned*)(lds + (bufoff) + ldsw + _i * 8192), 16, 0, 0); } while (0)
; #define PG8_LDA(dst, b, h) do { _Pragma("unroll") for (int m = 0; m < 4; ++m) _Pragma("unroll") for (int k = 0; k < 2; ++k) dst[m][k] = *(const PG8_LAS bf16x8*)(lds + PG8_SA(b, h) + aoff + m * 2048 + k * 1024); } while (0)
; #define PG8_LDB(dst, b, h) do { _Pragma("unroll") for (int n = 0; n < 2; ++n) _Pragma("unroll") for (int k = 0; k < 2; ++k) dst[n][k] = *(const PG8_LAS bf16x8*)(lds + PG8_SB(b, h) + boff + n * 2048 + k * 1024); } while (0)
; #define PG8_MMA(ai, bj, At, Bt) do { __builtin_amdgcn_s_setprio(1); _Pragma("unroll") for (int m = 0; m < 4; ++m) _Pragma("unroll") for (int n = 0; n < 2; ++n) _Pragma("unroll") for (int k = 0; k < 2; ++k) \
;         acc[ai][bj][m][n] = __builtin_amdgcn_mfma_f32_16x16x32_bf16(Bt[n][k], At[m][k], acc[ai][bj][m][n], 0, 0, 0); __builtin_amdgcn_s_setprio(0); } while (0)
; #define PG8_WAIT_V(n) asm volatile("s_waitcnt vmcnt(" #n ")" ::: "memory")
; #define PG8_WAIT_L(n) asm volatile("s_waitcnt lgkmcnt(" #n ")" ::: "memory")
; #define PG8_BAR __builtin_amdgcn_s_barrier()
; #define PG8_SCHED __builtin_amdgcn_sched_barrier(0)
; template <class Epi, class Sched, bool ALIGN_EPI = false, bool SP2 = false>
; __device__ __forceinline__ void gemm_phase(PG8_LAS unsigned char* lds, const Gemm g, const Sched& S, const Epi& E) {
;     ...
;             PG8_LDB(B0, 1, 0); PG8_LDB(B1, 1, 1); PG8_SCHED; PG8_LDA(At, 1, 0); PG8_STAGE(PG8_SA(0, 1), a2 + hstep, voffA);
;             PG8_WAIT_V(8); PG8_WAIT_L(0); PG8_BAR; PG8_MMA(0, 0, At, B0); PG8_MMA(0, 1, At, B1); PG8_BAR; PG8_SCHED;
	s_add_i32 s30, 0, 0x18000
	s_add_i32 s31, 0, 0x1c000
	v_add_u32_e32 v134, s30, v191
	v_add_u32_e32 v168, s31, v191
	ds_read_b128 v[114:117], v134
	ds_read_b128 v[126:129], v134 offset:1024
	ds_read_b128 v[130:133], v134 offset:2048
	ds_read_b128 v[134:137], v134 offset:3072
	ds_read_b128 v[146:149], v168
	ds_read_b128 v[150:153], v168 offset:1024
	ds_read_b128 v[154:157], v168 offset:2048
	ds_read_b128 v[168:171], v168 offset:3072
	s_add_u32 s20, s46, 0xb0000
	s_addc_u32 s21, s47, 0
	s_mov_b32 m0, s50
	v_lshl_add_u64 v[232:233], s[20:21], 0, v[162:163]
	ds_read_b128 v[172:175], v202 offset:32768
	ds_read_b128 v[176:179], v202 offset:33792
	ds_read_b128 v[180:183], v202 offset:34816
	ds_read_b128 v[184:187], v202 offset:35840
	ds_read_b128 v[198:201], v202 offset:36864
	ds_read_b128 v[204:207], v202 offset:37888
	ds_read_b128 v[208:211], v202 offset:38912
	ds_read_b128 v[222:225], v202 offset:39936
	global_load_lds_dwordx4 v[232:233], off
	v_lshl_add_u64 v[232:233], s[20:21], 0, v[160:161]
	s_mov_b32 m0, s51
	s_nop 0
	global_load_lds_dwordx4 v[232:233], off
	s_waitcnt vmcnt(8)
	s_waitcnt lgkmcnt(0)
	s_barrier
	s_nop 0
	s_setprio 1
	s_waitcnt lgkmcnt(0)
	v_mfma_f32_16x16x32_bf16 v[142:145], v[114:117], v[172:175], v[142:145]
	v_mfma_f32_16x16x32_bf16 v[138:141], v[130:133], v[172:175], v[138:141]
	v_mfma_f32_16x16x32_bf16 v[110:113], v[114:117], v[180:183], v[110:113]
	v_mfma_f32_16x16x32_bf16 v[106:109], v[130:133], v[180:183], v[106:109]
	v_mfma_f32_16x16x32_bf16 v[94:97], v[114:117], v[198:201], v[94:97]
	v_mfma_f32_16x16x32_bf16 v[90:93], v[130:133], v[198:201], v[90:93]
	v_mfma_f32_16x16x32_bf16 v[78:81], v[114:117], v[208:211], v[78:81]
	v_mfma_f32_16x16x32_bf16 v[74:77], v[130:133], v[208:211], v[74:77]
	v_mfma_f32_16x16x32_bf16 v[142:145], v[126:129], v[176:179], v[142:145]
	v_mfma_f32_16x16x32_bf16 v[138:141], v[134:137], v[176:179], v[138:141]
	v_mfma_f32_16x16x32_bf16 v[110:113], v[126:129], v[184:187], v[110:113]
	v_mfma_f32_16x16x32_bf16 v[106:109], v[134:137], v[184:187], v[106:109]
	v_mfma_f32_16x16x32_bf16 v[94:97], v[126:129], v[204:207], v[94:97]
	v_mfma_f32_16x16x32_bf16 v[90:93], v[134:137], v[204:207], v[90:93]
	v_mfma_f32_16x16x32_bf16 v[78:81], v[126:129], v[222:225], v[78:81]
	v_mfma_f32_16x16x32_bf16 v[74:77], v[134:137], v[222:225], v[74:77]
	s_setprio 0
	s_setprio 1
	v_mfma_f32_16x16x32_bf16 v[122:125], v[146:149], v[172:175], v[122:125]
	v_mfma_f32_16x16x32_bf16 v[118:121], v[154:157], v[172:175], v[118:121]
	v_mfma_f32_16x16x32_bf16 v[102:105], v[146:149], v[180:183], v[102:105]
	v_mfma_f32_16x16x32_bf16 v[98:101], v[154:157], v[180:183], v[98:101]
	v_mfma_f32_16x16x32_bf16 v[86:89], v[146:149], v[198:201], v[86:89]
	v_mfma_f32_16x16x32_bf16 v[82:85], v[154:157], v[198:201], v[82:85]
	v_mfma_f32_16x16x32_bf16 v[70:73], v[146:149], v[208:211], v[70:73]
	v_mfma_f32_16x16x32_bf16 v[66:69], v[154:157], v[208:211], v[66:69]
	v_mfma_f32_16x16x32_bf16 v[122:125], v[150:153], v[176:179], v[122:125]
	v_mfma_f32_16x16x32_bf16 v[118:121], v[168:171], v[176:179], v[118:121]
	v_mfma_f32_16x16x32_bf16 v[102:105], v[150:153], v[184:187], v[102:105]
	v_mfma_f32_16x16x32_bf16 v[98:101], v[168:171], v[184:187], v[98:101]
	v_mfma_f32_16x16x32_bf16 v[86:89], v[150:153], v[204:207], v[86:89]
	v_mfma_f32_16x16x32_bf16 v[82:85], v[168:171], v[204:207], v[82:85]
	v_mfma_f32_16x16x32_bf16 v[70:73], v[150:153], v[222:225], v[70:73]
	v_mfma_f32_16x16x32_bf16 v[66:69], v[168:171], v[222:225], v[66:69]
	s_setprio 0
	s_barrier
; #define PG8_STAGE(bufoff, gbase, voff) do { _Pragma("unroll") for (int _i = 0; _i < 2; ++_i) \
;         __builtin_amdgcn_global_load_lds((const unsigned*)((const char*)(gbase) + (voff)[_i]), (PG8_LAS unsigned*)(lds + (bufoff) + ldsw + _i * 8192), 16, 0, 0); } while (0)
; #define PG8_LDA(dst, b, h) do { _Pragma("unroll") for (int m = 0; m < 4; ++m) _Pragma("unroll") for (int k = 0; k < 2; ++k) dst[m][k] = *(const PG8_LAS bf16x8*)(lds + PG8_SA(b, h) + aoff + m * 2048 + k * 1024); } while (0)
; #define PG8_MMA(ai, bj, At, Bt) do { __builtin_amdgcn_s_setprio(1); _Pragma("unroll") for (int m = 0; m < 4; ++m) _Pragma("unroll") for (int n = 0; n < 2; ++n) _Pragma("unroll") for (int k = 0; k < 2; ++k) \
;         acc[ai][bj][m][n] = __builtin_amdgcn_mfma_f32_16x16x32_bf16(Bt[n][k], At[m][k], acc[ai][bj][m][n], 0, 0, 0); __builtin_amdgcn_s_setprio(0); } while (0)
; #define PG8_WAIT_V(n) asm volatile("s_waitcnt vmcnt(" #n ")" ::: "memory")
; #define PG8_WAIT_L(n) asm volatile("s_waitcnt lgkmcnt(" #n ")" ::: "memory")
; #define PG8_BAR __builtin_amdgcn_s_barrier()
; #define PG8_SCHED __builtin_amdgcn_sched_barrier(0)
; template <class Epi, class Sched, bool ALIGN_EPI = false, bool SP2 = false>
; __device__ __forceinline__ void gemm_phase(PG8_LAS unsigned char* lds, const Gemm g, const Sched& S, const Epi& E) {
;     ...
;             PG8_LDA(At, 1, 1); PG8_STAGE(PG8_SB(1, 0), b3, voffB); PG8_STAGE(PG8_SB(1, 1), b3 + hstep, voffB); PG8_STAGE(PG8_SA(1, 0), a3, voffA);
;             PG8_WAIT_V(8); PG8_WAIT_L(0); PG8_BAR; PG8_MMA(1, 0, At, B0); PG8_MMA(1, 1, At, B1); PG8_BAR; PG8_SCHED;
	s_add_i32 s20, s30, s33
	v_lshl_add_u64 v[188:189], v[188:189], 0, s[0:1]
	s_mov_b32 m0, s20
	ds_read_b128 v[172:175], v202 offset:49152
	ds_read_b128 v[176:179], v202 offset:50176
	ds_read_b128 v[180:183], v202 offset:51200
	ds_read_b128 v[184:187], v202 offset:52224
	ds_read_b128 v[198:201], v202 offset:53248
	ds_read_b128 v[204:207], v202 offset:54272
	ds_read_b128 v[208:211], v202 offset:55296
	ds_read_b128 v[222:225], v202 offset:56320
	global_load_lds_dwordx4 v[188:189], off
	s_add_i32 m0, s20, 0x2000
	s_add_u32 s20, s44, 0xb0080
	v_lshl_add_u64 v[188:189], v[226:227], 0, s[0:1]
	s_addc_u32 s21, s45, 0
	s_add_i32 s30, s31, s33
	global_load_lds_dwordx4 v[188:189], off
	v_lshl_add_u64 v[188:189], s[20:21], 0, v[0:1]
	s_mov_b32 m0, s30
	s_nop 0
	global_load_lds_dwordx4 v[188:189], off
	v_lshl_add_u64 v[188:189], s[20:21], 0, v[158:159]
	s_add_i32 m0, s30, 0x2000
	s_nop 0
	global_load_lds_dwordx4 v[188:189], off
	v_lshl_add_u64 v[188:189], v[228:229], 0, s[0:1]
	s_mov_b32 m0, s54
	s_nop 0
	global_load_lds_dwordx4 v[188:189], off
	v_lshl_add_u64 v[188:189], v[230:231], 0, s[0:1]
	s_mov_b32 m0, s55
	s_nop 0
	global_load_lds_dwordx4 v[188:189], off
	s_waitcnt vmcnt(8)
	s_waitcnt lgkmcnt(0)
	s_barrier
	s_setprio 1
	s_waitcnt lgkmcnt(0)
	v_mfma_f32_16x16x32_bf16 v[62:65], v[114:117], v[172:175], v[62:65]
	v_mfma_f32_16x16x32_bf16 v[58:61], v[130:133], v[172:175], v[58:61]
	v_mfma_f32_16x16x32_bf16 v[46:49], v[114:117], v[180:183], v[46:49]
	v_mfma_f32_16x16x32_bf16 v[42:45], v[130:133], v[180:183], v[42:45]
	v_mfma_f32_16x16x32_bf16 v[30:33], v[114:117], v[198:201], v[30:33]
	v_mfma_f32_16x16x32_bf16 v[26:29], v[130:133], v[198:201], v[26:29]
	v_mfma_f32_16x16x32_bf16 v[14:17], v[114:117], v[208:211], v[14:17]
	v_mfma_f32_16x16x32_bf16 v[10:13], v[130:133], v[208:211], v[10:13]
	v_mfma_f32_16x16x32_bf16 v[62:65], v[126:129], v[176:179], v[62:65]
	v_mfma_f32_16x16x32_bf16 v[58:61], v[134:137], v[176:179], v[58:61]
	v_mfma_f32_16x16x32_bf16 v[46:49], v[126:129], v[184:187], v[46:49]
	v_mfma_f32_16x16x32_bf16 v[42:45], v[134:137], v[184:187], v[42:45]
	v_mfma_f32_16x16x32_bf16 v[30:33], v[126:129], v[204:207], v[30:33]
	v_mfma_f32_16x16x32_bf16 v[26:29], v[134:137], v[204:207], v[26:29]
	v_mfma_f32_16x16x32_bf16 v[14:17], v[126:129], v[222:225], v[14:17]
	v_mfma_f32_16x16x32_bf16 v[10:13], v[134:137], v[222:225], v[10:13]
	s_setprio 0
	s_setprio 1
	v_mfma_f32_16x16x32_bf16 v[54:57], v[146:149], v[172:175], v[54:57]
	v_mfma_f32_16x16x32_bf16 v[50:53], v[154:157], v[172:175], v[50:53]
	v_mfma_f32_16x16x32_bf16 v[38:41], v[146:149], v[180:183], v[38:41]
	v_mfma_f32_16x16x32_bf16 v[34:37], v[154:157], v[180:183], v[34:37]
	v_mfma_f32_16x16x32_bf16 v[22:25], v[146:149], v[198:201], v[22:25]
	v_mfma_f32_16x16x32_bf16 v[18:21], v[154:157], v[198:201], v[18:21]
	v_mfma_f32_16x16x32_bf16 v[6:9], v[146:149], v[208:211], v[6:9]
	v_mfma_f32_16x16x32_bf16 v[2:5], v[154:157], v[208:211], v[2:5]
	v_mfma_f32_16x16x32_bf16 v[54:57], v[150:153], v[176:179], v[54:57]
	v_mfma_f32_16x16x32_bf16 v[50:53], v[168:171], v[176:179], v[50:53]
	v_mfma_f32_16x16x32_bf16 v[38:41], v[150:153], v[184:187], v[38:41]
	v_mfma_f32_16x16x32_bf16 v[34:37], v[168:171], v[184:187], v[34:37]
	v_mfma_f32_16x16x32_bf16 v[22:25], v[150:153], v[204:207], v[22:25]
	v_mfma_f32_16x16x32_bf16 v[18:21], v[168:171], v[204:207], v[18:21]
	v_mfma_f32_16x16x32_bf16 v[6:9], v[150:153], v[222:225], v[6:9]
	v_mfma_f32_16x16x32_bf16 v[2:5], v[168:171], v[222:225], v[2:5]
	s_setprio 0
	s_barrier
	s_add_i32 s59, s59, 2
	s_add_u32 s34, s34, 0x100
	s_addc_u32 s35, s35, 0
	s_cmp_gt_u32 s59, 41
	s_mov_b64 s[20:21], s[42:43]
	s_cbranch_scc0 .LBB0_868
